# Strategy: rebalance LDS-DMA issue across the K-loop load segments - two of the six pieces of the second segment move to the head of the third (2+6+2+6 -> 2+4+4+6), closing wait vmcnt(6)
# speedup vs baseline: 1.0134x; 1.0081x over previous
.LBB0_163:
	ds_read_b128 v[144:147], v151
	ds_read_b128 v[156:159], v151 offset:1024
	ds_read_b128 v[160:163], v151 offset:2048
	ds_read_b128 v[164:167], v151 offset:3072
	ds_read_b128 v[168:171], v152
	ds_read_b128 v[172:175], v152 offset:1024
	ds_read_b128 v[176:179], v152 offset:2048
	ds_read_b128 v[180:183], v152 offset:3072
	s_add_u32 s26, s24, 0xfffc0080
	s_addc_u32 s27, s25, -1
	s_cmp_eq_u32 s55, 12
	s_cselect_b32 s29, s19, s27
	s_cselect_b32 s28, s51, s26
	s_cselect_b32 s27, s17, s54
	s_cselect_b32 s26, s52, s53
	s_add_i32 m0, s38, 0xc000
	ds_read_b128 v[184:187], v153
	ds_read_b128 v[188:191], v153 offset:1024
	ds_read_b128 v[192:195], v153 offset:2048
	ds_read_b128 v[196:199], v153 offset:3072
	ds_read_b128 v[200:203], v153 offset:4096
	ds_read_b128 v[208:211], v153 offset:5120
	ds_read_b128 v[212:215], v153 offset:6144
	ds_read_b128 v[216:219], v153 offset:7168
	global_load_lds_dwordx4 v138, s[24:25]
	s_add_i32 m0, s38, 0xe000
	s_nop 0
	global_load_lds_dwordx4 v136, s[24:25]
	s_waitcnt vmcnt(8)
	s_waitcnt lgkmcnt(0)
	s_barrier
	s_waitcnt lgkmcnt(0)
	v_mfma_f32_16x16x32_bf16 v[124:127], v[144:147], v[184:187], v[124:127]
	v_mfma_f32_16x16x32_bf16 v[120:123], v[160:163], v[184:187], v[120:123]
	v_mfma_f32_16x16x32_bf16 v[108:111], v[144:147], v[192:195], v[108:111]
	v_mfma_f32_16x16x32_bf16 v[104:107], v[160:163], v[192:195], v[104:107]
	v_mfma_f32_16x16x32_bf16 v[92:95], v[144:147], v[200:203], v[92:95]
	v_mfma_f32_16x16x32_bf16 v[88:91], v[160:163], v[200:203], v[88:91]
	v_mfma_f32_16x16x32_bf16 v[76:79], v[144:147], v[212:215], v[76:79]
	v_mfma_f32_16x16x32_bf16 v[72:75], v[160:163], v[212:215], v[72:75]
	v_mfma_f32_16x16x32_bf16 v[124:127], v[156:159], v[188:191], v[124:127]
	v_mfma_f32_16x16x32_bf16 v[120:123], v[164:167], v[188:191], v[120:123]
	v_mfma_f32_16x16x32_bf16 v[108:111], v[156:159], v[196:199], v[108:111]
	v_mfma_f32_16x16x32_bf16 v[104:107], v[164:167], v[196:199], v[104:107]
	v_mfma_f32_16x16x32_bf16 v[92:95], v[156:159], v[208:211], v[92:95]
	v_mfma_f32_16x16x32_bf16 v[88:91], v[164:167], v[208:211], v[88:91]
	v_mfma_f32_16x16x32_bf16 v[76:79], v[156:159], v[216:219], v[76:79]
	v_mfma_f32_16x16x32_bf16 v[72:75], v[164:167], v[216:219], v[72:75]
	v_mfma_f32_16x16x32_bf16 v[116:119], v[168:171], v[184:187], v[116:119]
	v_mfma_f32_16x16x32_bf16 v[112:115], v[176:179], v[184:187], v[112:115]
	v_mfma_f32_16x16x32_bf16 v[100:103], v[168:171], v[192:195], v[100:103]
	v_mfma_f32_16x16x32_bf16 v[96:99], v[176:179], v[192:195], v[96:99]
	v_mfma_f32_16x16x32_bf16 v[84:87], v[168:171], v[200:203], v[84:87]
	v_mfma_f32_16x16x32_bf16 v[80:83], v[176:179], v[200:203], v[80:83]
	v_mfma_f32_16x16x32_bf16 v[68:71], v[168:171], v[212:215], v[68:71]
	v_mfma_f32_16x16x32_bf16 v[64:67], v[176:179], v[212:215], v[64:67]
	v_mfma_f32_16x16x32_bf16 v[116:119], v[172:175], v[188:191], v[116:119]
	v_mfma_f32_16x16x32_bf16 v[112:115], v[180:183], v[188:191], v[112:115]
	v_mfma_f32_16x16x32_bf16 v[100:103], v[172:175], v[196:199], v[100:103]
	v_mfma_f32_16x16x32_bf16 v[96:99], v[180:183], v[196:199], v[96:99]
	v_mfma_f32_16x16x32_bf16 v[84:87], v[172:175], v[208:211], v[84:87]
	v_mfma_f32_16x16x32_bf16 v[80:83], v[180:183], v[208:211], v[80:83]
	v_mfma_f32_16x16x32_bf16 v[68:71], v[172:175], v[216:219], v[68:71]
	v_mfma_f32_16x16x32_bf16 v[64:67], v[180:183], v[216:219], v[64:67]
	s_barrier
	s_add_i32 s56, s48, s35
	s_mov_b32 m0, s56
	ds_read_b128 v[184:187], v153 offset:16384
	ds_read_b128 v[188:191], v153 offset:17408
	ds_read_b128 v[192:195], v153 offset:18432
	ds_read_b128 v[196:199], v153 offset:19456
	ds_read_b128 v[200:203], v153 offset:20480
	ds_read_b128 v[208:211], v153 offset:21504
	ds_read_b128 v[212:215], v153 offset:22528
	ds_read_b128 v[216:219], v153 offset:23552
	global_load_lds_dwordx4 v132, s[26:27]
	s_add_i32 m0, s56, 0x2000
	s_add_u32 s56, s26, 0x40000
	s_mov_b64 s[98:99], s[26:27]
	s_addc_u32 s57, s27, 0
	s_add_i32 s58, s49, s35
	global_load_lds_dwordx4 v128, s[26:27]
	s_mov_b32 m0, s58
	s_mov_b64 s[100:101], s[28:29]
	global_load_lds_dwordx4 v132, s[56:57]
	s_add_i32 m0, s58, 0x2000
	s_nop 0
	global_load_lds_dwordx4 v128, s[56:57]
	s_waitcnt vmcnt(6)
	s_waitcnt lgkmcnt(0)
	s_barrier
	s_waitcnt lgkmcnt(0)
	v_mfma_f32_16x16x32_bf16 v[60:63], v[144:147], v[184:187], v[60:63]
	v_mfma_f32_16x16x32_bf16 v[56:59], v[160:163], v[184:187], v[56:59]
	v_mfma_f32_16x16x32_bf16 v[44:47], v[144:147], v[192:195], v[44:47]
	v_mfma_f32_16x16x32_bf16 v[40:43], v[160:163], v[192:195], v[40:43]
	v_mfma_f32_16x16x32_bf16 v[28:31], v[144:147], v[200:203], v[28:31]
	v_mfma_f32_16x16x32_bf16 v[24:27], v[160:163], v[200:203], v[24:27]
	v_mfma_f32_16x16x32_bf16 v[12:15], v[144:147], v[212:215], v[12:15]
	v_mfma_f32_16x16x32_bf16 v[8:11], v[160:163], v[212:215], v[8:11]
	v_mfma_f32_16x16x32_bf16 v[60:63], v[156:159], v[188:191], v[60:63]
	v_mfma_f32_16x16x32_bf16 v[56:59], v[164:167], v[188:191], v[56:59]
	v_mfma_f32_16x16x32_bf16 v[44:47], v[156:159], v[196:199], v[44:47]
	v_mfma_f32_16x16x32_bf16 v[40:43], v[164:167], v[196:199], v[40:43]
	v_mfma_f32_16x16x32_bf16 v[28:31], v[156:159], v[208:211], v[28:31]
	v_mfma_f32_16x16x32_bf16 v[24:27], v[164:167], v[208:211], v[24:27]
	v_mfma_f32_16x16x32_bf16 v[12:15], v[156:159], v[216:219], v[12:15]
	v_mfma_f32_16x16x32_bf16 v[8:11], v[164:167], v[216:219], v[8:11]
	v_mfma_f32_16x16x32_bf16 v[52:55], v[168:171], v[184:187], v[52:55]
	v_mfma_f32_16x16x32_bf16 v[48:51], v[176:179], v[184:187], v[48:51]
	v_mfma_f32_16x16x32_bf16 v[36:39], v[168:171], v[192:195], v[36:39]
	v_mfma_f32_16x16x32_bf16 v[32:35], v[176:179], v[192:195], v[32:35]
	v_mfma_f32_16x16x32_bf16 v[20:23], v[168:171], v[200:203], v[20:23]
	v_mfma_f32_16x16x32_bf16 v[16:19], v[176:179], v[200:203], v[16:19]
	v_mfma_f32_16x16x32_bf16 v[4:7], v[168:171], v[212:215], v[4:7]
	v_mfma_f32_16x16x32_bf16 v[0:3], v[176:179], v[212:215], v[0:3]
	v_mfma_f32_16x16x32_bf16 v[52:55], v[172:175], v[188:191], v[52:55]
	v_mfma_f32_16x16x32_bf16 v[48:51], v[180:183], v[188:191], v[48:51]
	v_mfma_f32_16x16x32_bf16 v[36:39], v[172:175], v[196:199], v[36:39]
	v_mfma_f32_16x16x32_bf16 v[32:35], v[180:183], v[196:199], v[32:35]
	v_mfma_f32_16x16x32_bf16 v[20:23], v[172:175], v[208:211], v[20:23]
	v_mfma_f32_16x16x32_bf16 v[16:19], v[180:183], v[208:211], v[16:19]
	v_mfma_f32_16x16x32_bf16 v[4:7], v[172:175], v[216:219], v[4:7]
	v_mfma_f32_16x16x32_bf16 v[0:3], v[180:183], v[216:219], v[0:3]
	s_barrier
	s_mov_b32 m0, s38
	s_nop 0
	global_load_lds_dwordx4 v134, s[28:29]
	s_mov_b32 m0, s39
	s_nop 0
	global_load_lds_dwordx4 v130, s[28:29]
	s_add_i32 s56, 0, 0x18000
	s_add_i32 s57, 0, 0x1c000
	v_add_u32_e32 v164, s56, v149
	v_add_u32_e32 v180, s57, v149
	ds_read_b128 v[144:147], v164
	ds_read_b128 v[156:159], v164 offset:1024
	ds_read_b128 v[160:163], v164 offset:2048
	ds_read_b128 v[164:167], v164 offset:3072
	ds_read_b128 v[168:171], v180
	ds_read_b128 v[172:175], v180 offset:1024
	ds_read_b128 v[176:179], v180 offset:2048
	ds_read_b128 v[180:183], v180 offset:3072
	s_add_u32 s28, s28, 0x40000
	s_addc_u32 s29, s29, 0
	s_mov_b32 m0, s40
	ds_read_b128 v[184:187], v153 offset:32768
	ds_read_b128 v[188:191], v153 offset:33792
	ds_read_b128 v[192:195], v153 offset:34816
	ds_read_b128 v[196:199], v153 offset:35840
	ds_read_b128 v[200:203], v153 offset:36864
	ds_read_b128 v[208:211], v153 offset:37888
	ds_read_b128 v[212:215], v153 offset:38912
	ds_read_b128 v[216:219], v153 offset:39936
	global_load_lds_dwordx4 v134, s[28:29]
	s_mov_b32 m0, s41
	s_nop 0
	global_load_lds_dwordx4 v130, s[28:29]
	s_waitcnt vmcnt(8)
	s_waitcnt lgkmcnt(0)
	s_barrier
	s_waitcnt lgkmcnt(0)
	v_mfma_f32_16x16x32_bf16 v[124:127], v[144:147], v[184:187], v[124:127]
	v_mfma_f32_16x16x32_bf16 v[120:123], v[160:163], v[184:187], v[120:123]
	v_mfma_f32_16x16x32_bf16 v[108:111], v[144:147], v[192:195], v[108:111]
	v_mfma_f32_16x16x32_bf16 v[104:107], v[160:163], v[192:195], v[104:107]
	v_mfma_f32_16x16x32_bf16 v[92:95], v[144:147], v[200:203], v[92:95]
	v_mfma_f32_16x16x32_bf16 v[88:91], v[160:163], v[200:203], v[88:91]
	v_mfma_f32_16x16x32_bf16 v[76:79], v[144:147], v[212:215], v[76:79]
	v_mfma_f32_16x16x32_bf16 v[72:75], v[160:163], v[212:215], v[72:75]
	v_mfma_f32_16x16x32_bf16 v[124:127], v[156:159], v[188:191], v[124:127]
	v_mfma_f32_16x16x32_bf16 v[120:123], v[164:167], v[188:191], v[120:123]
	v_mfma_f32_16x16x32_bf16 v[108:111], v[156:159], v[196:199], v[108:111]
	v_mfma_f32_16x16x32_bf16 v[104:107], v[164:167], v[196:199], v[104:107]
	v_mfma_f32_16x16x32_bf16 v[92:95], v[156:159], v[208:211], v[92:95]
	v_mfma_f32_16x16x32_bf16 v[88:91], v[164:167], v[208:211], v[88:91]
	v_mfma_f32_16x16x32_bf16 v[76:79], v[156:159], v[216:219], v[76:79]
	v_mfma_f32_16x16x32_bf16 v[72:75], v[164:167], v[216:219], v[72:75]
	v_mfma_f32_16x16x32_bf16 v[116:119], v[168:171], v[184:187], v[116:119]
	v_mfma_f32_16x16x32_bf16 v[112:115], v[176:179], v[184:187], v[112:115]
	v_mfma_f32_16x16x32_bf16 v[100:103], v[168:171], v[192:195], v[100:103]
	v_mfma_f32_16x16x32_bf16 v[96:99], v[176:179], v[192:195], v[96:99]
	v_mfma_f32_16x16x32_bf16 v[84:87], v[168:171], v[200:203], v[84:87]
	v_mfma_f32_16x16x32_bf16 v[80:83], v[176:179], v[200:203], v[80:83]
	v_mfma_f32_16x16x32_bf16 v[68:71], v[168:171], v[212:215], v[68:71]
	v_mfma_f32_16x16x32_bf16 v[64:67], v[176:179], v[212:215], v[64:67]
	v_mfma_f32_16x16x32_bf16 v[116:119], v[172:175], v[188:191], v[116:119]
	v_mfma_f32_16x16x32_bf16 v[112:115], v[180:183], v[188:191], v[112:115]
	v_mfma_f32_16x16x32_bf16 v[100:103], v[172:175], v[196:199], v[100:103]
	v_mfma_f32_16x16x32_bf16 v[96:99], v[180:183], v[196:199], v[96:99]
	v_mfma_f32_16x16x32_bf16 v[84:87], v[172:175], v[208:211], v[84:87]
	v_mfma_f32_16x16x32_bf16 v[80:83], v[180:183], v[208:211], v[80:83]
	v_mfma_f32_16x16x32_bf16 v[68:71], v[172:175], v[216:219], v[68:71]
	v_mfma_f32_16x16x32_bf16 v[64:67], v[180:183], v[216:219], v[64:67]
	s_barrier
	s_add_i32 s28, s56, s35
	s_mov_b32 m0, s28
	ds_read_b128 v[184:187], v153 offset:49152
	ds_read_b128 v[188:191], v153 offset:50176
	ds_read_b128 v[192:195], v153 offset:51200
	ds_read_b128 v[196:199], v153 offset:52224
	ds_read_b128 v[200:203], v153 offset:53248
	ds_read_b128 v[208:211], v153 offset:54272
	ds_read_b128 v[212:215], v153 offset:55296
	ds_read_b128 v[216:219], v153 offset:56320
	global_load_lds_dwordx4 v220, s[26:27]
	s_add_i32 m0, s28, 0x2000
	s_add_u32 s26, s26, 0x40080
	s_addc_u32 s27, s27, 0
	s_add_i32 s28, s57, s35
	global_load_lds_dwordx4 v204, s[98:99]
	s_mov_b32 m0, s28
	s_nop 0
	global_load_lds_dwordx4 v132, s[26:27]
	s_add_i32 m0, s28, 0x2000
	s_nop 0
	global_load_lds_dwordx4 v128, s[26:27]
	s_mov_b32 m0, s45
	s_nop 0
	global_load_lds_dwordx4 v221, s[100:101]
	s_mov_b32 m0, s46
	s_nop 0
	global_load_lds_dwordx4 v205, s[100:101]
	s_waitcnt vmcnt(8)
	s_waitcnt lgkmcnt(0)
	s_barrier
	s_waitcnt lgkmcnt(0)
	v_mfma_f32_16x16x32_bf16 v[60:63], v[144:147], v[184:187], v[60:63]
	v_mfma_f32_16x16x32_bf16 v[56:59], v[160:163], v[184:187], v[56:59]
	v_mfma_f32_16x16x32_bf16 v[44:47], v[144:147], v[192:195], v[44:47]
	v_mfma_f32_16x16x32_bf16 v[40:43], v[160:163], v[192:195], v[40:43]
	v_mfma_f32_16x16x32_bf16 v[28:31], v[144:147], v[200:203], v[28:31]
	v_mfma_f32_16x16x32_bf16 v[24:27], v[160:163], v[200:203], v[24:27]
	v_mfma_f32_16x16x32_bf16 v[12:15], v[144:147], v[212:215], v[12:15]
	v_mfma_f32_16x16x32_bf16 v[8:11], v[160:163], v[212:215], v[8:11]
	v_mfma_f32_16x16x32_bf16 v[60:63], v[156:159], v[188:191], v[60:63]
	v_mfma_f32_16x16x32_bf16 v[56:59], v[164:167], v[188:191], v[56:59]
	v_mfma_f32_16x16x32_bf16 v[44:47], v[156:159], v[196:199], v[44:47]
	v_mfma_f32_16x16x32_bf16 v[40:43], v[164:167], v[196:199], v[40:43]
	v_mfma_f32_16x16x32_bf16 v[28:31], v[156:159], v[208:211], v[28:31]
	v_mfma_f32_16x16x32_bf16 v[24:27], v[164:167], v[208:211], v[24:27]
	v_mfma_f32_16x16x32_bf16 v[12:15], v[156:159], v[216:219], v[12:15]
	v_mfma_f32_16x16x32_bf16 v[8:11], v[164:167], v[216:219], v[8:11]
	v_mfma_f32_16x16x32_bf16 v[52:55], v[168:171], v[184:187], v[52:55]
	v_mfma_f32_16x16x32_bf16 v[48:51], v[176:179], v[184:187], v[48:51]
	v_mfma_f32_16x16x32_bf16 v[36:39], v[168:171], v[192:195], v[36:39]
	v_mfma_f32_16x16x32_bf16 v[32:35], v[176:179], v[192:195], v[32:35]
	v_mfma_f32_16x16x32_bf16 v[20:23], v[168:171], v[200:203], v[20:23]
	v_mfma_f32_16x16x32_bf16 v[16:19], v[176:179], v[200:203], v[16:19]
	v_mfma_f32_16x16x32_bf16 v[4:7], v[168:171], v[212:215], v[4:7]
	v_mfma_f32_16x16x32_bf16 v[0:3], v[176:179], v[212:215], v[0:3]
	v_mfma_f32_16x16x32_bf16 v[52:55], v[172:175], v[188:191], v[52:55]
	v_mfma_f32_16x16x32_bf16 v[48:51], v[180:183], v[188:191], v[48:51]
	v_mfma_f32_16x16x32_bf16 v[36:39], v[172:175], v[196:199], v[36:39]
	v_mfma_f32_16x16x32_bf16 v[32:35], v[180:183], v[196:199], v[32:35]
	v_mfma_f32_16x16x32_bf16 v[20:23], v[172:175], v[208:211], v[20:23]
	v_mfma_f32_16x16x32_bf16 v[16:19], v[180:183], v[208:211], v[16:19]
	v_mfma_f32_16x16x32_bf16 v[4:7], v[172:175], v[216:219], v[4:7]
	v_mfma_f32_16x16x32_bf16 v[0:3], v[180:183], v[216:219], v[0:3]
	s_barrier
	s_add_i32 s55, s55, 2
	s_add_u32 s53, s53, 0x100
	s_addc_u32 s54, s54, 0
	s_add_u32 s24, s24, 0x100
	s_addc_u32 s25, s25, 0
	s_cmp_gt_u32 s55, 13
	s_cbranch_scc0 .LBB0_163
	s_setprio 0
	s_and_b64 vcc, exec, s[14:15]
	s_cbranch_vccz .LBB0_166
	s_barrier

.LBB0_606:
	ds_read_b128 v[140:143], v147
	ds_read_b128 v[150:153], v147 offset:1024
	ds_read_b128 v[154:157], v147 offset:2048
	ds_read_b128 v[158:161], v147 offset:3072
	ds_read_b128 v[162:165], v148
	ds_read_b128 v[166:169], v148 offset:1024
	ds_read_b128 v[170:173], v148 offset:2048
	ds_read_b128 v[174:177], v148 offset:3072
	s_add_u32 s30, s28, 0x100
	s_addc_u32 s31, s29, 0
	s_cmp_eq_u32 s58, 12
	s_cselect_b32 s37, s21, s31
	s_cselect_b32 s36, s27, s30
	s_cselect_b32 s35, s19, s57
	s_cselect_b32 s34, s55, s56
	s_add_i32 m0, s44, 0xc000
	ds_read_b128 v[178:181], v149
	ds_read_b128 v[182:185], v149 offset:1024
	ds_read_b128 v[186:189], v149 offset:2048
	ds_read_b128 v[190:193], v149 offset:3072
	ds_read_b128 v[194:197], v149 offset:4096
	ds_read_b128 v[198:201], v149 offset:5120
	ds_read_b128 v[202:205], v149 offset:6144
	ds_read_b128 v[208:211], v149 offset:7168
	global_load_lds_dwordx4 v134, s[28:29]
	s_add_i32 m0, s44, 0xe000
	s_nop 0
	global_load_lds_dwordx4 v132, s[28:29]
	s_waitcnt vmcnt(8)
	s_waitcnt lgkmcnt(0)
	s_barrier
	s_waitcnt lgkmcnt(0)
	v_mfma_f32_16x16x32_bf16 v[124:127], v[140:143], v[178:181], v[124:127]
	v_mfma_f32_16x16x32_bf16 v[120:123], v[154:157], v[178:181], v[120:123]
	v_mfma_f32_16x16x32_bf16 v[108:111], v[140:143], v[186:189], v[108:111]
	v_mfma_f32_16x16x32_bf16 v[104:107], v[154:157], v[186:189], v[104:107]
	v_mfma_f32_16x16x32_bf16 v[92:95], v[140:143], v[194:197], v[92:95]
	v_mfma_f32_16x16x32_bf16 v[88:91], v[154:157], v[194:197], v[88:91]
	v_mfma_f32_16x16x32_bf16 v[76:79], v[140:143], v[202:205], v[76:79]
	v_mfma_f32_16x16x32_bf16 v[72:75], v[154:157], v[202:205], v[72:75]
	v_mfma_f32_16x16x32_bf16 v[124:127], v[150:153], v[182:185], v[124:127]
	v_mfma_f32_16x16x32_bf16 v[120:123], v[158:161], v[182:185], v[120:123]
	v_mfma_f32_16x16x32_bf16 v[108:111], v[150:153], v[190:193], v[108:111]
	v_mfma_f32_16x16x32_bf16 v[104:107], v[158:161], v[190:193], v[104:107]
	v_mfma_f32_16x16x32_bf16 v[92:95], v[150:153], v[198:201], v[92:95]
	v_mfma_f32_16x16x32_bf16 v[88:91], v[158:161], v[198:201], v[88:91]
	v_mfma_f32_16x16x32_bf16 v[76:79], v[150:153], v[208:211], v[76:79]
	v_mfma_f32_16x16x32_bf16 v[72:75], v[158:161], v[208:211], v[72:75]
	v_mfma_f32_16x16x32_bf16 v[116:119], v[162:165], v[178:181], v[116:119]
	v_mfma_f32_16x16x32_bf16 v[112:115], v[170:173], v[178:181], v[112:115]
	v_mfma_f32_16x16x32_bf16 v[100:103], v[162:165], v[186:189], v[100:103]
	v_mfma_f32_16x16x32_bf16 v[96:99], v[170:173], v[186:189], v[96:99]
	v_mfma_f32_16x16x32_bf16 v[84:87], v[162:165], v[194:197], v[84:87]
	v_mfma_f32_16x16x32_bf16 v[80:83], v[170:173], v[194:197], v[80:83]
	v_mfma_f32_16x16x32_bf16 v[68:71], v[162:165], v[202:205], v[68:71]
	v_mfma_f32_16x16x32_bf16 v[64:67], v[170:173], v[202:205], v[64:67]
	v_mfma_f32_16x16x32_bf16 v[116:119], v[166:169], v[182:185], v[116:119]
	v_mfma_f32_16x16x32_bf16 v[112:115], v[174:177], v[182:185], v[112:115]
	v_mfma_f32_16x16x32_bf16 v[100:103], v[166:169], v[190:193], v[100:103]
	v_mfma_f32_16x16x32_bf16 v[96:99], v[174:177], v[190:193], v[96:99]
	v_mfma_f32_16x16x32_bf16 v[84:87], v[166:169], v[198:201], v[84:87]
	v_mfma_f32_16x16x32_bf16 v[80:83], v[174:177], v[198:201], v[80:83]
	v_mfma_f32_16x16x32_bf16 v[68:71], v[166:169], v[208:211], v[68:71]
	v_mfma_f32_16x16x32_bf16 v[64:67], v[174:177], v[208:211], v[64:67]
	s_barrier
	s_add_i32 s28, s52, s43
	s_mov_b32 m0, s28
	ds_read_b128 v[178:181], v149 offset:16384
	ds_read_b128 v[182:185], v149 offset:17408
	ds_read_b128 v[186:189], v149 offset:18432
	ds_read_b128 v[190:193], v149 offset:19456
	ds_read_b128 v[194:197], v149 offset:20480
	ds_read_b128 v[198:201], v149 offset:21504
	ds_read_b128 v[202:205], v149 offset:22528
	ds_read_b128 v[208:211], v149 offset:23552
	global_load_lds_dwordx4 v128, s[34:35]
	s_add_i32 m0, s28, 0x2000
	s_add_u32 s28, s34, 0x40000
	s_mov_b64 s[98:99], s[34:35]
	s_addc_u32 s29, s35, 0
	s_add_i32 s59, s53, s43
	global_load_lds_dwordx4 v130, s[34:35]
	s_mov_b32 m0, s59
	s_nop 0
	global_load_lds_dwordx4 v128, s[28:29]
	s_add_i32 m0, s59, 0x2000
	s_nop 0
	global_load_lds_dwordx4 v130, s[28:29]
	s_waitcnt vmcnt(6)
	s_waitcnt lgkmcnt(0)
	s_barrier
	s_waitcnt lgkmcnt(0)
	v_mfma_f32_16x16x32_bf16 v[60:63], v[140:143], v[178:181], v[60:63]
	v_mfma_f32_16x16x32_bf16 v[56:59], v[154:157], v[178:181], v[56:59]
	v_mfma_f32_16x16x32_bf16 v[44:47], v[140:143], v[186:189], v[44:47]
	v_mfma_f32_16x16x32_bf16 v[40:43], v[154:157], v[186:189], v[40:43]
	v_mfma_f32_16x16x32_bf16 v[28:31], v[140:143], v[194:197], v[28:31]
	v_mfma_f32_16x16x32_bf16 v[24:27], v[154:157], v[194:197], v[24:27]
	v_mfma_f32_16x16x32_bf16 v[12:15], v[140:143], v[202:205], v[12:15]
	v_mfma_f32_16x16x32_bf16 v[8:11], v[154:157], v[202:205], v[8:11]
	v_mfma_f32_16x16x32_bf16 v[60:63], v[150:153], v[182:185], v[60:63]
	v_mfma_f32_16x16x32_bf16 v[56:59], v[158:161], v[182:185], v[56:59]
	v_mfma_f32_16x16x32_bf16 v[44:47], v[150:153], v[190:193], v[44:47]
	v_mfma_f32_16x16x32_bf16 v[40:43], v[158:161], v[190:193], v[40:43]
	v_mfma_f32_16x16x32_bf16 v[28:31], v[150:153], v[198:201], v[28:31]
	v_mfma_f32_16x16x32_bf16 v[24:27], v[158:161], v[198:201], v[24:27]
	v_mfma_f32_16x16x32_bf16 v[12:15], v[150:153], v[208:211], v[12:15]
	v_mfma_f32_16x16x32_bf16 v[8:11], v[158:161], v[208:211], v[8:11]
	v_mfma_f32_16x16x32_bf16 v[52:55], v[162:165], v[178:181], v[52:55]
	v_mfma_f32_16x16x32_bf16 v[48:51], v[170:173], v[178:181], v[48:51]
	v_mfma_f32_16x16x32_bf16 v[36:39], v[162:165], v[186:189], v[36:39]
	v_mfma_f32_16x16x32_bf16 v[32:35], v[170:173], v[186:189], v[32:35]
	v_mfma_f32_16x16x32_bf16 v[20:23], v[162:165], v[194:197], v[20:23]
	v_mfma_f32_16x16x32_bf16 v[16:19], v[170:173], v[194:197], v[16:19]
	v_mfma_f32_16x16x32_bf16 v[4:7], v[162:165], v[202:205], v[4:7]
	v_mfma_f32_16x16x32_bf16 v[0:3], v[170:173], v[202:205], v[0:3]
	v_mfma_f32_16x16x32_bf16 v[52:55], v[166:169], v[182:185], v[52:55]
	v_mfma_f32_16x16x32_bf16 v[48:51], v[174:177], v[182:185], v[48:51]
	v_mfma_f32_16x16x32_bf16 v[36:39], v[166:169], v[190:193], v[36:39]
	v_mfma_f32_16x16x32_bf16 v[32:35], v[174:177], v[190:193], v[32:35]
	v_mfma_f32_16x16x32_bf16 v[20:23], v[166:169], v[198:201], v[20:23]
	v_mfma_f32_16x16x32_bf16 v[16:19], v[174:177], v[198:201], v[16:19]
	v_mfma_f32_16x16x32_bf16 v[4:7], v[166:169], v[208:211], v[4:7]
	v_mfma_f32_16x16x32_bf16 v[0:3], v[174:177], v[208:211], v[0:3]
	s_barrier
	s_mov_b32 m0, s44
	s_nop 0
	global_load_lds_dwordx4 v128, s[36:37]
	s_mov_b32 m0, s45
	s_nop 0
	global_load_lds_dwordx4 v130, s[36:37]
	s_add_i32 s59, 0, 0x18000
	s_add_i32 s60, 0, 0x1c000
	v_add_u32_e32 v158, s59, v145
	v_add_u32_e32 v174, s60, v145
	ds_read_b128 v[140:143], v158
	ds_read_b128 v[150:153], v158 offset:1024
	ds_read_b128 v[154:157], v158 offset:2048
	ds_read_b128 v[158:161], v158 offset:3072
	ds_read_b128 v[162:165], v174
	ds_read_b128 v[166:169], v174 offset:1024
	ds_read_b128 v[170:173], v174 offset:2048
	ds_read_b128 v[174:177], v174 offset:3072
	s_add_u32 s28, s36, 0x40000
	s_addc_u32 s29, s37, 0
	s_mov_b32 m0, s46
	ds_read_b128 v[178:181], v149 offset:32768
	ds_read_b128 v[182:185], v149 offset:33792
	ds_read_b128 v[186:189], v149 offset:34816
	ds_read_b128 v[190:193], v149 offset:35840
	ds_read_b128 v[194:197], v149 offset:36864
	ds_read_b128 v[198:201], v149 offset:37888
	ds_read_b128 v[202:205], v149 offset:38912
	ds_read_b128 v[208:211], v149 offset:39936
	global_load_lds_dwordx4 v128, s[28:29]
	s_mov_b32 m0, s47
	s_nop 0
	global_load_lds_dwordx4 v130, s[28:29]
	s_waitcnt vmcnt(8)
	s_waitcnt lgkmcnt(0)
	s_barrier
	s_waitcnt lgkmcnt(0)
	v_mfma_f32_16x16x32_bf16 v[124:127], v[140:143], v[178:181], v[124:127]
	v_mfma_f32_16x16x32_bf16 v[120:123], v[154:157], v[178:181], v[120:123]
	v_mfma_f32_16x16x32_bf16 v[108:111], v[140:143], v[186:189], v[108:111]
	v_mfma_f32_16x16x32_bf16 v[104:107], v[154:157], v[186:189], v[104:107]
	v_mfma_f32_16x16x32_bf16 v[92:95], v[140:143], v[194:197], v[92:95]
	v_mfma_f32_16x16x32_bf16 v[88:91], v[154:157], v[194:197], v[88:91]
	v_mfma_f32_16x16x32_bf16 v[76:79], v[140:143], v[202:205], v[76:79]
	v_mfma_f32_16x16x32_bf16 v[72:75], v[154:157], v[202:205], v[72:75]
	v_mfma_f32_16x16x32_bf16 v[124:127], v[150:153], v[182:185], v[124:127]
	v_mfma_f32_16x16x32_bf16 v[120:123], v[158:161], v[182:185], v[120:123]
	v_mfma_f32_16x16x32_bf16 v[108:111], v[150:153], v[190:193], v[108:111]
	v_mfma_f32_16x16x32_bf16 v[104:107], v[158:161], v[190:193], v[104:107]
	v_mfma_f32_16x16x32_bf16 v[92:95], v[150:153], v[198:201], v[92:95]
	v_mfma_f32_16x16x32_bf16 v[88:91], v[158:161], v[198:201], v[88:91]
	v_mfma_f32_16x16x32_bf16 v[76:79], v[150:153], v[208:211], v[76:79]
	v_mfma_f32_16x16x32_bf16 v[72:75], v[158:161], v[208:211], v[72:75]
	v_mfma_f32_16x16x32_bf16 v[116:119], v[162:165], v[178:181], v[116:119]
	v_mfma_f32_16x16x32_bf16 v[112:115], v[170:173], v[178:181], v[112:115]
	v_mfma_f32_16x16x32_bf16 v[100:103], v[162:165], v[186:189], v[100:103]
	v_mfma_f32_16x16x32_bf16 v[96:99], v[170:173], v[186:189], v[96:99]
	v_mfma_f32_16x16x32_bf16 v[84:87], v[162:165], v[194:197], v[84:87]
	v_mfma_f32_16x16x32_bf16 v[80:83], v[170:173], v[194:197], v[80:83]
	v_mfma_f32_16x16x32_bf16 v[68:71], v[162:165], v[202:205], v[68:71]
	v_mfma_f32_16x16x32_bf16 v[64:67], v[170:173], v[202:205], v[64:67]
	v_mfma_f32_16x16x32_bf16 v[116:119], v[166:169], v[182:185], v[116:119]
	v_mfma_f32_16x16x32_bf16 v[112:115], v[174:177], v[182:185], v[112:115]
	v_mfma_f32_16x16x32_bf16 v[100:103], v[166:169], v[190:193], v[100:103]
	v_mfma_f32_16x16x32_bf16 v[96:99], v[174:177], v[190:193], v[96:99]
	v_mfma_f32_16x16x32_bf16 v[84:87], v[166:169], v[198:201], v[84:87]
	v_mfma_f32_16x16x32_bf16 v[80:83], v[174:177], v[198:201], v[80:83]
	v_mfma_f32_16x16x32_bf16 v[68:71], v[166:169], v[208:211], v[68:71]
	v_mfma_f32_16x16x32_bf16 v[64:67], v[174:177], v[208:211], v[64:67]
	s_barrier
	s_add_i32 s28, s59, s43
	s_mov_b32 m0, s28
	ds_read_b128 v[178:181], v149 offset:49152
	ds_read_b128 v[182:185], v149 offset:50176
	ds_read_b128 v[186:189], v149 offset:51200
	ds_read_b128 v[190:193], v149 offset:52224
	ds_read_b128 v[194:197], v149 offset:53248
	ds_read_b128 v[198:201], v149 offset:54272
	ds_read_b128 v[202:205], v149 offset:55296
	ds_read_b128 v[208:211], v149 offset:56320
	global_load_lds_dwordx4 v212, s[34:35]
	s_add_i32 m0, s28, 0x2000
	s_add_u32 s28, s34, 0x40080
	s_addc_u32 s29, s35, 0
	s_add_i32 s34, s60, s43
	global_load_lds_dwordx4 v213, s[98:99]
	s_mov_b32 m0, s34
	s_nop 0
	global_load_lds_dwordx4 v128, s[28:29]
	s_add_i32 m0, s34, 0x2000
	s_nop 0
	global_load_lds_dwordx4 v130, s[28:29]
	s_mov_b32 m0, s49
	s_nop 0
	global_load_lds_dwordx4 v212, s[36:37]
	s_mov_b32 m0, s50
	s_nop 0
	global_load_lds_dwordx4 v213, s[36:37]
	s_waitcnt vmcnt(8)
	s_waitcnt lgkmcnt(0)
	s_barrier
	s_waitcnt lgkmcnt(0)
	v_mfma_f32_16x16x32_bf16 v[60:63], v[140:143], v[178:181], v[60:63]
	v_mfma_f32_16x16x32_bf16 v[56:59], v[154:157], v[178:181], v[56:59]
	v_mfma_f32_16x16x32_bf16 v[44:47], v[140:143], v[186:189], v[44:47]
	v_mfma_f32_16x16x32_bf16 v[40:43], v[154:157], v[186:189], v[40:43]
	v_mfma_f32_16x16x32_bf16 v[28:31], v[140:143], v[194:197], v[28:31]
	v_mfma_f32_16x16x32_bf16 v[24:27], v[154:157], v[194:197], v[24:27]
	v_mfma_f32_16x16x32_bf16 v[12:15], v[140:143], v[202:205], v[12:15]
	v_mfma_f32_16x16x32_bf16 v[8:11], v[154:157], v[202:205], v[8:11]
	v_mfma_f32_16x16x32_bf16 v[60:63], v[150:153], v[182:185], v[60:63]
	v_mfma_f32_16x16x32_bf16 v[56:59], v[158:161], v[182:185], v[56:59]
	v_mfma_f32_16x16x32_bf16 v[44:47], v[150:153], v[190:193], v[44:47]
	v_mfma_f32_16x16x32_bf16 v[40:43], v[158:161], v[190:193], v[40:43]
	v_mfma_f32_16x16x32_bf16 v[28:31], v[150:153], v[198:201], v[28:31]
	v_mfma_f32_16x16x32_bf16 v[24:27], v[158:161], v[198:201], v[24:27]
	v_mfma_f32_16x16x32_bf16 v[12:15], v[150:153], v[208:211], v[12:15]
	v_mfma_f32_16x16x32_bf16 v[8:11], v[158:161], v[208:211], v[8:11]
	v_mfma_f32_16x16x32_bf16 v[52:55], v[162:165], v[178:181], v[52:55]
	v_mfma_f32_16x16x32_bf16 v[48:51], v[170:173], v[178:181], v[48:51]
	v_mfma_f32_16x16x32_bf16 v[36:39], v[162:165], v[186:189], v[36:39]
	v_mfma_f32_16x16x32_bf16 v[32:35], v[170:173], v[186:189], v[32:35]
	v_mfma_f32_16x16x32_bf16 v[20:23], v[162:165], v[194:197], v[20:23]
	v_mfma_f32_16x16x32_bf16 v[16:19], v[170:173], v[194:197], v[16:19]
	v_mfma_f32_16x16x32_bf16 v[4:7], v[162:165], v[202:205], v[4:7]
	v_mfma_f32_16x16x32_bf16 v[0:3], v[170:173], v[202:205], v[0:3]
	v_mfma_f32_16x16x32_bf16 v[52:55], v[166:169], v[182:185], v[52:55]
	v_mfma_f32_16x16x32_bf16 v[48:51], v[174:177], v[182:185], v[48:51]
	v_mfma_f32_16x16x32_bf16 v[36:39], v[166:169], v[190:193], v[36:39]
	v_mfma_f32_16x16x32_bf16 v[32:35], v[174:177], v[190:193], v[32:35]
	v_mfma_f32_16x16x32_bf16 v[20:23], v[166:169], v[198:201], v[20:23]
	v_mfma_f32_16x16x32_bf16 v[16:19], v[174:177], v[198:201], v[16:19]
	v_mfma_f32_16x16x32_bf16 v[4:7], v[166:169], v[208:211], v[4:7]
	v_mfma_f32_16x16x32_bf16 v[0:3], v[174:177], v[208:211], v[0:3]
	s_barrier
	s_add_i32 s58, s58, 2
	s_add_u32 s56, s56, 0x100
	s_addc_u32 s57, s57, 0
	s_cmp_gt_u32 s58, 13
	s_mov_b64 s[28:29], s[30:31]
	s_cbranch_scc0 .LBB0_606
	s_setprio 0
	s_and_b64 vcc, exec, s[16:17]
	s_cbranch_vccz .LBB0_609
	s_barrier

.LBB0_699:
	ds_read_b128 v[144:147], v151
	ds_read_b128 v[156:159], v151 offset:1024
	ds_read_b128 v[160:163], v151 offset:2048
	ds_read_b128 v[164:167], v151 offset:3072
	ds_read_b128 v[168:171], v152
	ds_read_b128 v[172:175], v152 offset:1024
	ds_read_b128 v[176:179], v152 offset:2048
	ds_read_b128 v[180:183], v152 offset:3072
	s_add_u32 s28, s26, 0xfffc0080
	s_addc_u32 s29, s27, -1
	s_cmp_eq_u32 s53, 12
	s_cselect_b32 s31, s21, s29
	s_cselect_b32 s30, s49, s28
	s_cselect_b32 s29, s19, s52
	s_cselect_b32 s28, s50, s51
	s_add_i32 m0, s39, 0xc000
	ds_read_b128 v[184:187], v153
	ds_read_b128 v[188:191], v153 offset:1024
	ds_read_b128 v[192:195], v153 offset:2048
	ds_read_b128 v[196:199], v153 offset:3072
	ds_read_b128 v[200:203], v153 offset:4096
	ds_read_b128 v[208:211], v153 offset:5120
	ds_read_b128 v[212:215], v153 offset:6144
	ds_read_b128 v[216:219], v153 offset:7168
	global_load_lds_dwordx4 v138, s[26:27]
	s_add_i32 m0, s39, 0xe000
	s_nop 0
	global_load_lds_dwordx4 v136, s[26:27]
	s_waitcnt vmcnt(8)
	s_waitcnt lgkmcnt(0)
	s_barrier
	s_waitcnt lgkmcnt(0)
	v_mfma_f32_16x16x32_bf16 v[124:127], v[144:147], v[184:187], v[124:127]
	v_mfma_f32_16x16x32_bf16 v[120:123], v[160:163], v[184:187], v[120:123]
	v_mfma_f32_16x16x32_bf16 v[108:111], v[144:147], v[192:195], v[108:111]
	v_mfma_f32_16x16x32_bf16 v[104:107], v[160:163], v[192:195], v[104:107]
	v_mfma_f32_16x16x32_bf16 v[92:95], v[144:147], v[200:203], v[92:95]
	v_mfma_f32_16x16x32_bf16 v[88:91], v[160:163], v[200:203], v[88:91]
	v_mfma_f32_16x16x32_bf16 v[76:79], v[144:147], v[212:215], v[76:79]
	v_mfma_f32_16x16x32_bf16 v[72:75], v[160:163], v[212:215], v[72:75]
	v_mfma_f32_16x16x32_bf16 v[124:127], v[156:159], v[188:191], v[124:127]
	v_mfma_f32_16x16x32_bf16 v[120:123], v[164:167], v[188:191], v[120:123]
	v_mfma_f32_16x16x32_bf16 v[108:111], v[156:159], v[196:199], v[108:111]
	v_mfma_f32_16x16x32_bf16 v[104:107], v[164:167], v[196:199], v[104:107]
	v_mfma_f32_16x16x32_bf16 v[92:95], v[156:159], v[208:211], v[92:95]
	v_mfma_f32_16x16x32_bf16 v[88:91], v[164:167], v[208:211], v[88:91]
	v_mfma_f32_16x16x32_bf16 v[76:79], v[156:159], v[216:219], v[76:79]
	v_mfma_f32_16x16x32_bf16 v[72:75], v[164:167], v[216:219], v[72:75]
	v_mfma_f32_16x16x32_bf16 v[116:119], v[168:171], v[184:187], v[116:119]
	v_mfma_f32_16x16x32_bf16 v[112:115], v[176:179], v[184:187], v[112:115]
	v_mfma_f32_16x16x32_bf16 v[100:103], v[168:171], v[192:195], v[100:103]
	v_mfma_f32_16x16x32_bf16 v[96:99], v[176:179], v[192:195], v[96:99]
	v_mfma_f32_16x16x32_bf16 v[84:87], v[168:171], v[200:203], v[84:87]
	v_mfma_f32_16x16x32_bf16 v[80:83], v[176:179], v[200:203], v[80:83]
	v_mfma_f32_16x16x32_bf16 v[68:71], v[168:171], v[212:215], v[68:71]
	v_mfma_f32_16x16x32_bf16 v[64:67], v[176:179], v[212:215], v[64:67]
	v_mfma_f32_16x16x32_bf16 v[116:119], v[172:175], v[188:191], v[116:119]
	v_mfma_f32_16x16x32_bf16 v[112:115], v[180:183], v[188:191], v[112:115]
	v_mfma_f32_16x16x32_bf16 v[100:103], v[172:175], v[196:199], v[100:103]
	v_mfma_f32_16x16x32_bf16 v[96:99], v[180:183], v[196:199], v[96:99]
	v_mfma_f32_16x16x32_bf16 v[84:87], v[172:175], v[208:211], v[84:87]
	v_mfma_f32_16x16x32_bf16 v[80:83], v[180:183], v[208:211], v[80:83]
	v_mfma_f32_16x16x32_bf16 v[68:71], v[172:175], v[216:219], v[68:71]
	v_mfma_f32_16x16x32_bf16 v[64:67], v[180:183], v[216:219], v[64:67]
	s_barrier
	s_add_i32 s54, s46, s38
	s_mov_b32 m0, s54
	ds_read_b128 v[184:187], v153 offset:16384
	ds_read_b128 v[188:191], v153 offset:17408
	ds_read_b128 v[192:195], v153 offset:18432
	ds_read_b128 v[196:199], v153 offset:19456
	ds_read_b128 v[200:203], v153 offset:20480
	ds_read_b128 v[208:211], v153 offset:21504
	ds_read_b128 v[212:215], v153 offset:22528
	ds_read_b128 v[216:219], v153 offset:23552
	global_load_lds_dwordx4 v130, s[28:29]
	s_add_i32 m0, s54, 0x2000
	s_add_u32 s54, s28, 0x40000
	s_mov_b64 s[98:99], s[28:29]
	s_addc_u32 s55, s29, 0
	s_add_i32 s56, s47, s38
	global_load_lds_dwordx4 v134, s[28:29]
	s_mov_b32 m0, s56
	s_mov_b64 s[100:101], s[30:31]
	global_load_lds_dwordx4 v130, s[54:55]
	s_add_i32 m0, s56, 0x2000
	s_nop 0
	global_load_lds_dwordx4 v134, s[54:55]
	s_waitcnt vmcnt(6)
	s_waitcnt lgkmcnt(0)
	s_barrier
	s_waitcnt lgkmcnt(0)
	v_mfma_f32_16x16x32_bf16 v[60:63], v[144:147], v[184:187], v[60:63]
	v_mfma_f32_16x16x32_bf16 v[56:59], v[160:163], v[184:187], v[56:59]
	v_mfma_f32_16x16x32_bf16 v[44:47], v[144:147], v[192:195], v[44:47]
	v_mfma_f32_16x16x32_bf16 v[40:43], v[160:163], v[192:195], v[40:43]
	v_mfma_f32_16x16x32_bf16 v[28:31], v[144:147], v[200:203], v[28:31]
	v_mfma_f32_16x16x32_bf16 v[24:27], v[160:163], v[200:203], v[24:27]
	v_mfma_f32_16x16x32_bf16 v[12:15], v[144:147], v[212:215], v[12:15]
	v_mfma_f32_16x16x32_bf16 v[8:11], v[160:163], v[212:215], v[8:11]
	v_mfma_f32_16x16x32_bf16 v[60:63], v[156:159], v[188:191], v[60:63]
	v_mfma_f32_16x16x32_bf16 v[56:59], v[164:167], v[188:191], v[56:59]
	v_mfma_f32_16x16x32_bf16 v[44:47], v[156:159], v[196:199], v[44:47]
	v_mfma_f32_16x16x32_bf16 v[40:43], v[164:167], v[196:199], v[40:43]
	v_mfma_f32_16x16x32_bf16 v[28:31], v[156:159], v[208:211], v[28:31]
	v_mfma_f32_16x16x32_bf16 v[24:27], v[164:167], v[208:211], v[24:27]
	v_mfma_f32_16x16x32_bf16 v[12:15], v[156:159], v[216:219], v[12:15]
	v_mfma_f32_16x16x32_bf16 v[8:11], v[164:167], v[216:219], v[8:11]
	v_mfma_f32_16x16x32_bf16 v[52:55], v[168:171], v[184:187], v[52:55]
	v_mfma_f32_16x16x32_bf16 v[48:51], v[176:179], v[184:187], v[48:51]
	v_mfma_f32_16x16x32_bf16 v[36:39], v[168:171], v[192:195], v[36:39]
	v_mfma_f32_16x16x32_bf16 v[32:35], v[176:179], v[192:195], v[32:35]
	v_mfma_f32_16x16x32_bf16 v[20:23], v[168:171], v[200:203], v[20:23]
	v_mfma_f32_16x16x32_bf16 v[16:19], v[176:179], v[200:203], v[16:19]
	v_mfma_f32_16x16x32_bf16 v[4:7], v[168:171], v[212:215], v[4:7]
	v_mfma_f32_16x16x32_bf16 v[0:3], v[176:179], v[212:215], v[0:3]
	v_mfma_f32_16x16x32_bf16 v[52:55], v[172:175], v[188:191], v[52:55]
	v_mfma_f32_16x16x32_bf16 v[48:51], v[180:183], v[188:191], v[48:51]
	v_mfma_f32_16x16x32_bf16 v[36:39], v[172:175], v[196:199], v[36:39]
	v_mfma_f32_16x16x32_bf16 v[32:35], v[180:183], v[196:199], v[32:35]
	v_mfma_f32_16x16x32_bf16 v[20:23], v[172:175], v[208:211], v[20:23]
	v_mfma_f32_16x16x32_bf16 v[16:19], v[180:183], v[208:211], v[16:19]
	v_mfma_f32_16x16x32_bf16 v[4:7], v[172:175], v[216:219], v[4:7]
	v_mfma_f32_16x16x32_bf16 v[0:3], v[180:183], v[216:219], v[0:3]
	s_barrier
	s_mov_b32 m0, s39
	s_nop 0
	global_load_lds_dwordx4 v128, s[30:31]
	s_mov_b32 m0, s40
	s_nop 0
	global_load_lds_dwordx4 v132, s[30:31]
	s_add_i32 s54, 0, 0x18000
	v_add_u32_e32 v155, s54, v149
	s_add_i32 s55, 0, 0x1c000
	ds_read_b128 v[144:147], v155
	ds_read_b128 v[156:159], v155 offset:1024
	ds_read_b128 v[160:163], v155 offset:2048
	ds_read_b128 v[164:167], v155 offset:3072
	v_add_u32_e32 v155, s55, v149
	ds_read_b128 v[168:171], v155
	ds_read_b128 v[172:175], v155 offset:1024
	ds_read_b128 v[176:179], v155 offset:2048
	ds_read_b128 v[180:183], v155 offset:3072
	s_add_u32 s30, s30, 0x40000
	s_addc_u32 s31, s31, 0
	s_mov_b32 m0, s41
	ds_read_b128 v[184:187], v153 offset:32768
	ds_read_b128 v[188:191], v153 offset:33792
	ds_read_b128 v[192:195], v153 offset:34816
	ds_read_b128 v[196:199], v153 offset:35840
	ds_read_b128 v[200:203], v153 offset:36864
	ds_read_b128 v[208:211], v153 offset:37888
	ds_read_b128 v[212:215], v153 offset:38912
	ds_read_b128 v[216:219], v153 offset:39936
	global_load_lds_dwordx4 v128, s[30:31]
	s_mov_b32 m0, s42
	s_nop 0
	global_load_lds_dwordx4 v132, s[30:31]
	s_waitcnt vmcnt(8)
	s_waitcnt lgkmcnt(0)
	s_barrier
	s_waitcnt lgkmcnt(0)
	v_mfma_f32_16x16x32_bf16 v[124:127], v[144:147], v[184:187], v[124:127]
	v_mfma_f32_16x16x32_bf16 v[120:123], v[160:163], v[184:187], v[120:123]
	v_mfma_f32_16x16x32_bf16 v[108:111], v[144:147], v[192:195], v[108:111]
	v_mfma_f32_16x16x32_bf16 v[104:107], v[160:163], v[192:195], v[104:107]
	v_mfma_f32_16x16x32_bf16 v[92:95], v[144:147], v[200:203], v[92:95]
	v_mfma_f32_16x16x32_bf16 v[88:91], v[160:163], v[200:203], v[88:91]
	v_mfma_f32_16x16x32_bf16 v[76:79], v[144:147], v[212:215], v[76:79]
	v_mfma_f32_16x16x32_bf16 v[72:75], v[160:163], v[212:215], v[72:75]
	v_mfma_f32_16x16x32_bf16 v[124:127], v[156:159], v[188:191], v[124:127]
	v_mfma_f32_16x16x32_bf16 v[120:123], v[164:167], v[188:191], v[120:123]
	v_mfma_f32_16x16x32_bf16 v[108:111], v[156:159], v[196:199], v[108:111]
	v_mfma_f32_16x16x32_bf16 v[104:107], v[164:167], v[196:199], v[104:107]
	v_mfma_f32_16x16x32_bf16 v[92:95], v[156:159], v[208:211], v[92:95]
	v_mfma_f32_16x16x32_bf16 v[88:91], v[164:167], v[208:211], v[88:91]
	v_mfma_f32_16x16x32_bf16 v[76:79], v[156:159], v[216:219], v[76:79]
	v_mfma_f32_16x16x32_bf16 v[72:75], v[164:167], v[216:219], v[72:75]
	v_mfma_f32_16x16x32_bf16 v[116:119], v[168:171], v[184:187], v[116:119]
	v_mfma_f32_16x16x32_bf16 v[112:115], v[176:179], v[184:187], v[112:115]
	v_mfma_f32_16x16x32_bf16 v[100:103], v[168:171], v[192:195], v[100:103]
	v_mfma_f32_16x16x32_bf16 v[96:99], v[176:179], v[192:195], v[96:99]
	v_mfma_f32_16x16x32_bf16 v[84:87], v[168:171], v[200:203], v[84:87]
	v_mfma_f32_16x16x32_bf16 v[80:83], v[176:179], v[200:203], v[80:83]
	v_mfma_f32_16x16x32_bf16 v[68:71], v[168:171], v[212:215], v[68:71]
	v_mfma_f32_16x16x32_bf16 v[64:67], v[176:179], v[212:215], v[64:67]
	v_mfma_f32_16x16x32_bf16 v[116:119], v[172:175], v[188:191], v[116:119]
	v_mfma_f32_16x16x32_bf16 v[112:115], v[180:183], v[188:191], v[112:115]
	v_mfma_f32_16x16x32_bf16 v[100:103], v[172:175], v[196:199], v[100:103]
	v_mfma_f32_16x16x32_bf16 v[96:99], v[180:183], v[196:199], v[96:99]
	v_mfma_f32_16x16x32_bf16 v[84:87], v[172:175], v[208:211], v[84:87]
	v_mfma_f32_16x16x32_bf16 v[80:83], v[180:183], v[208:211], v[80:83]
	v_mfma_f32_16x16x32_bf16 v[68:71], v[172:175], v[216:219], v[68:71]
	v_mfma_f32_16x16x32_bf16 v[64:67], v[180:183], v[216:219], v[64:67]
	s_barrier
	s_add_i32 s30, s54, s38
	s_mov_b32 m0, s30
	ds_read_b128 v[184:187], v153 offset:49152
	ds_read_b128 v[188:191], v153 offset:50176
	ds_read_b128 v[192:195], v153 offset:51200
	ds_read_b128 v[196:199], v153 offset:52224
	ds_read_b128 v[200:203], v153 offset:53248
	ds_read_b128 v[208:211], v153 offset:54272
	ds_read_b128 v[212:215], v153 offset:55296
	ds_read_b128 v[216:219], v153 offset:56320
	global_load_lds_dwordx4 v205, s[28:29]
	s_add_i32 m0, s30, 0x2000
	s_add_u32 s28, s28, 0x40080
	s_addc_u32 s29, s29, 0
	s_add_i32 s30, s55, s38
	global_load_lds_dwordx4 v221, s[98:99]
	s_mov_b32 m0, s30
	s_nop 0
	global_load_lds_dwordx4 v130, s[28:29]
	s_add_i32 m0, s30, 0x2000
	s_nop 0
	global_load_lds_dwordx4 v134, s[28:29]
	s_mov_b32 m0, s44
	s_nop 0
	global_load_lds_dwordx4 v204, s[100:101]
	s_mov_b32 m0, s45
	s_nop 0
	global_load_lds_dwordx4 v220, s[100:101]
	s_waitcnt vmcnt(8)
	s_waitcnt lgkmcnt(0)
	s_barrier
	s_waitcnt lgkmcnt(0)
	v_mfma_f32_16x16x32_bf16 v[60:63], v[144:147], v[184:187], v[60:63]
	v_mfma_f32_16x16x32_bf16 v[56:59], v[160:163], v[184:187], v[56:59]
	v_mfma_f32_16x16x32_bf16 v[44:47], v[144:147], v[192:195], v[44:47]
	v_mfma_f32_16x16x32_bf16 v[40:43], v[160:163], v[192:195], v[40:43]
	v_mfma_f32_16x16x32_bf16 v[28:31], v[144:147], v[200:203], v[28:31]
	v_mfma_f32_16x16x32_bf16 v[24:27], v[160:163], v[200:203], v[24:27]
	v_mfma_f32_16x16x32_bf16 v[12:15], v[144:147], v[212:215], v[12:15]
	v_mfma_f32_16x16x32_bf16 v[8:11], v[160:163], v[212:215], v[8:11]
	v_mfma_f32_16x16x32_bf16 v[60:63], v[156:159], v[188:191], v[60:63]
	v_mfma_f32_16x16x32_bf16 v[56:59], v[164:167], v[188:191], v[56:59]
	v_mfma_f32_16x16x32_bf16 v[44:47], v[156:159], v[196:199], v[44:47]
	v_mfma_f32_16x16x32_bf16 v[40:43], v[164:167], v[196:199], v[40:43]
	v_mfma_f32_16x16x32_bf16 v[28:31], v[156:159], v[208:211], v[28:31]
	v_mfma_f32_16x16x32_bf16 v[24:27], v[164:167], v[208:211], v[24:27]
	v_mfma_f32_16x16x32_bf16 v[12:15], v[156:159], v[216:219], v[12:15]
	v_mfma_f32_16x16x32_bf16 v[8:11], v[164:167], v[216:219], v[8:11]
	v_mfma_f32_16x16x32_bf16 v[52:55], v[168:171], v[184:187], v[52:55]
	v_mfma_f32_16x16x32_bf16 v[48:51], v[176:179], v[184:187], v[48:51]
	v_mfma_f32_16x16x32_bf16 v[36:39], v[168:171], v[192:195], v[36:39]
	v_mfma_f32_16x16x32_bf16 v[32:35], v[176:179], v[192:195], v[32:35]
	v_mfma_f32_16x16x32_bf16 v[20:23], v[168:171], v[200:203], v[20:23]
	v_mfma_f32_16x16x32_bf16 v[16:19], v[176:179], v[200:203], v[16:19]
	v_mfma_f32_16x16x32_bf16 v[4:7], v[168:171], v[212:215], v[4:7]
	v_mfma_f32_16x16x32_bf16 v[0:3], v[176:179], v[212:215], v[0:3]
	v_mfma_f32_16x16x32_bf16 v[52:55], v[172:175], v[188:191], v[52:55]
	v_mfma_f32_16x16x32_bf16 v[48:51], v[180:183], v[188:191], v[48:51]
	v_mfma_f32_16x16x32_bf16 v[36:39], v[172:175], v[196:199], v[36:39]
	v_mfma_f32_16x16x32_bf16 v[32:35], v[180:183], v[196:199], v[32:35]
	v_mfma_f32_16x16x32_bf16 v[20:23], v[172:175], v[208:211], v[20:23]
	v_mfma_f32_16x16x32_bf16 v[16:19], v[180:183], v[208:211], v[16:19]
	v_mfma_f32_16x16x32_bf16 v[4:7], v[172:175], v[216:219], v[4:7]
	v_mfma_f32_16x16x32_bf16 v[0:3], v[180:183], v[216:219], v[0:3]
	s_barrier
	s_add_i32 s53, s53, 2
	s_add_u32 s51, s51, 0x100
	s_addc_u32 s52, s52, 0
	s_add_u32 s26, s26, 0x100
	s_addc_u32 s27, s27, 0
	s_cmp_gt_u32 s53, 13
	s_cbranch_scc0 .LBB0_699
	s_setprio 0
	s_and_b64 vcc, exec, s[16:17]
	s_cbranch_vccz .LBB0_702
	s_barrier

.LBB0_778:
	ds_read_b128 v[140:143], v147
	ds_read_b128 v[150:153], v147 offset:1024
	ds_read_b128 v[154:157], v147 offset:2048
	ds_read_b128 v[158:161], v147 offset:3072
	ds_read_b128 v[162:165], v148
	ds_read_b128 v[166:169], v148 offset:1024
	ds_read_b128 v[170:173], v148 offset:2048
	ds_read_b128 v[174:177], v148 offset:3072
	s_add_u32 s30, s28, 0x100
	s_addc_u32 s31, s29, 0
	s_cmp_eq_u32 s58, 60
	s_cselect_b32 s37, s21, s31
	s_cselect_b32 s36, s27, s30
	s_cselect_b32 s35, s19, s57
	s_cselect_b32 s34, s55, s56
	s_add_i32 m0, s44, 0xc000
	ds_read_b128 v[178:181], v149
	ds_read_b128 v[182:185], v149 offset:1024
	ds_read_b128 v[186:189], v149 offset:2048
	ds_read_b128 v[190:193], v149 offset:3072
	ds_read_b128 v[194:197], v149 offset:4096
	ds_read_b128 v[198:201], v149 offset:5120
	ds_read_b128 v[202:205], v149 offset:6144
	ds_read_b128 v[208:211], v149 offset:7168
	global_load_lds_dwordx4 v134, s[28:29]
	s_add_i32 m0, s44, 0xe000
	s_nop 0
	global_load_lds_dwordx4 v132, s[28:29]
	s_waitcnt vmcnt(8)
	s_waitcnt lgkmcnt(0)
	s_barrier
	s_waitcnt lgkmcnt(0)
	v_mfma_f32_16x16x32_bf16 v[124:127], v[140:143], v[178:181], v[124:127]
	v_mfma_f32_16x16x32_bf16 v[120:123], v[154:157], v[178:181], v[120:123]
	v_mfma_f32_16x16x32_bf16 v[108:111], v[140:143], v[186:189], v[108:111]
	v_mfma_f32_16x16x32_bf16 v[104:107], v[154:157], v[186:189], v[104:107]
	v_mfma_f32_16x16x32_bf16 v[92:95], v[140:143], v[194:197], v[92:95]
	v_mfma_f32_16x16x32_bf16 v[88:91], v[154:157], v[194:197], v[88:91]
	v_mfma_f32_16x16x32_bf16 v[76:79], v[140:143], v[202:205], v[76:79]
	v_mfma_f32_16x16x32_bf16 v[72:75], v[154:157], v[202:205], v[72:75]
	v_mfma_f32_16x16x32_bf16 v[124:127], v[150:153], v[182:185], v[124:127]
	v_mfma_f32_16x16x32_bf16 v[120:123], v[158:161], v[182:185], v[120:123]
	v_mfma_f32_16x16x32_bf16 v[108:111], v[150:153], v[190:193], v[108:111]
	v_mfma_f32_16x16x32_bf16 v[104:107], v[158:161], v[190:193], v[104:107]
	v_mfma_f32_16x16x32_bf16 v[92:95], v[150:153], v[198:201], v[92:95]
	v_mfma_f32_16x16x32_bf16 v[88:91], v[158:161], v[198:201], v[88:91]
	v_mfma_f32_16x16x32_bf16 v[76:79], v[150:153], v[208:211], v[76:79]
	v_mfma_f32_16x16x32_bf16 v[72:75], v[158:161], v[208:211], v[72:75]
	v_mfma_f32_16x16x32_bf16 v[116:119], v[162:165], v[178:181], v[116:119]
	v_mfma_f32_16x16x32_bf16 v[112:115], v[170:173], v[178:181], v[112:115]
	v_mfma_f32_16x16x32_bf16 v[100:103], v[162:165], v[186:189], v[100:103]
	v_mfma_f32_16x16x32_bf16 v[96:99], v[170:173], v[186:189], v[96:99]
	v_mfma_f32_16x16x32_bf16 v[84:87], v[162:165], v[194:197], v[84:87]
	v_mfma_f32_16x16x32_bf16 v[80:83], v[170:173], v[194:197], v[80:83]
	v_mfma_f32_16x16x32_bf16 v[68:71], v[162:165], v[202:205], v[68:71]
	v_mfma_f32_16x16x32_bf16 v[64:67], v[170:173], v[202:205], v[64:67]
	v_mfma_f32_16x16x32_bf16 v[116:119], v[166:169], v[182:185], v[116:119]
	v_mfma_f32_16x16x32_bf16 v[112:115], v[174:177], v[182:185], v[112:115]
	v_mfma_f32_16x16x32_bf16 v[100:103], v[166:169], v[190:193], v[100:103]
	v_mfma_f32_16x16x32_bf16 v[96:99], v[174:177], v[190:193], v[96:99]
	v_mfma_f32_16x16x32_bf16 v[84:87], v[166:169], v[198:201], v[84:87]
	v_mfma_f32_16x16x32_bf16 v[80:83], v[174:177], v[198:201], v[80:83]
	v_mfma_f32_16x16x32_bf16 v[68:71], v[166:169], v[208:211], v[68:71]
	v_mfma_f32_16x16x32_bf16 v[64:67], v[174:177], v[208:211], v[64:67]
	s_barrier
	s_add_i32 s28, s52, s43
	s_mov_b32 m0, s28
	ds_read_b128 v[178:181], v149 offset:16384
	ds_read_b128 v[182:185], v149 offset:17408
	ds_read_b128 v[186:189], v149 offset:18432
	ds_read_b128 v[190:193], v149 offset:19456
	ds_read_b128 v[194:197], v149 offset:20480
	ds_read_b128 v[198:201], v149 offset:21504
	ds_read_b128 v[202:205], v149 offset:22528
	ds_read_b128 v[208:211], v149 offset:23552
	global_load_lds_dwordx4 v128, s[34:35]
	s_add_i32 m0, s28, 0x2000
	s_add_u32 s28, s34, 0x100000
	s_mov_b64 s[98:99], s[34:35]
	s_addc_u32 s29, s35, 0
	s_add_i32 s59, s53, s43
	global_load_lds_dwordx4 v130, s[34:35]
	s_mov_b32 m0, s59
	s_nop 0
	global_load_lds_dwordx4 v128, s[28:29]
	s_add_i32 m0, s59, 0x2000
	s_nop 0
	global_load_lds_dwordx4 v130, s[28:29]
	s_waitcnt vmcnt(6)
	s_waitcnt lgkmcnt(0)
	s_barrier
	s_waitcnt lgkmcnt(0)
	v_mfma_f32_16x16x32_bf16 v[60:63], v[140:143], v[178:181], v[60:63]
	v_mfma_f32_16x16x32_bf16 v[56:59], v[154:157], v[178:181], v[56:59]
	v_mfma_f32_16x16x32_bf16 v[44:47], v[140:143], v[186:189], v[44:47]
	v_mfma_f32_16x16x32_bf16 v[40:43], v[154:157], v[186:189], v[40:43]
	v_mfma_f32_16x16x32_bf16 v[28:31], v[140:143], v[194:197], v[28:31]
	v_mfma_f32_16x16x32_bf16 v[24:27], v[154:157], v[194:197], v[24:27]
	v_mfma_f32_16x16x32_bf16 v[12:15], v[140:143], v[202:205], v[12:15]
	v_mfma_f32_16x16x32_bf16 v[8:11], v[154:157], v[202:205], v[8:11]
	v_mfma_f32_16x16x32_bf16 v[60:63], v[150:153], v[182:185], v[60:63]
	v_mfma_f32_16x16x32_bf16 v[56:59], v[158:161], v[182:185], v[56:59]
	v_mfma_f32_16x16x32_bf16 v[44:47], v[150:153], v[190:193], v[44:47]
	v_mfma_f32_16x16x32_bf16 v[40:43], v[158:161], v[190:193], v[40:43]
	v_mfma_f32_16x16x32_bf16 v[28:31], v[150:153], v[198:201], v[28:31]
	v_mfma_f32_16x16x32_bf16 v[24:27], v[158:161], v[198:201], v[24:27]
	v_mfma_f32_16x16x32_bf16 v[12:15], v[150:153], v[208:211], v[12:15]
	v_mfma_f32_16x16x32_bf16 v[8:11], v[158:161], v[208:211], v[8:11]
	v_mfma_f32_16x16x32_bf16 v[52:55], v[162:165], v[178:181], v[52:55]
	v_mfma_f32_16x16x32_bf16 v[48:51], v[170:173], v[178:181], v[48:51]
	v_mfma_f32_16x16x32_bf16 v[36:39], v[162:165], v[186:189], v[36:39]
	v_mfma_f32_16x16x32_bf16 v[32:35], v[170:173], v[186:189], v[32:35]
	v_mfma_f32_16x16x32_bf16 v[20:23], v[162:165], v[194:197], v[20:23]
	v_mfma_f32_16x16x32_bf16 v[16:19], v[170:173], v[194:197], v[16:19]
	v_mfma_f32_16x16x32_bf16 v[4:7], v[162:165], v[202:205], v[4:7]
	v_mfma_f32_16x16x32_bf16 v[0:3], v[170:173], v[202:205], v[0:3]
	v_mfma_f32_16x16x32_bf16 v[52:55], v[166:169], v[182:185], v[52:55]
	v_mfma_f32_16x16x32_bf16 v[48:51], v[174:177], v[182:185], v[48:51]
	v_mfma_f32_16x16x32_bf16 v[36:39], v[166:169], v[190:193], v[36:39]
	v_mfma_f32_16x16x32_bf16 v[32:35], v[174:177], v[190:193], v[32:35]
	v_mfma_f32_16x16x32_bf16 v[20:23], v[166:169], v[198:201], v[20:23]
	v_mfma_f32_16x16x32_bf16 v[16:19], v[174:177], v[198:201], v[16:19]
	v_mfma_f32_16x16x32_bf16 v[4:7], v[166:169], v[208:211], v[4:7]
	v_mfma_f32_16x16x32_bf16 v[0:3], v[174:177], v[208:211], v[0:3]
	s_barrier
	s_mov_b32 m0, s44
	s_nop 0
	global_load_lds_dwordx4 v128, s[36:37]
	s_mov_b32 m0, s45
	s_nop 0
	global_load_lds_dwordx4 v130, s[36:37]
	s_add_i32 s59, 0, 0x18000
	s_add_i32 s60, 0, 0x1c000
	v_add_u32_e32 v158, s59, v145
	v_add_u32_e32 v174, s60, v145
	ds_read_b128 v[140:143], v158
	ds_read_b128 v[150:153], v158 offset:1024
	ds_read_b128 v[154:157], v158 offset:2048
	ds_read_b128 v[158:161], v158 offset:3072
	ds_read_b128 v[162:165], v174
	ds_read_b128 v[166:169], v174 offset:1024
	ds_read_b128 v[170:173], v174 offset:2048
	ds_read_b128 v[174:177], v174 offset:3072
	s_add_u32 s28, s36, 0x100000
	s_addc_u32 s29, s37, 0
	s_mov_b32 m0, s46
	ds_read_b128 v[178:181], v149 offset:32768
	ds_read_b128 v[182:185], v149 offset:33792
	ds_read_b128 v[186:189], v149 offset:34816
	ds_read_b128 v[190:193], v149 offset:35840
	ds_read_b128 v[194:197], v149 offset:36864
	ds_read_b128 v[198:201], v149 offset:37888
	ds_read_b128 v[202:205], v149 offset:38912
	ds_read_b128 v[208:211], v149 offset:39936
	global_load_lds_dwordx4 v128, s[28:29]
	s_mov_b32 m0, s47
	s_nop 0
	global_load_lds_dwordx4 v130, s[28:29]
	s_waitcnt vmcnt(8)
	s_waitcnt lgkmcnt(0)
	s_barrier
	s_waitcnt lgkmcnt(0)
	v_mfma_f32_16x16x32_bf16 v[124:127], v[140:143], v[178:181], v[124:127]
	v_mfma_f32_16x16x32_bf16 v[120:123], v[154:157], v[178:181], v[120:123]
	v_mfma_f32_16x16x32_bf16 v[108:111], v[140:143], v[186:189], v[108:111]
	v_mfma_f32_16x16x32_bf16 v[104:107], v[154:157], v[186:189], v[104:107]
	v_mfma_f32_16x16x32_bf16 v[92:95], v[140:143], v[194:197], v[92:95]
	v_mfma_f32_16x16x32_bf16 v[88:91], v[154:157], v[194:197], v[88:91]
	v_mfma_f32_16x16x32_bf16 v[76:79], v[140:143], v[202:205], v[76:79]
	v_mfma_f32_16x16x32_bf16 v[72:75], v[154:157], v[202:205], v[72:75]
	v_mfma_f32_16x16x32_bf16 v[124:127], v[150:153], v[182:185], v[124:127]
	v_mfma_f32_16x16x32_bf16 v[120:123], v[158:161], v[182:185], v[120:123]
	v_mfma_f32_16x16x32_bf16 v[108:111], v[150:153], v[190:193], v[108:111]
	v_mfma_f32_16x16x32_bf16 v[104:107], v[158:161], v[190:193], v[104:107]
	v_mfma_f32_16x16x32_bf16 v[92:95], v[150:153], v[198:201], v[92:95]
	v_mfma_f32_16x16x32_bf16 v[88:91], v[158:161], v[198:201], v[88:91]
	v_mfma_f32_16x16x32_bf16 v[76:79], v[150:153], v[208:211], v[76:79]
	v_mfma_f32_16x16x32_bf16 v[72:75], v[158:161], v[208:211], v[72:75]
	v_mfma_f32_16x16x32_bf16 v[116:119], v[162:165], v[178:181], v[116:119]
	v_mfma_f32_16x16x32_bf16 v[112:115], v[170:173], v[178:181], v[112:115]
	v_mfma_f32_16x16x32_bf16 v[100:103], v[162:165], v[186:189], v[100:103]
	v_mfma_f32_16x16x32_bf16 v[96:99], v[170:173], v[186:189], v[96:99]
	v_mfma_f32_16x16x32_bf16 v[84:87], v[162:165], v[194:197], v[84:87]
	v_mfma_f32_16x16x32_bf16 v[80:83], v[170:173], v[194:197], v[80:83]
	v_mfma_f32_16x16x32_bf16 v[68:71], v[162:165], v[202:205], v[68:71]
	v_mfma_f32_16x16x32_bf16 v[64:67], v[170:173], v[202:205], v[64:67]
	v_mfma_f32_16x16x32_bf16 v[116:119], v[166:169], v[182:185], v[116:119]
	v_mfma_f32_16x16x32_bf16 v[112:115], v[174:177], v[182:185], v[112:115]
	v_mfma_f32_16x16x32_bf16 v[100:103], v[166:169], v[190:193], v[100:103]
	v_mfma_f32_16x16x32_bf16 v[96:99], v[174:177], v[190:193], v[96:99]
	v_mfma_f32_16x16x32_bf16 v[84:87], v[166:169], v[198:201], v[84:87]
	v_mfma_f32_16x16x32_bf16 v[80:83], v[174:177], v[198:201], v[80:83]
	v_mfma_f32_16x16x32_bf16 v[68:71], v[166:169], v[208:211], v[68:71]
	v_mfma_f32_16x16x32_bf16 v[64:67], v[174:177], v[208:211], v[64:67]
	s_barrier
	s_add_i32 s28, s59, s43
	s_mov_b32 m0, s28
	ds_read_b128 v[178:181], v149 offset:49152
	ds_read_b128 v[182:185], v149 offset:50176
	ds_read_b128 v[186:189], v149 offset:51200
	ds_read_b128 v[190:193], v149 offset:52224
	ds_read_b128 v[194:197], v149 offset:53248
	ds_read_b128 v[198:201], v149 offset:54272
	ds_read_b128 v[202:205], v149 offset:55296
	ds_read_b128 v[208:211], v149 offset:56320
	global_load_lds_dwordx4 v212, s[34:35]
	s_add_i32 m0, s28, 0x2000
	s_add_u32 s28, s34, 0x100080
	s_addc_u32 s29, s35, 0
	s_add_i32 s34, s60, s43
	global_load_lds_dwordx4 v213, s[98:99]
	s_mov_b32 m0, s34
	s_nop 0
	global_load_lds_dwordx4 v128, s[28:29]
	s_add_i32 m0, s34, 0x2000
	s_nop 0
	global_load_lds_dwordx4 v130, s[28:29]
	s_mov_b32 m0, s49
	s_nop 0
	global_load_lds_dwordx4 v212, s[36:37]
	s_mov_b32 m0, s50
	s_nop 0
	global_load_lds_dwordx4 v213, s[36:37]
	s_waitcnt vmcnt(8)
	s_waitcnt lgkmcnt(0)
	s_barrier
	s_waitcnt lgkmcnt(0)
	v_mfma_f32_16x16x32_bf16 v[60:63], v[140:143], v[178:181], v[60:63]
	v_mfma_f32_16x16x32_bf16 v[56:59], v[154:157], v[178:181], v[56:59]
	v_mfma_f32_16x16x32_bf16 v[44:47], v[140:143], v[186:189], v[44:47]
	v_mfma_f32_16x16x32_bf16 v[40:43], v[154:157], v[186:189], v[40:43]
	v_mfma_f32_16x16x32_bf16 v[28:31], v[140:143], v[194:197], v[28:31]
	v_mfma_f32_16x16x32_bf16 v[24:27], v[154:157], v[194:197], v[24:27]
	v_mfma_f32_16x16x32_bf16 v[12:15], v[140:143], v[202:205], v[12:15]
	v_mfma_f32_16x16x32_bf16 v[8:11], v[154:157], v[202:205], v[8:11]
	v_mfma_f32_16x16x32_bf16 v[60:63], v[150:153], v[182:185], v[60:63]
	v_mfma_f32_16x16x32_bf16 v[56:59], v[158:161], v[182:185], v[56:59]
	v_mfma_f32_16x16x32_bf16 v[44:47], v[150:153], v[190:193], v[44:47]
	v_mfma_f32_16x16x32_bf16 v[40:43], v[158:161], v[190:193], v[40:43]
	v_mfma_f32_16x16x32_bf16 v[28:31], v[150:153], v[198:201], v[28:31]
	v_mfma_f32_16x16x32_bf16 v[24:27], v[158:161], v[198:201], v[24:27]
	v_mfma_f32_16x16x32_bf16 v[12:15], v[150:153], v[208:211], v[12:15]
	v_mfma_f32_16x16x32_bf16 v[8:11], v[158:161], v[208:211], v[8:11]
	v_mfma_f32_16x16x32_bf16 v[52:55], v[162:165], v[178:181], v[52:55]
	v_mfma_f32_16x16x32_bf16 v[48:51], v[170:173], v[178:181], v[48:51]
	v_mfma_f32_16x16x32_bf16 v[36:39], v[162:165], v[186:189], v[36:39]
	v_mfma_f32_16x16x32_bf16 v[32:35], v[170:173], v[186:189], v[32:35]
	v_mfma_f32_16x16x32_bf16 v[20:23], v[162:165], v[194:197], v[20:23]
	v_mfma_f32_16x16x32_bf16 v[16:19], v[170:173], v[194:197], v[16:19]
	v_mfma_f32_16x16x32_bf16 v[4:7], v[162:165], v[202:205], v[4:7]
	v_mfma_f32_16x16x32_bf16 v[0:3], v[170:173], v[202:205], v[0:3]
	v_mfma_f32_16x16x32_bf16 v[52:55], v[166:169], v[182:185], v[52:55]
	v_mfma_f32_16x16x32_bf16 v[48:51], v[174:177], v[182:185], v[48:51]
	v_mfma_f32_16x16x32_bf16 v[36:39], v[166:169], v[190:193], v[36:39]
	v_mfma_f32_16x16x32_bf16 v[32:35], v[174:177], v[190:193], v[32:35]
	v_mfma_f32_16x16x32_bf16 v[20:23], v[166:169], v[198:201], v[20:23]
	v_mfma_f32_16x16x32_bf16 v[16:19], v[174:177], v[198:201], v[16:19]
	v_mfma_f32_16x16x32_bf16 v[4:7], v[166:169], v[208:211], v[4:7]
	v_mfma_f32_16x16x32_bf16 v[0:3], v[174:177], v[208:211], v[0:3]
	s_barrier
	s_add_i32 s58, s58, 2
	s_add_u32 s56, s56, 0x100
	s_addc_u32 s57, s57, 0
	s_cmp_gt_u32 s58, 61
	s_mov_b64 s[28:29], s[30:31]
	s_cbranch_scc0 .LBB0_778
	s_setprio 0
	s_and_b64 vcc, exec, s[16:17]
	s_cbranch_vccz .LBB0_781
	s_barrier

.LBB0_895:
	ds_read_b128 v[140:143], v153
	ds_read_b128 v[144:147], v153 offset:1024
	ds_read_b128 v[158:161], v153 offset:2048
	ds_read_b128 v[162:165], v153 offset:3072
	ds_read_b128 v[166:169], v154
	ds_read_b128 v[170:173], v154 offset:1024
	ds_read_b128 v[174:177], v154 offset:2048
	ds_read_b128 v[178:181], v154 offset:3072
	s_add_u32 s38, s36, 0xfffc0080
	s_addc_u32 s39, s37, -1
	s_cmp_eq_u32 s61, 12
	s_cselect_b32 s41, s3, s39
	s_cselect_b32 s40, s29, s38
	s_cselect_b32 s39, s27, s60
	s_cselect_b32 s38, s58, s59
	s_add_i32 m0, s46, 0xc000
	ds_read_b128 v[182:185], v155
	ds_read_b128 v[186:189], v155 offset:1024
	ds_read_b128 v[190:193], v155 offset:2048
	ds_read_b128 v[194:197], v155 offset:3072
	ds_read_b128 v[198:201], v155 offset:4096
	ds_read_b128 v[202:205], v155 offset:5120
	ds_read_b128 v[208:211], v155 offset:6144
	ds_read_b128 v[212:215], v155 offset:7168
	global_load_lds_dwordx4 v134, s[36:37]
	s_add_i32 m0, s46, 0xe000
	s_nop 0
	global_load_lds_dwordx4 v132, s[36:37]
	s_waitcnt vmcnt(8)
	s_waitcnt lgkmcnt(0)
	s_barrier
	s_waitcnt lgkmcnt(0)
	v_mfma_f32_16x16x32_bf16 v[124:127], v[140:143], v[182:185], v[124:127]
	v_mfma_f32_16x16x32_bf16 v[120:123], v[158:161], v[182:185], v[120:123]
	v_mfma_f32_16x16x32_bf16 v[108:111], v[140:143], v[190:193], v[108:111]
	v_mfma_f32_16x16x32_bf16 v[104:107], v[158:161], v[190:193], v[104:107]
	v_mfma_f32_16x16x32_bf16 v[92:95], v[140:143], v[198:201], v[92:95]
	v_mfma_f32_16x16x32_bf16 v[88:91], v[158:161], v[198:201], v[88:91]
	v_mfma_f32_16x16x32_bf16 v[76:79], v[140:143], v[208:211], v[76:79]
	v_mfma_f32_16x16x32_bf16 v[72:75], v[158:161], v[208:211], v[72:75]
	v_mfma_f32_16x16x32_bf16 v[124:127], v[144:147], v[186:189], v[124:127]
	v_mfma_f32_16x16x32_bf16 v[120:123], v[162:165], v[186:189], v[120:123]
	v_mfma_f32_16x16x32_bf16 v[108:111], v[144:147], v[194:197], v[108:111]
	v_mfma_f32_16x16x32_bf16 v[104:107], v[162:165], v[194:197], v[104:107]
	v_mfma_f32_16x16x32_bf16 v[92:95], v[144:147], v[202:205], v[92:95]
	v_mfma_f32_16x16x32_bf16 v[88:91], v[162:165], v[202:205], v[88:91]
	v_mfma_f32_16x16x32_bf16 v[76:79], v[144:147], v[212:215], v[76:79]
	v_mfma_f32_16x16x32_bf16 v[72:75], v[162:165], v[212:215], v[72:75]
	v_mfma_f32_16x16x32_bf16 v[116:119], v[166:169], v[182:185], v[116:119]
	v_mfma_f32_16x16x32_bf16 v[112:115], v[174:177], v[182:185], v[112:115]
	v_mfma_f32_16x16x32_bf16 v[100:103], v[166:169], v[190:193], v[100:103]
	v_mfma_f32_16x16x32_bf16 v[96:99], v[174:177], v[190:193], v[96:99]
	v_mfma_f32_16x16x32_bf16 v[84:87], v[166:169], v[198:201], v[84:87]
	v_mfma_f32_16x16x32_bf16 v[80:83], v[174:177], v[198:201], v[80:83]
	v_mfma_f32_16x16x32_bf16 v[68:71], v[166:169], v[208:211], v[68:71]
	v_mfma_f32_16x16x32_bf16 v[64:67], v[174:177], v[208:211], v[64:67]
	v_mfma_f32_16x16x32_bf16 v[116:119], v[170:173], v[186:189], v[116:119]
	v_mfma_f32_16x16x32_bf16 v[112:115], v[178:181], v[186:189], v[112:115]
	v_mfma_f32_16x16x32_bf16 v[100:103], v[170:173], v[194:197], v[100:103]
	v_mfma_f32_16x16x32_bf16 v[96:99], v[178:181], v[194:197], v[96:99]
	v_mfma_f32_16x16x32_bf16 v[84:87], v[170:173], v[202:205], v[84:87]
	v_mfma_f32_16x16x32_bf16 v[80:83], v[178:181], v[202:205], v[80:83]
	v_mfma_f32_16x16x32_bf16 v[68:71], v[170:173], v[212:215], v[68:71]
	v_mfma_f32_16x16x32_bf16 v[64:67], v[178:181], v[212:215], v[64:67]
	s_barrier
	s_add_i32 s62, s54, s45
	s_mov_b32 m0, s62
	ds_read_b128 v[182:185], v155 offset:16384
	ds_read_b128 v[186:189], v155 offset:17408
	ds_read_b128 v[190:193], v155 offset:18432
	ds_read_b128 v[194:197], v155 offset:19456
	ds_read_b128 v[198:201], v155 offset:20480
	ds_read_b128 v[202:205], v155 offset:21504
	ds_read_b128 v[208:211], v155 offset:22528
	ds_read_b128 v[212:215], v155 offset:23552
	global_load_lds_dwordx4 v128, s[38:39]
	s_add_i32 m0, s62, 0x2000
	s_add_u32 s62, s38, 0x40000
	s_mov_b64 s[98:99], s[38:39]
	s_addc_u32 s63, s39, 0
	s_add_i32 s64, s55, s45
	global_load_lds_dwordx4 v130, s[38:39]
	s_mov_b32 m0, s64
	s_mov_b64 s[100:101], s[40:41]
	global_load_lds_dwordx4 v128, s[62:63]
	s_add_i32 m0, s64, 0x2000
	s_nop 0
	global_load_lds_dwordx4 v130, s[62:63]
	s_waitcnt vmcnt(6)
	s_waitcnt lgkmcnt(0)
	s_barrier
	s_waitcnt lgkmcnt(0)
	v_mfma_f32_16x16x32_bf16 v[60:63], v[140:143], v[182:185], v[60:63]
	v_mfma_f32_16x16x32_bf16 v[56:59], v[158:161], v[182:185], v[56:59]
	v_mfma_f32_16x16x32_bf16 v[44:47], v[140:143], v[190:193], v[44:47]
	v_mfma_f32_16x16x32_bf16 v[40:43], v[158:161], v[190:193], v[40:43]
	v_mfma_f32_16x16x32_bf16 v[28:31], v[140:143], v[198:201], v[28:31]
	v_mfma_f32_16x16x32_bf16 v[24:27], v[158:161], v[198:201], v[24:27]
	v_mfma_f32_16x16x32_bf16 v[12:15], v[140:143], v[208:211], v[12:15]
	v_mfma_f32_16x16x32_bf16 v[8:11], v[158:161], v[208:211], v[8:11]
	v_mfma_f32_16x16x32_bf16 v[60:63], v[144:147], v[186:189], v[60:63]
	v_mfma_f32_16x16x32_bf16 v[56:59], v[162:165], v[186:189], v[56:59]
	v_mfma_f32_16x16x32_bf16 v[44:47], v[144:147], v[194:197], v[44:47]
	v_mfma_f32_16x16x32_bf16 v[40:43], v[162:165], v[194:197], v[40:43]
	v_mfma_f32_16x16x32_bf16 v[28:31], v[144:147], v[202:205], v[28:31]
	v_mfma_f32_16x16x32_bf16 v[24:27], v[162:165], v[202:205], v[24:27]
	v_mfma_f32_16x16x32_bf16 v[12:15], v[144:147], v[212:215], v[12:15]
	v_mfma_f32_16x16x32_bf16 v[8:11], v[162:165], v[212:215], v[8:11]
	v_mfma_f32_16x16x32_bf16 v[52:55], v[166:169], v[182:185], v[52:55]
	v_mfma_f32_16x16x32_bf16 v[48:51], v[174:177], v[182:185], v[48:51]
	v_mfma_f32_16x16x32_bf16 v[36:39], v[166:169], v[190:193], v[36:39]
	v_mfma_f32_16x16x32_bf16 v[32:35], v[174:177], v[190:193], v[32:35]
	v_mfma_f32_16x16x32_bf16 v[20:23], v[166:169], v[198:201], v[20:23]
	v_mfma_f32_16x16x32_bf16 v[16:19], v[174:177], v[198:201], v[16:19]
	v_mfma_f32_16x16x32_bf16 v[4:7], v[166:169], v[208:211], v[4:7]
	v_mfma_f32_16x16x32_bf16 v[0:3], v[174:177], v[208:211], v[0:3]
	v_mfma_f32_16x16x32_bf16 v[52:55], v[170:173], v[186:189], v[52:55]
	v_mfma_f32_16x16x32_bf16 v[48:51], v[178:181], v[186:189], v[48:51]
	v_mfma_f32_16x16x32_bf16 v[36:39], v[170:173], v[194:197], v[36:39]
	v_mfma_f32_16x16x32_bf16 v[32:35], v[178:181], v[194:197], v[32:35]
	v_mfma_f32_16x16x32_bf16 v[20:23], v[170:173], v[202:205], v[20:23]
	v_mfma_f32_16x16x32_bf16 v[16:19], v[178:181], v[202:205], v[16:19]
	v_mfma_f32_16x16x32_bf16 v[4:7], v[170:173], v[212:215], v[4:7]
	v_mfma_f32_16x16x32_bf16 v[0:3], v[178:181], v[212:215], v[0:3]
	s_barrier
	s_mov_b32 m0, s46
	s_nop 0
	global_load_lds_dwordx4 v128, s[40:41]
	s_mov_b32 m0, s47
	s_nop 0
	global_load_lds_dwordx4 v130, s[40:41]
	s_add_i32 s62, 0, 0x18000
	v_add_u32_e32 v157, s62, v151
	s_add_i32 s63, 0, 0x1c000
	ds_read_b128 v[140:143], v157
	ds_read_b128 v[144:147], v157 offset:1024
	ds_read_b128 v[158:161], v157 offset:2048
	ds_read_b128 v[162:165], v157 offset:3072
	v_add_u32_e32 v157, s63, v151
	ds_read_b128 v[166:169], v157
	ds_read_b128 v[170:173], v157 offset:1024
	ds_read_b128 v[174:177], v157 offset:2048
	ds_read_b128 v[178:181], v157 offset:3072
	s_add_u32 s40, s40, 0x40000
	s_addc_u32 s41, s41, 0
	s_mov_b32 m0, s48
	ds_read_b128 v[182:185], v155 offset:32768
	ds_read_b128 v[186:189], v155 offset:33792
	ds_read_b128 v[190:193], v155 offset:34816
	ds_read_b128 v[194:197], v155 offset:35840
	ds_read_b128 v[198:201], v155 offset:36864
	ds_read_b128 v[202:205], v155 offset:37888
	ds_read_b128 v[208:211], v155 offset:38912
	ds_read_b128 v[212:215], v155 offset:39936
	global_load_lds_dwordx4 v128, s[40:41]
	s_mov_b32 m0, s49
	s_nop 0
	global_load_lds_dwordx4 v130, s[40:41]
	s_waitcnt vmcnt(8)
	s_waitcnt lgkmcnt(0)
	s_barrier
	s_waitcnt lgkmcnt(0)
	v_mfma_f32_16x16x32_bf16 v[124:127], v[140:143], v[182:185], v[124:127]
	v_mfma_f32_16x16x32_bf16 v[120:123], v[158:161], v[182:185], v[120:123]
	v_mfma_f32_16x16x32_bf16 v[108:111], v[140:143], v[190:193], v[108:111]
	v_mfma_f32_16x16x32_bf16 v[104:107], v[158:161], v[190:193], v[104:107]
	v_mfma_f32_16x16x32_bf16 v[92:95], v[140:143], v[198:201], v[92:95]
	v_mfma_f32_16x16x32_bf16 v[88:91], v[158:161], v[198:201], v[88:91]
	v_mfma_f32_16x16x32_bf16 v[76:79], v[140:143], v[208:211], v[76:79]
	v_mfma_f32_16x16x32_bf16 v[72:75], v[158:161], v[208:211], v[72:75]
	v_mfma_f32_16x16x32_bf16 v[124:127], v[144:147], v[186:189], v[124:127]
	v_mfma_f32_16x16x32_bf16 v[120:123], v[162:165], v[186:189], v[120:123]
	v_mfma_f32_16x16x32_bf16 v[108:111], v[144:147], v[194:197], v[108:111]
	v_mfma_f32_16x16x32_bf16 v[104:107], v[162:165], v[194:197], v[104:107]
	v_mfma_f32_16x16x32_bf16 v[92:95], v[144:147], v[202:205], v[92:95]
	v_mfma_f32_16x16x32_bf16 v[88:91], v[162:165], v[202:205], v[88:91]
	v_mfma_f32_16x16x32_bf16 v[76:79], v[144:147], v[212:215], v[76:79]
	v_mfma_f32_16x16x32_bf16 v[72:75], v[162:165], v[212:215], v[72:75]
	v_mfma_f32_16x16x32_bf16 v[116:119], v[166:169], v[182:185], v[116:119]
	v_mfma_f32_16x16x32_bf16 v[112:115], v[174:177], v[182:185], v[112:115]
	v_mfma_f32_16x16x32_bf16 v[100:103], v[166:169], v[190:193], v[100:103]
	v_mfma_f32_16x16x32_bf16 v[96:99], v[174:177], v[190:193], v[96:99]
	v_mfma_f32_16x16x32_bf16 v[84:87], v[166:169], v[198:201], v[84:87]
	v_mfma_f32_16x16x32_bf16 v[80:83], v[174:177], v[198:201], v[80:83]
	v_mfma_f32_16x16x32_bf16 v[68:71], v[166:169], v[208:211], v[68:71]
	v_mfma_f32_16x16x32_bf16 v[64:67], v[174:177], v[208:211], v[64:67]
	v_mfma_f32_16x16x32_bf16 v[116:119], v[170:173], v[186:189], v[116:119]
	v_mfma_f32_16x16x32_bf16 v[112:115], v[178:181], v[186:189], v[112:115]
	v_mfma_f32_16x16x32_bf16 v[100:103], v[170:173], v[194:197], v[100:103]
	v_mfma_f32_16x16x32_bf16 v[96:99], v[178:181], v[194:197], v[96:99]
	v_mfma_f32_16x16x32_bf16 v[84:87], v[170:173], v[202:205], v[84:87]
	v_mfma_f32_16x16x32_bf16 v[80:83], v[178:181], v[202:205], v[80:83]
	v_mfma_f32_16x16x32_bf16 v[68:71], v[170:173], v[212:215], v[68:71]
	v_mfma_f32_16x16x32_bf16 v[64:67], v[178:181], v[212:215], v[64:67]
	s_barrier
	s_add_i32 s40, s62, s45
	s_mov_b32 m0, s40
	ds_read_b128 v[182:185], v155 offset:49152
	ds_read_b128 v[186:189], v155 offset:50176
	ds_read_b128 v[190:193], v155 offset:51200
	ds_read_b128 v[194:197], v155 offset:52224
	ds_read_b128 v[198:201], v155 offset:53248
	ds_read_b128 v[202:205], v155 offset:54272
	ds_read_b128 v[208:211], v155 offset:55296
	ds_read_b128 v[212:215], v155 offset:56320
	global_load_lds_dwordx4 v148, s[38:39]
	s_add_i32 m0, s40, 0x2000
	s_add_u32 s38, s38, 0x40080
	s_addc_u32 s39, s39, 0
	s_add_i32 s40, s63, s45
	global_load_lds_dwordx4 v149, s[98:99]
	s_mov_b32 m0, s40
	s_nop 0
	global_load_lds_dwordx4 v128, s[38:39]
	s_add_i32 m0, s40, 0x2000
	s_nop 0
	global_load_lds_dwordx4 v130, s[38:39]
	s_mov_b32 m0, s51
	s_nop 0
	global_load_lds_dwordx4 v148, s[100:101]
	s_mov_b32 m0, s52
	s_nop 0
	global_load_lds_dwordx4 v149, s[100:101]
	s_waitcnt vmcnt(8)
	s_waitcnt lgkmcnt(0)
	s_barrier
	s_waitcnt lgkmcnt(0)
	v_mfma_f32_16x16x32_bf16 v[60:63], v[140:143], v[182:185], v[60:63]
	v_mfma_f32_16x16x32_bf16 v[56:59], v[158:161], v[182:185], v[56:59]
	v_mfma_f32_16x16x32_bf16 v[44:47], v[140:143], v[190:193], v[44:47]
	v_mfma_f32_16x16x32_bf16 v[40:43], v[158:161], v[190:193], v[40:43]
	v_mfma_f32_16x16x32_bf16 v[28:31], v[140:143], v[198:201], v[28:31]
	v_mfma_f32_16x16x32_bf16 v[24:27], v[158:161], v[198:201], v[24:27]
	v_mfma_f32_16x16x32_bf16 v[12:15], v[140:143], v[208:211], v[12:15]
	v_mfma_f32_16x16x32_bf16 v[8:11], v[158:161], v[208:211], v[8:11]
	v_mfma_f32_16x16x32_bf16 v[60:63], v[144:147], v[186:189], v[60:63]
	v_mfma_f32_16x16x32_bf16 v[56:59], v[162:165], v[186:189], v[56:59]
	v_mfma_f32_16x16x32_bf16 v[44:47], v[144:147], v[194:197], v[44:47]
	v_mfma_f32_16x16x32_bf16 v[40:43], v[162:165], v[194:197], v[40:43]
	v_mfma_f32_16x16x32_bf16 v[28:31], v[144:147], v[202:205], v[28:31]
	v_mfma_f32_16x16x32_bf16 v[24:27], v[162:165], v[202:205], v[24:27]
	v_mfma_f32_16x16x32_bf16 v[12:15], v[144:147], v[212:215], v[12:15]
	v_mfma_f32_16x16x32_bf16 v[8:11], v[162:165], v[212:215], v[8:11]
	v_mfma_f32_16x16x32_bf16 v[52:55], v[166:169], v[182:185], v[52:55]
	v_mfma_f32_16x16x32_bf16 v[48:51], v[174:177], v[182:185], v[48:51]
	v_mfma_f32_16x16x32_bf16 v[36:39], v[166:169], v[190:193], v[36:39]
	v_mfma_f32_16x16x32_bf16 v[32:35], v[174:177], v[190:193], v[32:35]
	v_mfma_f32_16x16x32_bf16 v[20:23], v[166:169], v[198:201], v[20:23]
	v_mfma_f32_16x16x32_bf16 v[16:19], v[174:177], v[198:201], v[16:19]
	v_mfma_f32_16x16x32_bf16 v[4:7], v[166:169], v[208:211], v[4:7]
	v_mfma_f32_16x16x32_bf16 v[0:3], v[174:177], v[208:211], v[0:3]
	v_mfma_f32_16x16x32_bf16 v[52:55], v[170:173], v[186:189], v[52:55]
	v_mfma_f32_16x16x32_bf16 v[48:51], v[178:181], v[186:189], v[48:51]
	v_mfma_f32_16x16x32_bf16 v[36:39], v[170:173], v[194:197], v[36:39]
	v_mfma_f32_16x16x32_bf16 v[32:35], v[178:181], v[194:197], v[32:35]
	v_mfma_f32_16x16x32_bf16 v[20:23], v[170:173], v[202:205], v[20:23]
	v_mfma_f32_16x16x32_bf16 v[16:19], v[178:181], v[202:205], v[16:19]
	v_mfma_f32_16x16x32_bf16 v[4:7], v[170:173], v[212:215], v[4:7]
	v_mfma_f32_16x16x32_bf16 v[0:3], v[178:181], v[212:215], v[0:3]
	s_barrier
	s_add_i32 s61, s61, 2
	s_add_u32 s59, s59, 0x100
	s_addc_u32 s60, s60, 0
	s_add_u32 s36, s36, 0x100
	s_addc_u32 s37, s37, 0
	s_cmp_gt_u32 s61, 13
	s_cbranch_scc0 .LBB0_895
	s_setprio 0
	s_and_b64 vcc, exec, s[24:25]
	s_cbranch_vccz .LBB0_898
	s_barrier

.LBB0_988:
	ds_read_b128 v[144:147], v151
	ds_read_b128 v[156:159], v151 offset:1024
	ds_read_b128 v[160:163], v151 offset:2048
	ds_read_b128 v[164:167], v151 offset:3072
	ds_read_b128 v[168:171], v152
	ds_read_b128 v[172:175], v152 offset:1024
	ds_read_b128 v[176:179], v152 offset:2048
	ds_read_b128 v[180:183], v152 offset:3072
	s_add_u32 s26, s6, 0xfffc0080
	s_addc_u32 s27, s7, -1
	s_cmp_eq_u32 s53, 12
	s_cselect_b32 s29, s19, s27
	s_cselect_b32 s28, s49, s26
	s_cselect_b32 s27, s17, s52
	s_cselect_b32 s26, s50, s51
	s_add_i32 m0, s25, 0xc000
	ds_read_b128 v[184:187], v153
	ds_read_b128 v[188:191], v153 offset:1024
	ds_read_b128 v[192:195], v153 offset:2048
	ds_read_b128 v[196:199], v153 offset:3072
	ds_read_b128 v[200:203], v153 offset:4096
	ds_read_b128 v[208:211], v153 offset:5120
	ds_read_b128 v[212:215], v153 offset:6144
	ds_read_b128 v[216:219], v153 offset:7168
	global_load_lds_dwordx4 v138, s[6:7]
	s_add_i32 m0, s25, 0xe000
	s_nop 0
	global_load_lds_dwordx4 v136, s[6:7]
	s_waitcnt vmcnt(8)
	s_waitcnt lgkmcnt(0)
	s_barrier
	s_waitcnt lgkmcnt(0)
	v_mfma_f32_16x16x32_bf16 v[124:127], v[144:147], v[184:187], v[124:127]
	v_mfma_f32_16x16x32_bf16 v[120:123], v[160:163], v[184:187], v[120:123]
	v_mfma_f32_16x16x32_bf16 v[108:111], v[144:147], v[192:195], v[108:111]
	v_mfma_f32_16x16x32_bf16 v[104:107], v[160:163], v[192:195], v[104:107]
	v_mfma_f32_16x16x32_bf16 v[92:95], v[144:147], v[200:203], v[92:95]
	v_mfma_f32_16x16x32_bf16 v[88:91], v[160:163], v[200:203], v[88:91]
	v_mfma_f32_16x16x32_bf16 v[76:79], v[144:147], v[212:215], v[76:79]
	v_mfma_f32_16x16x32_bf16 v[72:75], v[160:163], v[212:215], v[72:75]
	v_mfma_f32_16x16x32_bf16 v[124:127], v[156:159], v[188:191], v[124:127]
	v_mfma_f32_16x16x32_bf16 v[120:123], v[164:167], v[188:191], v[120:123]
	v_mfma_f32_16x16x32_bf16 v[108:111], v[156:159], v[196:199], v[108:111]
	v_mfma_f32_16x16x32_bf16 v[104:107], v[164:167], v[196:199], v[104:107]
	v_mfma_f32_16x16x32_bf16 v[92:95], v[156:159], v[208:211], v[92:95]
	v_mfma_f32_16x16x32_bf16 v[88:91], v[164:167], v[208:211], v[88:91]
	v_mfma_f32_16x16x32_bf16 v[76:79], v[156:159], v[216:219], v[76:79]
	v_mfma_f32_16x16x32_bf16 v[72:75], v[164:167], v[216:219], v[72:75]
	v_mfma_f32_16x16x32_bf16 v[116:119], v[168:171], v[184:187], v[116:119]
	v_mfma_f32_16x16x32_bf16 v[112:115], v[176:179], v[184:187], v[112:115]
	v_mfma_f32_16x16x32_bf16 v[100:103], v[168:171], v[192:195], v[100:103]
	v_mfma_f32_16x16x32_bf16 v[96:99], v[176:179], v[192:195], v[96:99]
	v_mfma_f32_16x16x32_bf16 v[84:87], v[168:171], v[200:203], v[84:87]
	v_mfma_f32_16x16x32_bf16 v[80:83], v[176:179], v[200:203], v[80:83]
	v_mfma_f32_16x16x32_bf16 v[68:71], v[168:171], v[212:215], v[68:71]
	v_mfma_f32_16x16x32_bf16 v[64:67], v[176:179], v[212:215], v[64:67]
	v_mfma_f32_16x16x32_bf16 v[116:119], v[172:175], v[188:191], v[116:119]
	v_mfma_f32_16x16x32_bf16 v[112:115], v[180:183], v[188:191], v[112:115]
	v_mfma_f32_16x16x32_bf16 v[100:103], v[172:175], v[196:199], v[100:103]
	v_mfma_f32_16x16x32_bf16 v[96:99], v[180:183], v[196:199], v[96:99]
	v_mfma_f32_16x16x32_bf16 v[84:87], v[172:175], v[208:211], v[84:87]
	v_mfma_f32_16x16x32_bf16 v[80:83], v[180:183], v[208:211], v[80:83]
	v_mfma_f32_16x16x32_bf16 v[68:71], v[172:175], v[216:219], v[68:71]
	v_mfma_f32_16x16x32_bf16 v[64:67], v[180:183], v[216:219], v[64:67]
	s_barrier
	s_add_i32 s54, s45, s38
	s_mov_b32 m0, s54
	ds_read_b128 v[184:187], v153 offset:16384
	ds_read_b128 v[188:191], v153 offset:17408
	ds_read_b128 v[192:195], v153 offset:18432
	ds_read_b128 v[196:199], v153 offset:19456
	ds_read_b128 v[200:203], v153 offset:20480
	ds_read_b128 v[208:211], v153 offset:21504
	ds_read_b128 v[212:215], v153 offset:22528
	ds_read_b128 v[216:219], v153 offset:23552
	global_load_lds_dwordx4 v130, s[26:27]
	s_add_i32 m0, s54, 0x2000
	s_add_u32 s54, s26, 0x40000
	s_mov_b64 s[98:99], s[26:27]
	s_addc_u32 s55, s27, 0
	s_add_i32 s56, s46, s38
	global_load_lds_dwordx4 v134, s[26:27]
	s_mov_b32 m0, s56
	s_mov_b64 s[100:101], s[28:29]
	global_load_lds_dwordx4 v130, s[54:55]
	s_add_i32 m0, s56, 0x2000
	s_nop 0
	global_load_lds_dwordx4 v134, s[54:55]
	s_waitcnt vmcnt(6)
	s_waitcnt lgkmcnt(0)
	s_barrier
	s_waitcnt lgkmcnt(0)
	v_mfma_f32_16x16x32_bf16 v[60:63], v[144:147], v[184:187], v[60:63]
	v_mfma_f32_16x16x32_bf16 v[56:59], v[160:163], v[184:187], v[56:59]
	v_mfma_f32_16x16x32_bf16 v[44:47], v[144:147], v[192:195], v[44:47]
	v_mfma_f32_16x16x32_bf16 v[40:43], v[160:163], v[192:195], v[40:43]
	v_mfma_f32_16x16x32_bf16 v[28:31], v[144:147], v[200:203], v[28:31]
	v_mfma_f32_16x16x32_bf16 v[24:27], v[160:163], v[200:203], v[24:27]
	v_mfma_f32_16x16x32_bf16 v[12:15], v[144:147], v[212:215], v[12:15]
	v_mfma_f32_16x16x32_bf16 v[8:11], v[160:163], v[212:215], v[8:11]
	v_mfma_f32_16x16x32_bf16 v[60:63], v[156:159], v[188:191], v[60:63]
	v_mfma_f32_16x16x32_bf16 v[56:59], v[164:167], v[188:191], v[56:59]
	v_mfma_f32_16x16x32_bf16 v[44:47], v[156:159], v[196:199], v[44:47]
	v_mfma_f32_16x16x32_bf16 v[40:43], v[164:167], v[196:199], v[40:43]
	v_mfma_f32_16x16x32_bf16 v[28:31], v[156:159], v[208:211], v[28:31]
	v_mfma_f32_16x16x32_bf16 v[24:27], v[164:167], v[208:211], v[24:27]
	v_mfma_f32_16x16x32_bf16 v[12:15], v[156:159], v[216:219], v[12:15]
	v_mfma_f32_16x16x32_bf16 v[8:11], v[164:167], v[216:219], v[8:11]
	v_mfma_f32_16x16x32_bf16 v[52:55], v[168:171], v[184:187], v[52:55]
	v_mfma_f32_16x16x32_bf16 v[48:51], v[176:179], v[184:187], v[48:51]
	v_mfma_f32_16x16x32_bf16 v[36:39], v[168:171], v[192:195], v[36:39]
	v_mfma_f32_16x16x32_bf16 v[32:35], v[176:179], v[192:195], v[32:35]
	v_mfma_f32_16x16x32_bf16 v[20:23], v[168:171], v[200:203], v[20:23]
	v_mfma_f32_16x16x32_bf16 v[16:19], v[176:179], v[200:203], v[16:19]
	v_mfma_f32_16x16x32_bf16 v[4:7], v[168:171], v[212:215], v[4:7]
	v_mfma_f32_16x16x32_bf16 v[0:3], v[176:179], v[212:215], v[0:3]
	v_mfma_f32_16x16x32_bf16 v[52:55], v[172:175], v[188:191], v[52:55]
	v_mfma_f32_16x16x32_bf16 v[48:51], v[180:183], v[188:191], v[48:51]
	v_mfma_f32_16x16x32_bf16 v[36:39], v[172:175], v[196:199], v[36:39]
	v_mfma_f32_16x16x32_bf16 v[32:35], v[180:183], v[196:199], v[32:35]
	v_mfma_f32_16x16x32_bf16 v[20:23], v[172:175], v[208:211], v[20:23]
	v_mfma_f32_16x16x32_bf16 v[16:19], v[180:183], v[208:211], v[16:19]
	v_mfma_f32_16x16x32_bf16 v[4:7], v[172:175], v[216:219], v[4:7]
	v_mfma_f32_16x16x32_bf16 v[0:3], v[180:183], v[216:219], v[0:3]
	s_barrier
	s_mov_b32 m0, s25
	s_nop 0
	global_load_lds_dwordx4 v128, s[28:29]
	s_mov_b32 m0, s39
	s_nop 0
	global_load_lds_dwordx4 v132, s[28:29]
	s_add_i32 s54, 0, 0x18000
	v_add_u32_e32 v155, s54, v149
	s_add_i32 s55, 0, 0x1c000
	ds_read_b128 v[144:147], v155
	ds_read_b128 v[156:159], v155 offset:1024
	ds_read_b128 v[160:163], v155 offset:2048
	ds_read_b128 v[164:167], v155 offset:3072
	v_add_u32_e32 v155, s55, v149
	ds_read_b128 v[168:171], v155
	ds_read_b128 v[172:175], v155 offset:1024
	ds_read_b128 v[176:179], v155 offset:2048
	ds_read_b128 v[180:183], v155 offset:3072
	s_add_u32 s28, s28, 0x40000
	s_addc_u32 s29, s29, 0
	s_mov_b32 m0, s40
	ds_read_b128 v[184:187], v153 offset:32768
	ds_read_b128 v[188:191], v153 offset:33792
	ds_read_b128 v[192:195], v153 offset:34816
	ds_read_b128 v[196:199], v153 offset:35840
	ds_read_b128 v[200:203], v153 offset:36864
	ds_read_b128 v[208:211], v153 offset:37888
	ds_read_b128 v[212:215], v153 offset:38912
	ds_read_b128 v[216:219], v153 offset:39936
	global_load_lds_dwordx4 v128, s[28:29]
	s_mov_b32 m0, s41
	s_nop 0
	global_load_lds_dwordx4 v132, s[28:29]
	s_waitcnt vmcnt(8)
	s_waitcnt lgkmcnt(0)
	s_barrier
	s_waitcnt lgkmcnt(0)
	v_mfma_f32_16x16x32_bf16 v[124:127], v[144:147], v[184:187], v[124:127]
	v_mfma_f32_16x16x32_bf16 v[120:123], v[160:163], v[184:187], v[120:123]
	v_mfma_f32_16x16x32_bf16 v[108:111], v[144:147], v[192:195], v[108:111]
	v_mfma_f32_16x16x32_bf16 v[104:107], v[160:163], v[192:195], v[104:107]
	v_mfma_f32_16x16x32_bf16 v[92:95], v[144:147], v[200:203], v[92:95]
	v_mfma_f32_16x16x32_bf16 v[88:91], v[160:163], v[200:203], v[88:91]
	v_mfma_f32_16x16x32_bf16 v[76:79], v[144:147], v[212:215], v[76:79]
	v_mfma_f32_16x16x32_bf16 v[72:75], v[160:163], v[212:215], v[72:75]
	v_mfma_f32_16x16x32_bf16 v[124:127], v[156:159], v[188:191], v[124:127]
	v_mfma_f32_16x16x32_bf16 v[120:123], v[164:167], v[188:191], v[120:123]
	v_mfma_f32_16x16x32_bf16 v[108:111], v[156:159], v[196:199], v[108:111]
	v_mfma_f32_16x16x32_bf16 v[104:107], v[164:167], v[196:199], v[104:107]
	v_mfma_f32_16x16x32_bf16 v[92:95], v[156:159], v[208:211], v[92:95]
	v_mfma_f32_16x16x32_bf16 v[88:91], v[164:167], v[208:211], v[88:91]
	v_mfma_f32_16x16x32_bf16 v[76:79], v[156:159], v[216:219], v[76:79]
	v_mfma_f32_16x16x32_bf16 v[72:75], v[164:167], v[216:219], v[72:75]
	v_mfma_f32_16x16x32_bf16 v[116:119], v[168:171], v[184:187], v[116:119]
	v_mfma_f32_16x16x32_bf16 v[112:115], v[176:179], v[184:187], v[112:115]
	v_mfma_f32_16x16x32_bf16 v[100:103], v[168:171], v[192:195], v[100:103]
	v_mfma_f32_16x16x32_bf16 v[96:99], v[176:179], v[192:195], v[96:99]
	v_mfma_f32_16x16x32_bf16 v[84:87], v[168:171], v[200:203], v[84:87]
	v_mfma_f32_16x16x32_bf16 v[80:83], v[176:179], v[200:203], v[80:83]
	v_mfma_f32_16x16x32_bf16 v[68:71], v[168:171], v[212:215], v[68:71]
	v_mfma_f32_16x16x32_bf16 v[64:67], v[176:179], v[212:215], v[64:67]
	v_mfma_f32_16x16x32_bf16 v[116:119], v[172:175], v[188:191], v[116:119]
	v_mfma_f32_16x16x32_bf16 v[112:115], v[180:183], v[188:191], v[112:115]
	v_mfma_f32_16x16x32_bf16 v[100:103], v[172:175], v[196:199], v[100:103]
	v_mfma_f32_16x16x32_bf16 v[96:99], v[180:183], v[196:199], v[96:99]
	v_mfma_f32_16x16x32_bf16 v[84:87], v[172:175], v[208:211], v[84:87]
	v_mfma_f32_16x16x32_bf16 v[80:83], v[180:183], v[208:211], v[80:83]
	v_mfma_f32_16x16x32_bf16 v[68:71], v[172:175], v[216:219], v[68:71]
	v_mfma_f32_16x16x32_bf16 v[64:67], v[180:183], v[216:219], v[64:67]
	s_barrier
	s_add_i32 s28, s54, s38
	s_mov_b32 m0, s28
	ds_read_b128 v[184:187], v153 offset:49152
	ds_read_b128 v[188:191], v153 offset:50176
	ds_read_b128 v[192:195], v153 offset:51200
	ds_read_b128 v[196:199], v153 offset:52224
	ds_read_b128 v[200:203], v153 offset:53248
	ds_read_b128 v[208:211], v153 offset:54272
	ds_read_b128 v[212:215], v153 offset:55296
	ds_read_b128 v[216:219], v153 offset:56320
	global_load_lds_dwordx4 v205, s[26:27]
	s_add_i32 m0, s28, 0x2000
	s_add_u32 s26, s26, 0x40080
	s_addc_u32 s27, s27, 0
	s_add_i32 s28, s55, s38
	global_load_lds_dwordx4 v221, s[98:99]
	s_mov_b32 m0, s28
	s_nop 0
	global_load_lds_dwordx4 v130, s[26:27]
	s_add_i32 m0, s28, 0x2000
	s_nop 0
	global_load_lds_dwordx4 v134, s[26:27]
	s_mov_b32 m0, s43
	s_nop 0
	global_load_lds_dwordx4 v204, s[100:101]
	s_mov_b32 m0, s44
	s_nop 0
	global_load_lds_dwordx4 v220, s[100:101]
	s_waitcnt vmcnt(8)
	s_waitcnt lgkmcnt(0)
	s_barrier
	s_waitcnt lgkmcnt(0)
	v_mfma_f32_16x16x32_bf16 v[60:63], v[144:147], v[184:187], v[60:63]
	v_mfma_f32_16x16x32_bf16 v[56:59], v[160:163], v[184:187], v[56:59]
	v_mfma_f32_16x16x32_bf16 v[44:47], v[144:147], v[192:195], v[44:47]
	v_mfma_f32_16x16x32_bf16 v[40:43], v[160:163], v[192:195], v[40:43]
	v_mfma_f32_16x16x32_bf16 v[28:31], v[144:147], v[200:203], v[28:31]
	v_mfma_f32_16x16x32_bf16 v[24:27], v[160:163], v[200:203], v[24:27]
	v_mfma_f32_16x16x32_bf16 v[12:15], v[144:147], v[212:215], v[12:15]
	v_mfma_f32_16x16x32_bf16 v[8:11], v[160:163], v[212:215], v[8:11]
	v_mfma_f32_16x16x32_bf16 v[60:63], v[156:159], v[188:191], v[60:63]
	v_mfma_f32_16x16x32_bf16 v[56:59], v[164:167], v[188:191], v[56:59]
	v_mfma_f32_16x16x32_bf16 v[44:47], v[156:159], v[196:199], v[44:47]
	v_mfma_f32_16x16x32_bf16 v[40:43], v[164:167], v[196:199], v[40:43]
	v_mfma_f32_16x16x32_bf16 v[28:31], v[156:159], v[208:211], v[28:31]
	v_mfma_f32_16x16x32_bf16 v[24:27], v[164:167], v[208:211], v[24:27]
	v_mfma_f32_16x16x32_bf16 v[12:15], v[156:159], v[216:219], v[12:15]
	v_mfma_f32_16x16x32_bf16 v[8:11], v[164:167], v[216:219], v[8:11]
	v_mfma_f32_16x16x32_bf16 v[52:55], v[168:171], v[184:187], v[52:55]
	v_mfma_f32_16x16x32_bf16 v[48:51], v[176:179], v[184:187], v[48:51]
	v_mfma_f32_16x16x32_bf16 v[36:39], v[168:171], v[192:195], v[36:39]
	v_mfma_f32_16x16x32_bf16 v[32:35], v[176:179], v[192:195], v[32:35]
	v_mfma_f32_16x16x32_bf16 v[20:23], v[168:171], v[200:203], v[20:23]
	v_mfma_f32_16x16x32_bf16 v[16:19], v[176:179], v[200:203], v[16:19]
	v_mfma_f32_16x16x32_bf16 v[4:7], v[168:171], v[212:215], v[4:7]
	v_mfma_f32_16x16x32_bf16 v[0:3], v[176:179], v[212:215], v[0:3]
	v_mfma_f32_16x16x32_bf16 v[52:55], v[172:175], v[188:191], v[52:55]
	v_mfma_f32_16x16x32_bf16 v[48:51], v[180:183], v[188:191], v[48:51]
	v_mfma_f32_16x16x32_bf16 v[36:39], v[172:175], v[196:199], v[36:39]
	v_mfma_f32_16x16x32_bf16 v[32:35], v[180:183], v[196:199], v[32:35]
	v_mfma_f32_16x16x32_bf16 v[20:23], v[172:175], v[208:211], v[20:23]
	v_mfma_f32_16x16x32_bf16 v[16:19], v[180:183], v[208:211], v[16:19]
	v_mfma_f32_16x16x32_bf16 v[4:7], v[172:175], v[216:219], v[4:7]
	v_mfma_f32_16x16x32_bf16 v[0:3], v[180:183], v[216:219], v[0:3]
	s_barrier
	s_add_i32 s53, s53, 2
	s_add_u32 s51, s51, 0x100
	s_addc_u32 s52, s52, 0
	s_add_u32 s6, s6, 0x100
	s_addc_u32 s7, s7, 0
	s_cmp_gt_u32 s53, 13
	s_cbranch_scc0 .LBB0_988
	s_setprio 0
	s_and_b64 vcc, exec, s[14:15]
	s_cbranch_vccz .LBB0_991
	s_barrier

.LBB0_1193:
	ds_read_b128 v[144:147], v151
	ds_read_b128 v[154:157], v151 offset:1024
	ds_read_b128 v[158:161], v151 offset:2048
	ds_read_b128 v[162:165], v151 offset:3072
	ds_read_b128 v[166:169], v152
	ds_read_b128 v[170:173], v152 offset:1024
	ds_read_b128 v[174:177], v152 offset:2048
	ds_read_b128 v[178:181], v152 offset:3072
	s_add_u32 s26, s24, 0xfffe0080
	s_addc_u32 s27, s25, -1
	s_cmp_eq_u32 s50, 4
	s_cselect_b32 s29, s17, s27
	s_cselect_b32 s28, s46, s26
	s_cselect_b32 s27, s15, s49
	s_cselect_b32 s26, s47, s48
	s_add_i32 m0, s23, 0xc000
	ds_read_b128 v[182:185], v153
	ds_read_b128 v[186:189], v153 offset:1024
	ds_read_b128 v[190:193], v153 offset:2048
	ds_read_b128 v[194:197], v153 offset:3072
	ds_read_b128 v[198:201], v153 offset:4096
	ds_read_b128 v[202:205], v153 offset:5120
	ds_read_b128 v[208:211], v153 offset:6144
	ds_read_b128 v[212:215], v153 offset:7168
	global_load_lds_dwordx4 v138, s[24:25]
	s_add_i32 m0, s23, 0xe000
	s_nop 0
	global_load_lds_dwordx4 v136, s[24:25]
	s_waitcnt vmcnt(8)
	s_waitcnt lgkmcnt(0)
	s_barrier
	s_waitcnt lgkmcnt(0)
	v_mfma_f32_16x16x32_bf16 v[124:127], v[144:147], v[182:185], v[124:127]
	v_mfma_f32_16x16x32_bf16 v[120:123], v[158:161], v[182:185], v[120:123]
	v_mfma_f32_16x16x32_bf16 v[108:111], v[144:147], v[190:193], v[108:111]
	v_mfma_f32_16x16x32_bf16 v[104:107], v[158:161], v[190:193], v[104:107]
	v_mfma_f32_16x16x32_bf16 v[92:95], v[144:147], v[198:201], v[92:95]
	v_mfma_f32_16x16x32_bf16 v[88:91], v[158:161], v[198:201], v[88:91]
	v_mfma_f32_16x16x32_bf16 v[76:79], v[144:147], v[208:211], v[76:79]
	v_mfma_f32_16x16x32_bf16 v[72:75], v[158:161], v[208:211], v[72:75]
	v_mfma_f32_16x16x32_bf16 v[124:127], v[154:157], v[186:189], v[124:127]
	v_mfma_f32_16x16x32_bf16 v[120:123], v[162:165], v[186:189], v[120:123]
	v_mfma_f32_16x16x32_bf16 v[108:111], v[154:157], v[194:197], v[108:111]
	v_mfma_f32_16x16x32_bf16 v[104:107], v[162:165], v[194:197], v[104:107]
	v_mfma_f32_16x16x32_bf16 v[92:95], v[154:157], v[202:205], v[92:95]
	v_mfma_f32_16x16x32_bf16 v[88:91], v[162:165], v[202:205], v[88:91]
	v_mfma_f32_16x16x32_bf16 v[76:79], v[154:157], v[212:215], v[76:79]
	v_mfma_f32_16x16x32_bf16 v[72:75], v[162:165], v[212:215], v[72:75]
	v_mfma_f32_16x16x32_bf16 v[116:119], v[166:169], v[182:185], v[116:119]
	v_mfma_f32_16x16x32_bf16 v[112:115], v[174:177], v[182:185], v[112:115]
	v_mfma_f32_16x16x32_bf16 v[100:103], v[166:169], v[190:193], v[100:103]
	v_mfma_f32_16x16x32_bf16 v[96:99], v[174:177], v[190:193], v[96:99]
	v_mfma_f32_16x16x32_bf16 v[84:87], v[166:169], v[198:201], v[84:87]
	v_mfma_f32_16x16x32_bf16 v[80:83], v[174:177], v[198:201], v[80:83]
	v_mfma_f32_16x16x32_bf16 v[68:71], v[166:169], v[208:211], v[68:71]
	v_mfma_f32_16x16x32_bf16 v[64:67], v[174:177], v[208:211], v[64:67]
	v_mfma_f32_16x16x32_bf16 v[116:119], v[170:173], v[186:189], v[116:119]
	v_mfma_f32_16x16x32_bf16 v[112:115], v[178:181], v[186:189], v[112:115]
	v_mfma_f32_16x16x32_bf16 v[100:103], v[170:173], v[194:197], v[100:103]
	v_mfma_f32_16x16x32_bf16 v[96:99], v[178:181], v[194:197], v[96:99]
	v_mfma_f32_16x16x32_bf16 v[84:87], v[170:173], v[202:205], v[84:87]
	v_mfma_f32_16x16x32_bf16 v[80:83], v[178:181], v[202:205], v[80:83]
	v_mfma_f32_16x16x32_bf16 v[68:71], v[170:173], v[212:215], v[68:71]
	v_mfma_f32_16x16x32_bf16 v[64:67], v[178:181], v[212:215], v[64:67]
	s_barrier
	s_add_i32 s51, s43, s36
	s_mov_b32 m0, s51
	ds_read_b128 v[182:185], v153 offset:16384
	ds_read_b128 v[186:189], v153 offset:17408
	ds_read_b128 v[190:193], v153 offset:18432
	ds_read_b128 v[194:197], v153 offset:19456
	ds_read_b128 v[198:201], v153 offset:20480
	ds_read_b128 v[202:205], v153 offset:21504
	ds_read_b128 v[208:211], v153 offset:22528
	ds_read_b128 v[212:215], v153 offset:23552
	global_load_lds_dwordx4 v130, s[26:27]
	s_add_i32 m0, s51, 0x2000
	s_add_u32 s52, s26, 0x20000
	s_mov_b64 s[98:99], s[26:27]
	s_addc_u32 s53, s27, 0
	s_add_i32 s51, s44, s36
	global_load_lds_dwordx4 v134, s[26:27]
	s_mov_b32 m0, s51
	s_mov_b64 s[100:101], s[28:29]
	global_load_lds_dwordx4 v130, s[52:53]
	s_add_i32 m0, s51, 0x2000
	s_nop 0
	global_load_lds_dwordx4 v134, s[52:53]
	s_waitcnt vmcnt(6)
	s_waitcnt lgkmcnt(0)
	s_barrier
	s_waitcnt lgkmcnt(0)
	v_mfma_f32_16x16x32_bf16 v[60:63], v[144:147], v[182:185], v[60:63]
	v_mfma_f32_16x16x32_bf16 v[56:59], v[158:161], v[182:185], v[56:59]
	v_mfma_f32_16x16x32_bf16 v[44:47], v[144:147], v[190:193], v[44:47]
	v_mfma_f32_16x16x32_bf16 v[40:43], v[158:161], v[190:193], v[40:43]
	v_mfma_f32_16x16x32_bf16 v[28:31], v[144:147], v[198:201], v[28:31]
	v_mfma_f32_16x16x32_bf16 v[24:27], v[158:161], v[198:201], v[24:27]
	v_mfma_f32_16x16x32_bf16 v[12:15], v[144:147], v[208:211], v[12:15]
	v_mfma_f32_16x16x32_bf16 v[8:11], v[158:161], v[208:211], v[8:11]
	v_mfma_f32_16x16x32_bf16 v[60:63], v[154:157], v[186:189], v[60:63]
	v_mfma_f32_16x16x32_bf16 v[56:59], v[162:165], v[186:189], v[56:59]
	v_mfma_f32_16x16x32_bf16 v[44:47], v[154:157], v[194:197], v[44:47]
	v_mfma_f32_16x16x32_bf16 v[40:43], v[162:165], v[194:197], v[40:43]
	v_mfma_f32_16x16x32_bf16 v[28:31], v[154:157], v[202:205], v[28:31]
	v_mfma_f32_16x16x32_bf16 v[24:27], v[162:165], v[202:205], v[24:27]
	v_mfma_f32_16x16x32_bf16 v[12:15], v[154:157], v[212:215], v[12:15]
	v_mfma_f32_16x16x32_bf16 v[8:11], v[162:165], v[212:215], v[8:11]
	v_mfma_f32_16x16x32_bf16 v[52:55], v[166:169], v[182:185], v[52:55]
	v_mfma_f32_16x16x32_bf16 v[48:51], v[174:177], v[182:185], v[48:51]
	v_mfma_f32_16x16x32_bf16 v[36:39], v[166:169], v[190:193], v[36:39]
	v_mfma_f32_16x16x32_bf16 v[32:35], v[174:177], v[190:193], v[32:35]
	v_mfma_f32_16x16x32_bf16 v[20:23], v[166:169], v[198:201], v[20:23]
	v_mfma_f32_16x16x32_bf16 v[16:19], v[174:177], v[198:201], v[16:19]
	v_mfma_f32_16x16x32_bf16 v[4:7], v[166:169], v[208:211], v[4:7]
	v_mfma_f32_16x16x32_bf16 v[0:3], v[174:177], v[208:211], v[0:3]
	v_mfma_f32_16x16x32_bf16 v[52:55], v[170:173], v[186:189], v[52:55]
	v_mfma_f32_16x16x32_bf16 v[48:51], v[178:181], v[186:189], v[48:51]
	v_mfma_f32_16x16x32_bf16 v[36:39], v[170:173], v[194:197], v[36:39]
	v_mfma_f32_16x16x32_bf16 v[32:35], v[178:181], v[194:197], v[32:35]
	v_mfma_f32_16x16x32_bf16 v[20:23], v[170:173], v[202:205], v[20:23]
	v_mfma_f32_16x16x32_bf16 v[16:19], v[178:181], v[202:205], v[16:19]
	v_mfma_f32_16x16x32_bf16 v[4:7], v[170:173], v[212:215], v[4:7]
	v_mfma_f32_16x16x32_bf16 v[0:3], v[178:181], v[212:215], v[0:3]
	s_barrier
	s_mov_b32 m0, s23
	s_nop 0
	global_load_lds_dwordx4 v128, s[28:29]
	s_mov_b32 m0, s37
	s_nop 0
	global_load_lds_dwordx4 v132, s[28:29]
	s_add_i32 s51, 0, 0x18000
	s_add_i32 s52, 0, 0x1c000
	v_add_u32_e32 v162, s51, v149
	v_add_u32_e32 v178, s52, v149
	ds_read_b128 v[144:147], v162
	ds_read_b128 v[154:157], v162 offset:1024
	ds_read_b128 v[158:161], v162 offset:2048
	ds_read_b128 v[162:165], v162 offset:3072
	ds_read_b128 v[166:169], v178
	ds_read_b128 v[170:173], v178 offset:1024
	ds_read_b128 v[174:177], v178 offset:2048
	ds_read_b128 v[178:181], v178 offset:3072
	s_add_u32 s28, s28, 0x20000
	s_addc_u32 s29, s29, 0
	s_mov_b32 m0, s38
	ds_read_b128 v[182:185], v153 offset:32768
	ds_read_b128 v[186:189], v153 offset:33792
	ds_read_b128 v[190:193], v153 offset:34816
	ds_read_b128 v[194:197], v153 offset:35840
	ds_read_b128 v[198:201], v153 offset:36864
	ds_read_b128 v[202:205], v153 offset:37888
	ds_read_b128 v[208:211], v153 offset:38912
	ds_read_b128 v[212:215], v153 offset:39936
	global_load_lds_dwordx4 v128, s[28:29]
	s_mov_b32 m0, s39
	s_nop 0
	global_load_lds_dwordx4 v132, s[28:29]
	s_waitcnt vmcnt(8)
	s_waitcnt lgkmcnt(0)
	s_barrier
	s_waitcnt lgkmcnt(0)
	v_mfma_f32_16x16x32_bf16 v[124:127], v[144:147], v[182:185], v[124:127]
	v_mfma_f32_16x16x32_bf16 v[120:123], v[158:161], v[182:185], v[120:123]
	v_mfma_f32_16x16x32_bf16 v[108:111], v[144:147], v[190:193], v[108:111]
	v_mfma_f32_16x16x32_bf16 v[104:107], v[158:161], v[190:193], v[104:107]
	v_mfma_f32_16x16x32_bf16 v[92:95], v[144:147], v[198:201], v[92:95]
	v_mfma_f32_16x16x32_bf16 v[88:91], v[158:161], v[198:201], v[88:91]
	v_mfma_f32_16x16x32_bf16 v[76:79], v[144:147], v[208:211], v[76:79]
	v_mfma_f32_16x16x32_bf16 v[72:75], v[158:161], v[208:211], v[72:75]
	v_mfma_f32_16x16x32_bf16 v[124:127], v[154:157], v[186:189], v[124:127]
	v_mfma_f32_16x16x32_bf16 v[120:123], v[162:165], v[186:189], v[120:123]
	v_mfma_f32_16x16x32_bf16 v[108:111], v[154:157], v[194:197], v[108:111]
	v_mfma_f32_16x16x32_bf16 v[104:107], v[162:165], v[194:197], v[104:107]
	v_mfma_f32_16x16x32_bf16 v[92:95], v[154:157], v[202:205], v[92:95]
	v_mfma_f32_16x16x32_bf16 v[88:91], v[162:165], v[202:205], v[88:91]
	v_mfma_f32_16x16x32_bf16 v[76:79], v[154:157], v[212:215], v[76:79]
	v_mfma_f32_16x16x32_bf16 v[72:75], v[162:165], v[212:215], v[72:75]
	v_mfma_f32_16x16x32_bf16 v[116:119], v[166:169], v[182:185], v[116:119]
	v_mfma_f32_16x16x32_bf16 v[112:115], v[174:177], v[182:185], v[112:115]
	v_mfma_f32_16x16x32_bf16 v[100:103], v[166:169], v[190:193], v[100:103]
	v_mfma_f32_16x16x32_bf16 v[96:99], v[174:177], v[190:193], v[96:99]
	v_mfma_f32_16x16x32_bf16 v[84:87], v[166:169], v[198:201], v[84:87]
	v_mfma_f32_16x16x32_bf16 v[80:83], v[174:177], v[198:201], v[80:83]
	v_mfma_f32_16x16x32_bf16 v[68:71], v[166:169], v[208:211], v[68:71]
	v_mfma_f32_16x16x32_bf16 v[64:67], v[174:177], v[208:211], v[64:67]
	v_mfma_f32_16x16x32_bf16 v[116:119], v[170:173], v[186:189], v[116:119]
	v_mfma_f32_16x16x32_bf16 v[112:115], v[178:181], v[186:189], v[112:115]
	v_mfma_f32_16x16x32_bf16 v[100:103], v[170:173], v[194:197], v[100:103]
	v_mfma_f32_16x16x32_bf16 v[96:99], v[178:181], v[194:197], v[96:99]
	v_mfma_f32_16x16x32_bf16 v[84:87], v[170:173], v[202:205], v[84:87]
	v_mfma_f32_16x16x32_bf16 v[80:83], v[178:181], v[202:205], v[80:83]
	v_mfma_f32_16x16x32_bf16 v[68:71], v[170:173], v[212:215], v[68:71]
	v_mfma_f32_16x16x32_bf16 v[64:67], v[178:181], v[212:215], v[64:67]
	s_barrier
	s_add_i32 s28, s51, s36
	s_mov_b32 m0, s28
	ds_read_b128 v[182:185], v153 offset:49152
	ds_read_b128 v[186:189], v153 offset:50176
	ds_read_b128 v[190:193], v153 offset:51200
	ds_read_b128 v[194:197], v153 offset:52224
	ds_read_b128 v[198:201], v153 offset:53248
	ds_read_b128 v[202:205], v153 offset:54272
	ds_read_b128 v[208:211], v153 offset:55296
	ds_read_b128 v[212:215], v153 offset:56320
	global_load_lds_dwordx4 v217, s[26:27]
	s_add_i32 m0, s28, 0x2000
	s_add_u32 s26, s26, 0x20080
	s_addc_u32 s27, s27, 0
	s_add_i32 s28, s52, s36
	global_load_lds_dwordx4 v219, s[98:99]
	s_mov_b32 m0, s28
	s_nop 0
	global_load_lds_dwordx4 v130, s[26:27]
	s_add_i32 m0, s28, 0x2000
	s_nop 0
	global_load_lds_dwordx4 v134, s[26:27]
	s_mov_b32 m0, s41
	s_nop 0
	global_load_lds_dwordx4 v216, s[100:101]
	s_mov_b32 m0, s42
	s_nop 0
	global_load_lds_dwordx4 v218, s[100:101]
	s_waitcnt vmcnt(8)
	s_waitcnt lgkmcnt(0)
	s_barrier
	s_waitcnt lgkmcnt(0)
	v_mfma_f32_16x16x32_bf16 v[60:63], v[144:147], v[182:185], v[60:63]
	v_mfma_f32_16x16x32_bf16 v[56:59], v[158:161], v[182:185], v[56:59]
	v_mfma_f32_16x16x32_bf16 v[44:47], v[144:147], v[190:193], v[44:47]
	v_mfma_f32_16x16x32_bf16 v[40:43], v[158:161], v[190:193], v[40:43]
	v_mfma_f32_16x16x32_bf16 v[28:31], v[144:147], v[198:201], v[28:31]
	v_mfma_f32_16x16x32_bf16 v[24:27], v[158:161], v[198:201], v[24:27]
	v_mfma_f32_16x16x32_bf16 v[12:15], v[144:147], v[208:211], v[12:15]
	v_mfma_f32_16x16x32_bf16 v[8:11], v[158:161], v[208:211], v[8:11]
	v_mfma_f32_16x16x32_bf16 v[60:63], v[154:157], v[186:189], v[60:63]
	v_mfma_f32_16x16x32_bf16 v[56:59], v[162:165], v[186:189], v[56:59]
	v_mfma_f32_16x16x32_bf16 v[44:47], v[154:157], v[194:197], v[44:47]
	v_mfma_f32_16x16x32_bf16 v[40:43], v[162:165], v[194:197], v[40:43]
	v_mfma_f32_16x16x32_bf16 v[28:31], v[154:157], v[202:205], v[28:31]
	v_mfma_f32_16x16x32_bf16 v[24:27], v[162:165], v[202:205], v[24:27]
	v_mfma_f32_16x16x32_bf16 v[12:15], v[154:157], v[212:215], v[12:15]
	v_mfma_f32_16x16x32_bf16 v[8:11], v[162:165], v[212:215], v[8:11]
	v_mfma_f32_16x16x32_bf16 v[52:55], v[166:169], v[182:185], v[52:55]
	v_mfma_f32_16x16x32_bf16 v[48:51], v[174:177], v[182:185], v[48:51]
	v_mfma_f32_16x16x32_bf16 v[36:39], v[166:169], v[190:193], v[36:39]
	v_mfma_f32_16x16x32_bf16 v[32:35], v[174:177], v[190:193], v[32:35]
	v_mfma_f32_16x16x32_bf16 v[20:23], v[166:169], v[198:201], v[20:23]
	v_mfma_f32_16x16x32_bf16 v[16:19], v[174:177], v[198:201], v[16:19]
	v_mfma_f32_16x16x32_bf16 v[4:7], v[166:169], v[208:211], v[4:7]
	v_mfma_f32_16x16x32_bf16 v[0:3], v[174:177], v[208:211], v[0:3]
	v_mfma_f32_16x16x32_bf16 v[52:55], v[170:173], v[186:189], v[52:55]
	v_mfma_f32_16x16x32_bf16 v[48:51], v[178:181], v[186:189], v[48:51]
	v_mfma_f32_16x16x32_bf16 v[36:39], v[170:173], v[194:197], v[36:39]
	v_mfma_f32_16x16x32_bf16 v[32:35], v[178:181], v[194:197], v[32:35]
	v_mfma_f32_16x16x32_bf16 v[20:23], v[170:173], v[202:205], v[20:23]
	v_mfma_f32_16x16x32_bf16 v[16:19], v[178:181], v[202:205], v[16:19]
	v_mfma_f32_16x16x32_bf16 v[4:7], v[170:173], v[212:215], v[4:7]
	v_mfma_f32_16x16x32_bf16 v[0:3], v[178:181], v[212:215], v[0:3]
	s_barrier
	s_add_i32 s50, s50, 2
	s_add_u32 s48, s48, 0x100
	s_addc_u32 s49, s49, 0
	s_add_u32 s24, s24, 0x100
	s_addc_u32 s25, s25, 0
	s_cmp_gt_u32 s50, 5
	s_cbranch_scc0 .LBB0_1193
	s_setprio 0
	s_and_b64 vcc, exec, s[12:13]
	s_cbranch_vccz .LBB0_1196
	s_barrier

.LBB0_1365:
	ds_read_b128 v[144:147], v151
	ds_read_b128 v[156:159], v151 offset:1024
	ds_read_b128 v[160:163], v151 offset:2048
	ds_read_b128 v[164:167], v151 offset:3072
	ds_read_b128 v[168:171], v152
	ds_read_b128 v[172:175], v152 offset:1024
	ds_read_b128 v[176:179], v152 offset:2048
	ds_read_b128 v[180:183], v152 offset:3072
	s_add_u32 s26, s24, 0xfffc0080
	s_addc_u32 s27, s25, -1
	s_cmp_eq_u32 s53, 12
	s_cselect_b32 s29, s19, s27
	s_cselect_b32 s28, s49, s26
	s_cselect_b32 s27, s17, s52
	s_cselect_b32 s26, s50, s51
	s_add_i32 m0, s39, 0xc000
	ds_read_b128 v[184:187], v153
	ds_read_b128 v[188:191], v153 offset:1024
	ds_read_b128 v[192:195], v153 offset:2048
	ds_read_b128 v[196:199], v153 offset:3072
	ds_read_b128 v[200:203], v153 offset:4096
	ds_read_b128 v[208:211], v153 offset:5120
	ds_read_b128 v[212:215], v153 offset:6144
	ds_read_b128 v[216:219], v153 offset:7168
	global_load_lds_dwordx4 v138, s[24:25]
	s_add_i32 m0, s39, 0xe000
	s_nop 0
	global_load_lds_dwordx4 v136, s[24:25]
	s_waitcnt vmcnt(8)
	s_waitcnt lgkmcnt(0)
	s_barrier
	s_waitcnt lgkmcnt(0)
	v_mfma_f32_16x16x32_bf16 v[124:127], v[144:147], v[184:187], v[124:127]
	v_mfma_f32_16x16x32_bf16 v[120:123], v[160:163], v[184:187], v[120:123]
	v_mfma_f32_16x16x32_bf16 v[108:111], v[144:147], v[192:195], v[108:111]
	v_mfma_f32_16x16x32_bf16 v[104:107], v[160:163], v[192:195], v[104:107]
	v_mfma_f32_16x16x32_bf16 v[92:95], v[144:147], v[200:203], v[92:95]
	v_mfma_f32_16x16x32_bf16 v[88:91], v[160:163], v[200:203], v[88:91]
	v_mfma_f32_16x16x32_bf16 v[76:79], v[144:147], v[212:215], v[76:79]
	v_mfma_f32_16x16x32_bf16 v[72:75], v[160:163], v[212:215], v[72:75]
	v_mfma_f32_16x16x32_bf16 v[124:127], v[156:159], v[188:191], v[124:127]
	v_mfma_f32_16x16x32_bf16 v[120:123], v[164:167], v[188:191], v[120:123]
	v_mfma_f32_16x16x32_bf16 v[108:111], v[156:159], v[196:199], v[108:111]
	v_mfma_f32_16x16x32_bf16 v[104:107], v[164:167], v[196:199], v[104:107]
	v_mfma_f32_16x16x32_bf16 v[92:95], v[156:159], v[208:211], v[92:95]
	v_mfma_f32_16x16x32_bf16 v[88:91], v[164:167], v[208:211], v[88:91]
	v_mfma_f32_16x16x32_bf16 v[76:79], v[156:159], v[216:219], v[76:79]
	v_mfma_f32_16x16x32_bf16 v[72:75], v[164:167], v[216:219], v[72:75]
	v_mfma_f32_16x16x32_bf16 v[116:119], v[168:171], v[184:187], v[116:119]
	v_mfma_f32_16x16x32_bf16 v[112:115], v[176:179], v[184:187], v[112:115]
	v_mfma_f32_16x16x32_bf16 v[100:103], v[168:171], v[192:195], v[100:103]
	v_mfma_f32_16x16x32_bf16 v[96:99], v[176:179], v[192:195], v[96:99]
	v_mfma_f32_16x16x32_bf16 v[84:87], v[168:171], v[200:203], v[84:87]
	v_mfma_f32_16x16x32_bf16 v[80:83], v[176:179], v[200:203], v[80:83]
	v_mfma_f32_16x16x32_bf16 v[68:71], v[168:171], v[212:215], v[68:71]
	v_mfma_f32_16x16x32_bf16 v[64:67], v[176:179], v[212:215], v[64:67]
	v_mfma_f32_16x16x32_bf16 v[116:119], v[172:175], v[188:191], v[116:119]
	v_mfma_f32_16x16x32_bf16 v[112:115], v[180:183], v[188:191], v[112:115]
	v_mfma_f32_16x16x32_bf16 v[100:103], v[172:175], v[196:199], v[100:103]
	v_mfma_f32_16x16x32_bf16 v[96:99], v[180:183], v[196:199], v[96:99]
	v_mfma_f32_16x16x32_bf16 v[84:87], v[172:175], v[208:211], v[84:87]
	v_mfma_f32_16x16x32_bf16 v[80:83], v[180:183], v[208:211], v[80:83]
	v_mfma_f32_16x16x32_bf16 v[68:71], v[172:175], v[216:219], v[68:71]
	v_mfma_f32_16x16x32_bf16 v[64:67], v[180:183], v[216:219], v[64:67]
	s_barrier
	s_add_i32 s54, s46, s38
	s_mov_b32 m0, s54
	ds_read_b128 v[184:187], v153 offset:16384
	ds_read_b128 v[188:191], v153 offset:17408
	ds_read_b128 v[192:195], v153 offset:18432
	ds_read_b128 v[196:199], v153 offset:19456
	ds_read_b128 v[200:203], v153 offset:20480
	ds_read_b128 v[208:211], v153 offset:21504
	ds_read_b128 v[212:215], v153 offset:22528
	ds_read_b128 v[216:219], v153 offset:23552
	global_load_lds_dwordx4 v130, s[26:27]
	s_add_i32 m0, s54, 0x2000
	s_add_u32 s54, s26, 0x40000
	s_mov_b64 s[98:99], s[26:27]
	s_addc_u32 s55, s27, 0
	s_add_i32 s56, s47, s38
	global_load_lds_dwordx4 v134, s[26:27]
	s_mov_b32 m0, s56
	s_mov_b64 s[100:101], s[28:29]
	global_load_lds_dwordx4 v130, s[54:55]
	s_add_i32 m0, s56, 0x2000
	s_nop 0
	global_load_lds_dwordx4 v134, s[54:55]
	s_waitcnt vmcnt(6)
	s_waitcnt lgkmcnt(0)
	s_barrier
	s_waitcnt lgkmcnt(0)
	v_mfma_f32_16x16x32_bf16 v[60:63], v[144:147], v[184:187], v[60:63]
	v_mfma_f32_16x16x32_bf16 v[56:59], v[160:163], v[184:187], v[56:59]
	v_mfma_f32_16x16x32_bf16 v[44:47], v[144:147], v[192:195], v[44:47]
	v_mfma_f32_16x16x32_bf16 v[40:43], v[160:163], v[192:195], v[40:43]
	v_mfma_f32_16x16x32_bf16 v[28:31], v[144:147], v[200:203], v[28:31]
	v_mfma_f32_16x16x32_bf16 v[24:27], v[160:163], v[200:203], v[24:27]
	v_mfma_f32_16x16x32_bf16 v[12:15], v[144:147], v[212:215], v[12:15]
	v_mfma_f32_16x16x32_bf16 v[8:11], v[160:163], v[212:215], v[8:11]
	v_mfma_f32_16x16x32_bf16 v[60:63], v[156:159], v[188:191], v[60:63]
	v_mfma_f32_16x16x32_bf16 v[56:59], v[164:167], v[188:191], v[56:59]
	v_mfma_f32_16x16x32_bf16 v[44:47], v[156:159], v[196:199], v[44:47]
	v_mfma_f32_16x16x32_bf16 v[40:43], v[164:167], v[196:199], v[40:43]
	v_mfma_f32_16x16x32_bf16 v[28:31], v[156:159], v[208:211], v[28:31]
	v_mfma_f32_16x16x32_bf16 v[24:27], v[164:167], v[208:211], v[24:27]
	v_mfma_f32_16x16x32_bf16 v[12:15], v[156:159], v[216:219], v[12:15]
	v_mfma_f32_16x16x32_bf16 v[8:11], v[164:167], v[216:219], v[8:11]
	v_mfma_f32_16x16x32_bf16 v[52:55], v[168:171], v[184:187], v[52:55]
	v_mfma_f32_16x16x32_bf16 v[48:51], v[176:179], v[184:187], v[48:51]
	v_mfma_f32_16x16x32_bf16 v[36:39], v[168:171], v[192:195], v[36:39]
	v_mfma_f32_16x16x32_bf16 v[32:35], v[176:179], v[192:195], v[32:35]
	v_mfma_f32_16x16x32_bf16 v[20:23], v[168:171], v[200:203], v[20:23]
	v_mfma_f32_16x16x32_bf16 v[16:19], v[176:179], v[200:203], v[16:19]
	v_mfma_f32_16x16x32_bf16 v[4:7], v[168:171], v[212:215], v[4:7]
	v_mfma_f32_16x16x32_bf16 v[0:3], v[176:179], v[212:215], v[0:3]
	v_mfma_f32_16x16x32_bf16 v[52:55], v[172:175], v[188:191], v[52:55]
	v_mfma_f32_16x16x32_bf16 v[48:51], v[180:183], v[188:191], v[48:51]
	v_mfma_f32_16x16x32_bf16 v[36:39], v[172:175], v[196:199], v[36:39]
	v_mfma_f32_16x16x32_bf16 v[32:35], v[180:183], v[196:199], v[32:35]
	v_mfma_f32_16x16x32_bf16 v[20:23], v[172:175], v[208:211], v[20:23]
	v_mfma_f32_16x16x32_bf16 v[16:19], v[180:183], v[208:211], v[16:19]
	v_mfma_f32_16x16x32_bf16 v[4:7], v[172:175], v[216:219], v[4:7]
	v_mfma_f32_16x16x32_bf16 v[0:3], v[180:183], v[216:219], v[0:3]
	s_barrier
	s_mov_b32 m0, s39
	s_nop 0
	global_load_lds_dwordx4 v128, s[28:29]
	s_mov_b32 m0, s40
	s_nop 0
	global_load_lds_dwordx4 v132, s[28:29]
	s_add_i32 s54, 0, 0x18000
	v_add_u32_e32 v155, s54, v149
	s_add_i32 s55, 0, 0x1c000
	ds_read_b128 v[144:147], v155
	ds_read_b128 v[156:159], v155 offset:1024
	ds_read_b128 v[160:163], v155 offset:2048
	ds_read_b128 v[164:167], v155 offset:3072
	v_add_u32_e32 v155, s55, v149
	ds_read_b128 v[168:171], v155
	ds_read_b128 v[172:175], v155 offset:1024
	ds_read_b128 v[176:179], v155 offset:2048
	ds_read_b128 v[180:183], v155 offset:3072
	s_add_u32 s28, s28, 0x40000
	s_addc_u32 s29, s29, 0
	s_mov_b32 m0, s41
	ds_read_b128 v[184:187], v153 offset:32768
	ds_read_b128 v[188:191], v153 offset:33792
	ds_read_b128 v[192:195], v153 offset:34816
	ds_read_b128 v[196:199], v153 offset:35840
	ds_read_b128 v[200:203], v153 offset:36864
	ds_read_b128 v[208:211], v153 offset:37888
	ds_read_b128 v[212:215], v153 offset:38912
	ds_read_b128 v[216:219], v153 offset:39936
	global_load_lds_dwordx4 v128, s[28:29]
	s_mov_b32 m0, s42
	s_nop 0
	global_load_lds_dwordx4 v132, s[28:29]
	s_waitcnt vmcnt(8)
	s_waitcnt lgkmcnt(0)
	s_barrier
	s_waitcnt lgkmcnt(0)
	v_mfma_f32_16x16x32_bf16 v[124:127], v[144:147], v[184:187], v[124:127]
	v_mfma_f32_16x16x32_bf16 v[120:123], v[160:163], v[184:187], v[120:123]
	v_mfma_f32_16x16x32_bf16 v[108:111], v[144:147], v[192:195], v[108:111]
	v_mfma_f32_16x16x32_bf16 v[104:107], v[160:163], v[192:195], v[104:107]
	v_mfma_f32_16x16x32_bf16 v[92:95], v[144:147], v[200:203], v[92:95]
	v_mfma_f32_16x16x32_bf16 v[88:91], v[160:163], v[200:203], v[88:91]
	v_mfma_f32_16x16x32_bf16 v[76:79], v[144:147], v[212:215], v[76:79]
	v_mfma_f32_16x16x32_bf16 v[72:75], v[160:163], v[212:215], v[72:75]
	v_mfma_f32_16x16x32_bf16 v[124:127], v[156:159], v[188:191], v[124:127]
	v_mfma_f32_16x16x32_bf16 v[120:123], v[164:167], v[188:191], v[120:123]
	v_mfma_f32_16x16x32_bf16 v[108:111], v[156:159], v[196:199], v[108:111]
	v_mfma_f32_16x16x32_bf16 v[104:107], v[164:167], v[196:199], v[104:107]
	v_mfma_f32_16x16x32_bf16 v[92:95], v[156:159], v[208:211], v[92:95]
	v_mfma_f32_16x16x32_bf16 v[88:91], v[164:167], v[208:211], v[88:91]
	v_mfma_f32_16x16x32_bf16 v[76:79], v[156:159], v[216:219], v[76:79]
	v_mfma_f32_16x16x32_bf16 v[72:75], v[164:167], v[216:219], v[72:75]
	v_mfma_f32_16x16x32_bf16 v[116:119], v[168:171], v[184:187], v[116:119]
	v_mfma_f32_16x16x32_bf16 v[112:115], v[176:179], v[184:187], v[112:115]
	v_mfma_f32_16x16x32_bf16 v[100:103], v[168:171], v[192:195], v[100:103]
	v_mfma_f32_16x16x32_bf16 v[96:99], v[176:179], v[192:195], v[96:99]
	v_mfma_f32_16x16x32_bf16 v[84:87], v[168:171], v[200:203], v[84:87]
	v_mfma_f32_16x16x32_bf16 v[80:83], v[176:179], v[200:203], v[80:83]
	v_mfma_f32_16x16x32_bf16 v[68:71], v[168:171], v[212:215], v[68:71]
	v_mfma_f32_16x16x32_bf16 v[64:67], v[176:179], v[212:215], v[64:67]
	v_mfma_f32_16x16x32_bf16 v[116:119], v[172:175], v[188:191], v[116:119]
	v_mfma_f32_16x16x32_bf16 v[112:115], v[180:183], v[188:191], v[112:115]
	v_mfma_f32_16x16x32_bf16 v[100:103], v[172:175], v[196:199], v[100:103]
	v_mfma_f32_16x16x32_bf16 v[96:99], v[180:183], v[196:199], v[96:99]
	v_mfma_f32_16x16x32_bf16 v[84:87], v[172:175], v[208:211], v[84:87]
	v_mfma_f32_16x16x32_bf16 v[80:83], v[180:183], v[208:211], v[80:83]
	v_mfma_f32_16x16x32_bf16 v[68:71], v[172:175], v[216:219], v[68:71]
	v_mfma_f32_16x16x32_bf16 v[64:67], v[180:183], v[216:219], v[64:67]
	s_barrier
	s_add_i32 s28, s54, s38
	s_mov_b32 m0, s28
	ds_read_b128 v[184:187], v153 offset:49152
	ds_read_b128 v[188:191], v153 offset:50176
	ds_read_b128 v[192:195], v153 offset:51200
	ds_read_b128 v[196:199], v153 offset:52224
	ds_read_b128 v[200:203], v153 offset:53248
	ds_read_b128 v[208:211], v153 offset:54272
	ds_read_b128 v[212:215], v153 offset:55296
	ds_read_b128 v[216:219], v153 offset:56320
	global_load_lds_dwordx4 v205, s[26:27]
	s_add_i32 m0, s28, 0x2000
	s_add_u32 s26, s26, 0x40080
	s_addc_u32 s27, s27, 0
	s_add_i32 s28, s55, s38
	global_load_lds_dwordx4 v221, s[98:99]
	s_mov_b32 m0, s28
	s_nop 0
	global_load_lds_dwordx4 v130, s[26:27]
	s_add_i32 m0, s28, 0x2000
	s_nop 0
	global_load_lds_dwordx4 v134, s[26:27]
	s_mov_b32 m0, s44
	s_nop 0
	global_load_lds_dwordx4 v204, s[100:101]
	s_mov_b32 m0, s45
	s_nop 0
	global_load_lds_dwordx4 v220, s[100:101]
	s_waitcnt vmcnt(8)
	s_waitcnt lgkmcnt(0)
	s_barrier
	s_waitcnt lgkmcnt(0)
	v_mfma_f32_16x16x32_bf16 v[60:63], v[144:147], v[184:187], v[60:63]
	v_mfma_f32_16x16x32_bf16 v[56:59], v[160:163], v[184:187], v[56:59]
	v_mfma_f32_16x16x32_bf16 v[44:47], v[144:147], v[192:195], v[44:47]
	v_mfma_f32_16x16x32_bf16 v[40:43], v[160:163], v[192:195], v[40:43]
	v_mfma_f32_16x16x32_bf16 v[28:31], v[144:147], v[200:203], v[28:31]
	v_mfma_f32_16x16x32_bf16 v[24:27], v[160:163], v[200:203], v[24:27]
	v_mfma_f32_16x16x32_bf16 v[12:15], v[144:147], v[212:215], v[12:15]
	v_mfma_f32_16x16x32_bf16 v[8:11], v[160:163], v[212:215], v[8:11]
	v_mfma_f32_16x16x32_bf16 v[60:63], v[156:159], v[188:191], v[60:63]
	v_mfma_f32_16x16x32_bf16 v[56:59], v[164:167], v[188:191], v[56:59]
	v_mfma_f32_16x16x32_bf16 v[44:47], v[156:159], v[196:199], v[44:47]
	v_mfma_f32_16x16x32_bf16 v[40:43], v[164:167], v[196:199], v[40:43]
	v_mfma_f32_16x16x32_bf16 v[28:31], v[156:159], v[208:211], v[28:31]
	v_mfma_f32_16x16x32_bf16 v[24:27], v[164:167], v[208:211], v[24:27]
	v_mfma_f32_16x16x32_bf16 v[12:15], v[156:159], v[216:219], v[12:15]
	v_mfma_f32_16x16x32_bf16 v[8:11], v[164:167], v[216:219], v[8:11]
	v_mfma_f32_16x16x32_bf16 v[52:55], v[168:171], v[184:187], v[52:55]
	v_mfma_f32_16x16x32_bf16 v[48:51], v[176:179], v[184:187], v[48:51]
	v_mfma_f32_16x16x32_bf16 v[36:39], v[168:171], v[192:195], v[36:39]
	v_mfma_f32_16x16x32_bf16 v[32:35], v[176:179], v[192:195], v[32:35]
	v_mfma_f32_16x16x32_bf16 v[20:23], v[168:171], v[200:203], v[20:23]
	v_mfma_f32_16x16x32_bf16 v[16:19], v[176:179], v[200:203], v[16:19]
	v_mfma_f32_16x16x32_bf16 v[4:7], v[168:171], v[212:215], v[4:7]
	v_mfma_f32_16x16x32_bf16 v[0:3], v[176:179], v[212:215], v[0:3]
	v_mfma_f32_16x16x32_bf16 v[52:55], v[172:175], v[188:191], v[52:55]
	v_mfma_f32_16x16x32_bf16 v[48:51], v[180:183], v[188:191], v[48:51]
	v_mfma_f32_16x16x32_bf16 v[36:39], v[172:175], v[196:199], v[36:39]
	v_mfma_f32_16x16x32_bf16 v[32:35], v[180:183], v[196:199], v[32:35]
	v_mfma_f32_16x16x32_bf16 v[20:23], v[172:175], v[208:211], v[20:23]
	v_mfma_f32_16x16x32_bf16 v[16:19], v[180:183], v[208:211], v[16:19]
	v_mfma_f32_16x16x32_bf16 v[4:7], v[172:175], v[216:219], v[4:7]
	v_mfma_f32_16x16x32_bf16 v[0:3], v[180:183], v[216:219], v[0:3]
	s_barrier
	s_add_i32 s53, s53, 2
	s_add_u32 s51, s51, 0x100
	s_addc_u32 s52, s52, 0
	s_add_u32 s24, s24, 0x100
	s_addc_u32 s25, s25, 0
	s_cmp_gt_u32 s53, 13
	s_cbranch_scc0 .LBB0_1365
	s_setprio 0
	s_and_b64 vcc, exec, s[14:15]
	s_cbranch_vccz .LBB0_1368
	s_barrier

.LBB0_1561:
	ds_read_b128 v[140:143], v151
	ds_read_b128 v[144:147], v151 offset:1024
	ds_read_b128 v[156:159], v151 offset:2048
	ds_read_b128 v[160:163], v151 offset:3072
	ds_read_b128 v[164:167], v152
	ds_read_b128 v[168:171], v152 offset:1024
	ds_read_b128 v[172:175], v152 offset:2048
	ds_read_b128 v[176:179], v152 offset:3072
	s_add_u32 s38, s36, 0xfffc0080
	s_addc_u32 s39, s37, -1
	s_cmp_eq_u32 s61, 12
	s_cselect_b32 s41, s3, s39
	s_cselect_b32 s40, s29, s38
	s_cselect_b32 s39, s27, s60
	s_cselect_b32 s38, s58, s59
	s_add_i32 m0, s46, 0xc000
	ds_read_b128 v[180:183], v153
	ds_read_b128 v[184:187], v153 offset:1024
	ds_read_b128 v[188:191], v153 offset:2048
	ds_read_b128 v[192:195], v153 offset:3072
	ds_read_b128 v[196:199], v153 offset:4096
	ds_read_b128 v[200:203], v153 offset:5120
	ds_read_b128 v[208:211], v153 offset:6144
	ds_read_b128 v[212:215], v153 offset:7168
	global_load_lds_dwordx4 v134, s[36:37]
	s_add_i32 m0, s46, 0xe000
	s_nop 0
	global_load_lds_dwordx4 v132, s[36:37]
	s_waitcnt vmcnt(8)
	s_waitcnt lgkmcnt(0)
	s_barrier
	s_waitcnt lgkmcnt(0)
	v_mfma_f32_16x16x32_bf16 v[124:127], v[140:143], v[180:183], v[124:127]
	v_mfma_f32_16x16x32_bf16 v[120:123], v[156:159], v[180:183], v[120:123]
	v_mfma_f32_16x16x32_bf16 v[108:111], v[140:143], v[188:191], v[108:111]
	v_mfma_f32_16x16x32_bf16 v[104:107], v[156:159], v[188:191], v[104:107]
	v_mfma_f32_16x16x32_bf16 v[92:95], v[140:143], v[196:199], v[92:95]
	v_mfma_f32_16x16x32_bf16 v[88:91], v[156:159], v[196:199], v[88:91]
	v_mfma_f32_16x16x32_bf16 v[76:79], v[140:143], v[208:211], v[76:79]
	v_mfma_f32_16x16x32_bf16 v[72:75], v[156:159], v[208:211], v[72:75]
	v_mfma_f32_16x16x32_bf16 v[124:127], v[144:147], v[184:187], v[124:127]
	v_mfma_f32_16x16x32_bf16 v[120:123], v[160:163], v[184:187], v[120:123]
	v_mfma_f32_16x16x32_bf16 v[108:111], v[144:147], v[192:195], v[108:111]
	v_mfma_f32_16x16x32_bf16 v[104:107], v[160:163], v[192:195], v[104:107]
	v_mfma_f32_16x16x32_bf16 v[92:95], v[144:147], v[200:203], v[92:95]
	v_mfma_f32_16x16x32_bf16 v[88:91], v[160:163], v[200:203], v[88:91]
	v_mfma_f32_16x16x32_bf16 v[76:79], v[144:147], v[212:215], v[76:79]
	v_mfma_f32_16x16x32_bf16 v[72:75], v[160:163], v[212:215], v[72:75]
	v_mfma_f32_16x16x32_bf16 v[116:119], v[164:167], v[180:183], v[116:119]
	v_mfma_f32_16x16x32_bf16 v[112:115], v[172:175], v[180:183], v[112:115]
	v_mfma_f32_16x16x32_bf16 v[100:103], v[164:167], v[188:191], v[100:103]
	v_mfma_f32_16x16x32_bf16 v[96:99], v[172:175], v[188:191], v[96:99]
	v_mfma_f32_16x16x32_bf16 v[84:87], v[164:167], v[196:199], v[84:87]
	v_mfma_f32_16x16x32_bf16 v[80:83], v[172:175], v[196:199], v[80:83]
	v_mfma_f32_16x16x32_bf16 v[68:71], v[164:167], v[208:211], v[68:71]
	v_mfma_f32_16x16x32_bf16 v[64:67], v[172:175], v[208:211], v[64:67]
	v_mfma_f32_16x16x32_bf16 v[116:119], v[168:171], v[184:187], v[116:119]
	v_mfma_f32_16x16x32_bf16 v[112:115], v[176:179], v[184:187], v[112:115]
	v_mfma_f32_16x16x32_bf16 v[100:103], v[168:171], v[192:195], v[100:103]
	v_mfma_f32_16x16x32_bf16 v[96:99], v[176:179], v[192:195], v[96:99]
	v_mfma_f32_16x16x32_bf16 v[84:87], v[168:171], v[200:203], v[84:87]
	v_mfma_f32_16x16x32_bf16 v[80:83], v[176:179], v[200:203], v[80:83]
	v_mfma_f32_16x16x32_bf16 v[68:71], v[168:171], v[212:215], v[68:71]
	v_mfma_f32_16x16x32_bf16 v[64:67], v[176:179], v[212:215], v[64:67]
	s_barrier
	s_add_i32 s62, s54, s45
	s_mov_b32 m0, s62
	ds_read_b128 v[180:183], v153 offset:16384
	ds_read_b128 v[184:187], v153 offset:17408
	ds_read_b128 v[188:191], v153 offset:18432
	ds_read_b128 v[192:195], v153 offset:19456
	ds_read_b128 v[196:199], v153 offset:20480
	ds_read_b128 v[200:203], v153 offset:21504
	ds_read_b128 v[208:211], v153 offset:22528
	ds_read_b128 v[212:215], v153 offset:23552
	global_load_lds_dwordx4 v128, s[38:39]
	s_add_i32 m0, s62, 0x2000
	s_add_u32 s62, s38, 0x40000
	s_mov_b64 s[98:99], s[38:39]
	s_addc_u32 s63, s39, 0
	s_add_i32 s64, s55, s45
	global_load_lds_dwordx4 v130, s[38:39]
	s_mov_b32 m0, s64
	s_mov_b64 s[100:101], s[40:41]
	global_load_lds_dwordx4 v128, s[62:63]
	s_add_i32 m0, s64, 0x2000
	s_nop 0
	global_load_lds_dwordx4 v130, s[62:63]
	s_waitcnt vmcnt(6)
	s_waitcnt lgkmcnt(0)
	s_barrier
	s_waitcnt lgkmcnt(0)
	v_mfma_f32_16x16x32_bf16 v[60:63], v[140:143], v[180:183], v[60:63]
	v_mfma_f32_16x16x32_bf16 v[56:59], v[156:159], v[180:183], v[56:59]
	v_mfma_f32_16x16x32_bf16 v[44:47], v[140:143], v[188:191], v[44:47]
	v_mfma_f32_16x16x32_bf16 v[40:43], v[156:159], v[188:191], v[40:43]
	v_mfma_f32_16x16x32_bf16 v[28:31], v[140:143], v[196:199], v[28:31]
	v_mfma_f32_16x16x32_bf16 v[24:27], v[156:159], v[196:199], v[24:27]
	v_mfma_f32_16x16x32_bf16 v[12:15], v[140:143], v[208:211], v[12:15]
	v_mfma_f32_16x16x32_bf16 v[8:11], v[156:159], v[208:211], v[8:11]
	v_mfma_f32_16x16x32_bf16 v[60:63], v[144:147], v[184:187], v[60:63]
	v_mfma_f32_16x16x32_bf16 v[56:59], v[160:163], v[184:187], v[56:59]
	v_mfma_f32_16x16x32_bf16 v[44:47], v[144:147], v[192:195], v[44:47]
	v_mfma_f32_16x16x32_bf16 v[40:43], v[160:163], v[192:195], v[40:43]
	v_mfma_f32_16x16x32_bf16 v[28:31], v[144:147], v[200:203], v[28:31]
	v_mfma_f32_16x16x32_bf16 v[24:27], v[160:163], v[200:203], v[24:27]
	v_mfma_f32_16x16x32_bf16 v[12:15], v[144:147], v[212:215], v[12:15]
	v_mfma_f32_16x16x32_bf16 v[8:11], v[160:163], v[212:215], v[8:11]
	v_mfma_f32_16x16x32_bf16 v[52:55], v[164:167], v[180:183], v[52:55]
	v_mfma_f32_16x16x32_bf16 v[48:51], v[172:175], v[180:183], v[48:51]
	v_mfma_f32_16x16x32_bf16 v[36:39], v[164:167], v[188:191], v[36:39]
	v_mfma_f32_16x16x32_bf16 v[32:35], v[172:175], v[188:191], v[32:35]
	v_mfma_f32_16x16x32_bf16 v[20:23], v[164:167], v[196:199], v[20:23]
	v_mfma_f32_16x16x32_bf16 v[16:19], v[172:175], v[196:199], v[16:19]
	v_mfma_f32_16x16x32_bf16 v[4:7], v[164:167], v[208:211], v[4:7]
	v_mfma_f32_16x16x32_bf16 v[0:3], v[172:175], v[208:211], v[0:3]
	v_mfma_f32_16x16x32_bf16 v[52:55], v[168:171], v[184:187], v[52:55]
	v_mfma_f32_16x16x32_bf16 v[48:51], v[176:179], v[184:187], v[48:51]
	v_mfma_f32_16x16x32_bf16 v[36:39], v[168:171], v[192:195], v[36:39]
	v_mfma_f32_16x16x32_bf16 v[32:35], v[176:179], v[192:195], v[32:35]
	v_mfma_f32_16x16x32_bf16 v[20:23], v[168:171], v[200:203], v[20:23]
	v_mfma_f32_16x16x32_bf16 v[16:19], v[176:179], v[200:203], v[16:19]
	v_mfma_f32_16x16x32_bf16 v[4:7], v[168:171], v[212:215], v[4:7]
	v_mfma_f32_16x16x32_bf16 v[0:3], v[176:179], v[212:215], v[0:3]
	s_barrier
	s_mov_b32 m0, s46
	s_nop 0
	global_load_lds_dwordx4 v128, s[40:41]
	s_mov_b32 m0, s47
	s_nop 0
	global_load_lds_dwordx4 v130, s[40:41]
	s_add_i32 s62, 0, 0x18000
	v_add_u32_e32 v155, s62, v149
	s_add_i32 s63, 0, 0x1c000
	ds_read_b128 v[140:143], v155
	ds_read_b128 v[144:147], v155 offset:1024
	ds_read_b128 v[156:159], v155 offset:2048
	ds_read_b128 v[160:163], v155 offset:3072
	v_add_u32_e32 v155, s63, v149
	ds_read_b128 v[164:167], v155
	ds_read_b128 v[168:171], v155 offset:1024
	ds_read_b128 v[172:175], v155 offset:2048
	ds_read_b128 v[176:179], v155 offset:3072
	s_add_u32 s40, s40, 0x40000
	s_addc_u32 s41, s41, 0
	s_mov_b32 m0, s48
	ds_read_b128 v[180:183], v153 offset:32768
	ds_read_b128 v[184:187], v153 offset:33792
	ds_read_b128 v[188:191], v153 offset:34816
	ds_read_b128 v[192:195], v153 offset:35840
	ds_read_b128 v[196:199], v153 offset:36864
	ds_read_b128 v[200:203], v153 offset:37888
	ds_read_b128 v[208:211], v153 offset:38912
	ds_read_b128 v[212:215], v153 offset:39936
	global_load_lds_dwordx4 v128, s[40:41]
	s_mov_b32 m0, s49
	s_nop 0
	global_load_lds_dwordx4 v130, s[40:41]
	s_waitcnt vmcnt(8)
	s_waitcnt lgkmcnt(0)
	s_barrier
	s_waitcnt lgkmcnt(0)
	v_mfma_f32_16x16x32_bf16 v[124:127], v[140:143], v[180:183], v[124:127]
	v_mfma_f32_16x16x32_bf16 v[120:123], v[156:159], v[180:183], v[120:123]
	v_mfma_f32_16x16x32_bf16 v[108:111], v[140:143], v[188:191], v[108:111]
	v_mfma_f32_16x16x32_bf16 v[104:107], v[156:159], v[188:191], v[104:107]
	v_mfma_f32_16x16x32_bf16 v[92:95], v[140:143], v[196:199], v[92:95]
	v_mfma_f32_16x16x32_bf16 v[88:91], v[156:159], v[196:199], v[88:91]
	v_mfma_f32_16x16x32_bf16 v[76:79], v[140:143], v[208:211], v[76:79]
	v_mfma_f32_16x16x32_bf16 v[72:75], v[156:159], v[208:211], v[72:75]
	v_mfma_f32_16x16x32_bf16 v[124:127], v[144:147], v[184:187], v[124:127]
	v_mfma_f32_16x16x32_bf16 v[120:123], v[160:163], v[184:187], v[120:123]
	v_mfma_f32_16x16x32_bf16 v[108:111], v[144:147], v[192:195], v[108:111]
	v_mfma_f32_16x16x32_bf16 v[104:107], v[160:163], v[192:195], v[104:107]
	v_mfma_f32_16x16x32_bf16 v[92:95], v[144:147], v[200:203], v[92:95]
	v_mfma_f32_16x16x32_bf16 v[88:91], v[160:163], v[200:203], v[88:91]
	v_mfma_f32_16x16x32_bf16 v[76:79], v[144:147], v[212:215], v[76:79]
	v_mfma_f32_16x16x32_bf16 v[72:75], v[160:163], v[212:215], v[72:75]
	v_mfma_f32_16x16x32_bf16 v[116:119], v[164:167], v[180:183], v[116:119]
	v_mfma_f32_16x16x32_bf16 v[112:115], v[172:175], v[180:183], v[112:115]
	v_mfma_f32_16x16x32_bf16 v[100:103], v[164:167], v[188:191], v[100:103]
	v_mfma_f32_16x16x32_bf16 v[96:99], v[172:175], v[188:191], v[96:99]
	v_mfma_f32_16x16x32_bf16 v[84:87], v[164:167], v[196:199], v[84:87]
	v_mfma_f32_16x16x32_bf16 v[80:83], v[172:175], v[196:199], v[80:83]
	v_mfma_f32_16x16x32_bf16 v[68:71], v[164:167], v[208:211], v[68:71]
	v_mfma_f32_16x16x32_bf16 v[64:67], v[172:175], v[208:211], v[64:67]
	v_mfma_f32_16x16x32_bf16 v[116:119], v[168:171], v[184:187], v[116:119]
	v_mfma_f32_16x16x32_bf16 v[112:115], v[176:179], v[184:187], v[112:115]
	v_mfma_f32_16x16x32_bf16 v[100:103], v[168:171], v[192:195], v[100:103]
	v_mfma_f32_16x16x32_bf16 v[96:99], v[176:179], v[192:195], v[96:99]
	v_mfma_f32_16x16x32_bf16 v[84:87], v[168:171], v[200:203], v[84:87]
	v_mfma_f32_16x16x32_bf16 v[80:83], v[176:179], v[200:203], v[80:83]
	v_mfma_f32_16x16x32_bf16 v[68:71], v[168:171], v[212:215], v[68:71]
	v_mfma_f32_16x16x32_bf16 v[64:67], v[176:179], v[212:215], v[64:67]
	s_barrier
	s_add_i32 s40, s62, s45
	s_mov_b32 m0, s40
	ds_read_b128 v[180:183], v153 offset:49152
	ds_read_b128 v[184:187], v153 offset:50176
	ds_read_b128 v[188:191], v153 offset:51200
	ds_read_b128 v[192:195], v153 offset:52224
	ds_read_b128 v[196:199], v153 offset:53248
	ds_read_b128 v[200:203], v153 offset:54272
	ds_read_b128 v[208:211], v153 offset:55296
	ds_read_b128 v[212:215], v153 offset:56320
	global_load_lds_dwordx4 v204, s[38:39]
	s_add_i32 m0, s40, 0x2000
	s_add_u32 s38, s38, 0x40080
	s_addc_u32 s39, s39, 0
	s_add_i32 s40, s63, s45
	global_load_lds_dwordx4 v205, s[98:99]
	s_mov_b32 m0, s40
	s_nop 0
	global_load_lds_dwordx4 v128, s[38:39]
	s_add_i32 m0, s40, 0x2000
	s_nop 0
	global_load_lds_dwordx4 v130, s[38:39]
	s_mov_b32 m0, s51
	s_nop 0
	global_load_lds_dwordx4 v204, s[100:101]
	s_mov_b32 m0, s52
	s_nop 0
	global_load_lds_dwordx4 v205, s[100:101]
	s_waitcnt vmcnt(8)
	s_waitcnt lgkmcnt(0)
	s_barrier
	s_waitcnt lgkmcnt(0)
	v_mfma_f32_16x16x32_bf16 v[60:63], v[140:143], v[180:183], v[60:63]
	v_mfma_f32_16x16x32_bf16 v[56:59], v[156:159], v[180:183], v[56:59]
	v_mfma_f32_16x16x32_bf16 v[44:47], v[140:143], v[188:191], v[44:47]
	v_mfma_f32_16x16x32_bf16 v[40:43], v[156:159], v[188:191], v[40:43]
	v_mfma_f32_16x16x32_bf16 v[28:31], v[140:143], v[196:199], v[28:31]
	v_mfma_f32_16x16x32_bf16 v[24:27], v[156:159], v[196:199], v[24:27]
	v_mfma_f32_16x16x32_bf16 v[12:15], v[140:143], v[208:211], v[12:15]
	v_mfma_f32_16x16x32_bf16 v[8:11], v[156:159], v[208:211], v[8:11]
	v_mfma_f32_16x16x32_bf16 v[60:63], v[144:147], v[184:187], v[60:63]
	v_mfma_f32_16x16x32_bf16 v[56:59], v[160:163], v[184:187], v[56:59]
	v_mfma_f32_16x16x32_bf16 v[44:47], v[144:147], v[192:195], v[44:47]
	v_mfma_f32_16x16x32_bf16 v[40:43], v[160:163], v[192:195], v[40:43]
	v_mfma_f32_16x16x32_bf16 v[28:31], v[144:147], v[200:203], v[28:31]
	v_mfma_f32_16x16x32_bf16 v[24:27], v[160:163], v[200:203], v[24:27]
	v_mfma_f32_16x16x32_bf16 v[12:15], v[144:147], v[212:215], v[12:15]
	v_mfma_f32_16x16x32_bf16 v[8:11], v[160:163], v[212:215], v[8:11]
	v_mfma_f32_16x16x32_bf16 v[52:55], v[164:167], v[180:183], v[52:55]
	v_mfma_f32_16x16x32_bf16 v[48:51], v[172:175], v[180:183], v[48:51]
	v_mfma_f32_16x16x32_bf16 v[36:39], v[164:167], v[188:191], v[36:39]
	v_mfma_f32_16x16x32_bf16 v[32:35], v[172:175], v[188:191], v[32:35]
	v_mfma_f32_16x16x32_bf16 v[20:23], v[164:167], v[196:199], v[20:23]
	v_mfma_f32_16x16x32_bf16 v[16:19], v[172:175], v[196:199], v[16:19]
	v_mfma_f32_16x16x32_bf16 v[4:7], v[164:167], v[208:211], v[4:7]
	v_mfma_f32_16x16x32_bf16 v[0:3], v[172:175], v[208:211], v[0:3]
	v_mfma_f32_16x16x32_bf16 v[52:55], v[168:171], v[184:187], v[52:55]
	v_mfma_f32_16x16x32_bf16 v[48:51], v[176:179], v[184:187], v[48:51]
	v_mfma_f32_16x16x32_bf16 v[36:39], v[168:171], v[192:195], v[36:39]
	v_mfma_f32_16x16x32_bf16 v[32:35], v[176:179], v[192:195], v[32:35]
	v_mfma_f32_16x16x32_bf16 v[20:23], v[168:171], v[200:203], v[20:23]
	v_mfma_f32_16x16x32_bf16 v[16:19], v[176:179], v[200:203], v[16:19]
	v_mfma_f32_16x16x32_bf16 v[4:7], v[168:171], v[212:215], v[4:7]
	v_mfma_f32_16x16x32_bf16 v[0:3], v[176:179], v[212:215], v[0:3]
	s_barrier
	s_add_i32 s61, s61, 2
	s_add_u32 s59, s59, 0x100
	s_addc_u32 s60, s60, 0
	s_add_u32 s36, s36, 0x100
	s_addc_u32 s37, s37, 0
	s_cmp_gt_u32 s61, 13
	s_cbranch_scc0 .LBB0_1561
	s_setprio 0
	s_and_b64 vcc, exec, s[24:25]
	s_cbranch_vccz .LBB0_1564
	s_barrier

.LBB0_1646:
	ds_read_b128 v[144:147], v151
	ds_read_b128 v[156:159], v151 offset:1024
	ds_read_b128 v[160:163], v151 offset:2048
	ds_read_b128 v[164:167], v151 offset:3072
	ds_read_b128 v[168:171], v152
	ds_read_b128 v[172:175], v152 offset:1024
	ds_read_b128 v[176:179], v152 offset:2048
	ds_read_b128 v[180:183], v152 offset:3072
	s_add_u32 s26, s24, 0xfffc0080
	s_addc_u32 s27, s25, -1
	s_cmp_eq_u32 s54, 12
	s_cselect_b32 s29, s19, s27
	s_cselect_b32 s28, s50, s26
	s_cselect_b32 s27, s17, s53
	s_cselect_b32 s26, s51, s52
	s_add_i32 m0, s38, 0xc000
	ds_read_b128 v[184:187], v153
	ds_read_b128 v[188:191], v153 offset:1024
	ds_read_b128 v[192:195], v153 offset:2048
	ds_read_b128 v[196:199], v153 offset:3072
	ds_read_b128 v[200:203], v153 offset:4096
	ds_read_b128 v[208:211], v153 offset:5120
	ds_read_b128 v[212:215], v153 offset:6144
	ds_read_b128 v[216:219], v153 offset:7168
	global_load_lds_dwordx4 v138, s[24:25]
	s_add_i32 m0, s38, 0xe000
	s_nop 0
	global_load_lds_dwordx4 v136, s[24:25]
	s_waitcnt vmcnt(8)
	s_waitcnt lgkmcnt(0)
	s_barrier
	s_waitcnt lgkmcnt(0)
	v_mfma_f32_16x16x32_bf16 v[124:127], v[144:147], v[184:187], v[124:127]
	v_mfma_f32_16x16x32_bf16 v[120:123], v[160:163], v[184:187], v[120:123]
	v_mfma_f32_16x16x32_bf16 v[108:111], v[144:147], v[192:195], v[108:111]
	v_mfma_f32_16x16x32_bf16 v[104:107], v[160:163], v[192:195], v[104:107]
	v_mfma_f32_16x16x32_bf16 v[92:95], v[144:147], v[200:203], v[92:95]
	v_mfma_f32_16x16x32_bf16 v[88:91], v[160:163], v[200:203], v[88:91]
	v_mfma_f32_16x16x32_bf16 v[76:79], v[144:147], v[212:215], v[76:79]
	v_mfma_f32_16x16x32_bf16 v[72:75], v[160:163], v[212:215], v[72:75]
	v_mfma_f32_16x16x32_bf16 v[124:127], v[156:159], v[188:191], v[124:127]
	v_mfma_f32_16x16x32_bf16 v[120:123], v[164:167], v[188:191], v[120:123]
	v_mfma_f32_16x16x32_bf16 v[108:111], v[156:159], v[196:199], v[108:111]
	v_mfma_f32_16x16x32_bf16 v[104:107], v[164:167], v[196:199], v[104:107]
	v_mfma_f32_16x16x32_bf16 v[92:95], v[156:159], v[208:211], v[92:95]
	v_mfma_f32_16x16x32_bf16 v[88:91], v[164:167], v[208:211], v[88:91]
	v_mfma_f32_16x16x32_bf16 v[76:79], v[156:159], v[216:219], v[76:79]
	v_mfma_f32_16x16x32_bf16 v[72:75], v[164:167], v[216:219], v[72:75]
	v_mfma_f32_16x16x32_bf16 v[116:119], v[168:171], v[184:187], v[116:119]
	v_mfma_f32_16x16x32_bf16 v[112:115], v[176:179], v[184:187], v[112:115]
	v_mfma_f32_16x16x32_bf16 v[100:103], v[168:171], v[192:195], v[100:103]
	v_mfma_f32_16x16x32_bf16 v[96:99], v[176:179], v[192:195], v[96:99]
	v_mfma_f32_16x16x32_bf16 v[84:87], v[168:171], v[200:203], v[84:87]
	v_mfma_f32_16x16x32_bf16 v[80:83], v[176:179], v[200:203], v[80:83]
	v_mfma_f32_16x16x32_bf16 v[68:71], v[168:171], v[212:215], v[68:71]
	v_mfma_f32_16x16x32_bf16 v[64:67], v[176:179], v[212:215], v[64:67]
	v_mfma_f32_16x16x32_bf16 v[116:119], v[172:175], v[188:191], v[116:119]
	v_mfma_f32_16x16x32_bf16 v[112:115], v[180:183], v[188:191], v[112:115]
	v_mfma_f32_16x16x32_bf16 v[100:103], v[172:175], v[196:199], v[100:103]
	v_mfma_f32_16x16x32_bf16 v[96:99], v[180:183], v[196:199], v[96:99]
	v_mfma_f32_16x16x32_bf16 v[84:87], v[172:175], v[208:211], v[84:87]
	v_mfma_f32_16x16x32_bf16 v[80:83], v[180:183], v[208:211], v[80:83]
	v_mfma_f32_16x16x32_bf16 v[68:71], v[172:175], v[216:219], v[68:71]
	v_mfma_f32_16x16x32_bf16 v[64:67], v[180:183], v[216:219], v[64:67]
	s_barrier
	s_add_i32 s55, s47, s35
	s_mov_b32 m0, s55
	ds_read_b128 v[184:187], v153 offset:16384
	ds_read_b128 v[188:191], v153 offset:17408
	ds_read_b128 v[192:195], v153 offset:18432
	ds_read_b128 v[196:199], v153 offset:19456
	ds_read_b128 v[200:203], v153 offset:20480
	ds_read_b128 v[208:211], v153 offset:21504
	ds_read_b128 v[212:215], v153 offset:22528
	ds_read_b128 v[216:219], v153 offset:23552
	global_load_lds_dwordx4 v132, s[26:27]
	s_add_i32 m0, s55, 0x2000
	s_add_u32 s56, s26, 0x40000
	s_mov_b64 s[98:99], s[26:27]
	s_addc_u32 s57, s27, 0
	s_add_i32 s55, s48, s35
	global_load_lds_dwordx4 v128, s[26:27]
	s_mov_b32 m0, s55
	s_mov_b64 s[100:101], s[28:29]
	global_load_lds_dwordx4 v132, s[56:57]
	s_add_i32 m0, s55, 0x2000
	s_nop 0
	global_load_lds_dwordx4 v128, s[56:57]
	s_waitcnt vmcnt(6)
	s_waitcnt lgkmcnt(0)
	s_barrier
	s_waitcnt lgkmcnt(0)
	v_mfma_f32_16x16x32_bf16 v[60:63], v[144:147], v[184:187], v[60:63]
	v_mfma_f32_16x16x32_bf16 v[56:59], v[160:163], v[184:187], v[56:59]
	v_mfma_f32_16x16x32_bf16 v[44:47], v[144:147], v[192:195], v[44:47]
	v_mfma_f32_16x16x32_bf16 v[40:43], v[160:163], v[192:195], v[40:43]
	v_mfma_f32_16x16x32_bf16 v[28:31], v[144:147], v[200:203], v[28:31]
	v_mfma_f32_16x16x32_bf16 v[24:27], v[160:163], v[200:203], v[24:27]
	v_mfma_f32_16x16x32_bf16 v[12:15], v[144:147], v[212:215], v[12:15]
	v_mfma_f32_16x16x32_bf16 v[8:11], v[160:163], v[212:215], v[8:11]
	v_mfma_f32_16x16x32_bf16 v[60:63], v[156:159], v[188:191], v[60:63]
	v_mfma_f32_16x16x32_bf16 v[56:59], v[164:167], v[188:191], v[56:59]
	v_mfma_f32_16x16x32_bf16 v[44:47], v[156:159], v[196:199], v[44:47]
	v_mfma_f32_16x16x32_bf16 v[40:43], v[164:167], v[196:199], v[40:43]
	v_mfma_f32_16x16x32_bf16 v[28:31], v[156:159], v[208:211], v[28:31]
	v_mfma_f32_16x16x32_bf16 v[24:27], v[164:167], v[208:211], v[24:27]
	v_mfma_f32_16x16x32_bf16 v[12:15], v[156:159], v[216:219], v[12:15]
	v_mfma_f32_16x16x32_bf16 v[8:11], v[164:167], v[216:219], v[8:11]
	v_mfma_f32_16x16x32_bf16 v[52:55], v[168:171], v[184:187], v[52:55]
	v_mfma_f32_16x16x32_bf16 v[48:51], v[176:179], v[184:187], v[48:51]
	v_mfma_f32_16x16x32_bf16 v[36:39], v[168:171], v[192:195], v[36:39]
	v_mfma_f32_16x16x32_bf16 v[32:35], v[176:179], v[192:195], v[32:35]
	v_mfma_f32_16x16x32_bf16 v[20:23], v[168:171], v[200:203], v[20:23]
	v_mfma_f32_16x16x32_bf16 v[16:19], v[176:179], v[200:203], v[16:19]
	v_mfma_f32_16x16x32_bf16 v[4:7], v[168:171], v[212:215], v[4:7]
	v_mfma_f32_16x16x32_bf16 v[0:3], v[176:179], v[212:215], v[0:3]
	v_mfma_f32_16x16x32_bf16 v[52:55], v[172:175], v[188:191], v[52:55]
	v_mfma_f32_16x16x32_bf16 v[48:51], v[180:183], v[188:191], v[48:51]
	v_mfma_f32_16x16x32_bf16 v[36:39], v[172:175], v[196:199], v[36:39]
	v_mfma_f32_16x16x32_bf16 v[32:35], v[180:183], v[196:199], v[32:35]
	v_mfma_f32_16x16x32_bf16 v[20:23], v[172:175], v[208:211], v[20:23]
	v_mfma_f32_16x16x32_bf16 v[16:19], v[180:183], v[208:211], v[16:19]
	v_mfma_f32_16x16x32_bf16 v[4:7], v[172:175], v[216:219], v[4:7]
	v_mfma_f32_16x16x32_bf16 v[0:3], v[180:183], v[216:219], v[0:3]
	s_barrier
	s_mov_b32 m0, s38
	s_nop 0
	global_load_lds_dwordx4 v134, s[28:29]
	s_mov_b32 m0, s39
	s_nop 0
	global_load_lds_dwordx4 v130, s[28:29]
	s_add_i32 s55, 0, 0x18000
	s_add_i32 s56, 0, 0x1c000
	v_add_u32_e32 v164, s55, v149
	v_add_u32_e32 v180, s56, v149
	ds_read_b128 v[144:147], v164
	ds_read_b128 v[156:159], v164 offset:1024
	ds_read_b128 v[160:163], v164 offset:2048
	ds_read_b128 v[164:167], v164 offset:3072
	ds_read_b128 v[168:171], v180
	ds_read_b128 v[172:175], v180 offset:1024
	ds_read_b128 v[176:179], v180 offset:2048
	ds_read_b128 v[180:183], v180 offset:3072
	s_add_u32 s28, s28, 0x40000
	s_addc_u32 s29, s29, 0
	s_mov_b32 m0, s40
	ds_read_b128 v[184:187], v153 offset:32768
	ds_read_b128 v[188:191], v153 offset:33792
	ds_read_b128 v[192:195], v153 offset:34816
	ds_read_b128 v[196:199], v153 offset:35840
	ds_read_b128 v[200:203], v153 offset:36864
	ds_read_b128 v[208:211], v153 offset:37888
	ds_read_b128 v[212:215], v153 offset:38912
	ds_read_b128 v[216:219], v153 offset:39936
	global_load_lds_dwordx4 v134, s[28:29]
	s_mov_b32 m0, s41
	s_nop 0
	global_load_lds_dwordx4 v130, s[28:29]
	s_waitcnt vmcnt(8)
	s_waitcnt lgkmcnt(0)
	s_barrier
	s_waitcnt lgkmcnt(0)
	v_mfma_f32_16x16x32_bf16 v[124:127], v[144:147], v[184:187], v[124:127]
	v_mfma_f32_16x16x32_bf16 v[120:123], v[160:163], v[184:187], v[120:123]
	v_mfma_f32_16x16x32_bf16 v[108:111], v[144:147], v[192:195], v[108:111]
	v_mfma_f32_16x16x32_bf16 v[104:107], v[160:163], v[192:195], v[104:107]
	v_mfma_f32_16x16x32_bf16 v[92:95], v[144:147], v[200:203], v[92:95]
	v_mfma_f32_16x16x32_bf16 v[88:91], v[160:163], v[200:203], v[88:91]
	v_mfma_f32_16x16x32_bf16 v[76:79], v[144:147], v[212:215], v[76:79]
	v_mfma_f32_16x16x32_bf16 v[72:75], v[160:163], v[212:215], v[72:75]
	v_mfma_f32_16x16x32_bf16 v[124:127], v[156:159], v[188:191], v[124:127]
	v_mfma_f32_16x16x32_bf16 v[120:123], v[164:167], v[188:191], v[120:123]
	v_mfma_f32_16x16x32_bf16 v[108:111], v[156:159], v[196:199], v[108:111]
	v_mfma_f32_16x16x32_bf16 v[104:107], v[164:167], v[196:199], v[104:107]
	v_mfma_f32_16x16x32_bf16 v[92:95], v[156:159], v[208:211], v[92:95]
	v_mfma_f32_16x16x32_bf16 v[88:91], v[164:167], v[208:211], v[88:91]
	v_mfma_f32_16x16x32_bf16 v[76:79], v[156:159], v[216:219], v[76:79]
	v_mfma_f32_16x16x32_bf16 v[72:75], v[164:167], v[216:219], v[72:75]
	v_mfma_f32_16x16x32_bf16 v[116:119], v[168:171], v[184:187], v[116:119]
	v_mfma_f32_16x16x32_bf16 v[112:115], v[176:179], v[184:187], v[112:115]
	v_mfma_f32_16x16x32_bf16 v[100:103], v[168:171], v[192:195], v[100:103]
	v_mfma_f32_16x16x32_bf16 v[96:99], v[176:179], v[192:195], v[96:99]
	v_mfma_f32_16x16x32_bf16 v[84:87], v[168:171], v[200:203], v[84:87]
	v_mfma_f32_16x16x32_bf16 v[80:83], v[176:179], v[200:203], v[80:83]
	v_mfma_f32_16x16x32_bf16 v[68:71], v[168:171], v[212:215], v[68:71]
	v_mfma_f32_16x16x32_bf16 v[64:67], v[176:179], v[212:215], v[64:67]
	v_mfma_f32_16x16x32_bf16 v[116:119], v[172:175], v[188:191], v[116:119]
	v_mfma_f32_16x16x32_bf16 v[112:115], v[180:183], v[188:191], v[112:115]
	v_mfma_f32_16x16x32_bf16 v[100:103], v[172:175], v[196:199], v[100:103]
	v_mfma_f32_16x16x32_bf16 v[96:99], v[180:183], v[196:199], v[96:99]
	v_mfma_f32_16x16x32_bf16 v[84:87], v[172:175], v[208:211], v[84:87]
	v_mfma_f32_16x16x32_bf16 v[80:83], v[180:183], v[208:211], v[80:83]
	v_mfma_f32_16x16x32_bf16 v[68:71], v[172:175], v[216:219], v[68:71]
	v_mfma_f32_16x16x32_bf16 v[64:67], v[180:183], v[216:219], v[64:67]
	s_barrier
	s_add_i32 s28, s55, s35
	s_mov_b32 m0, s28
	ds_read_b128 v[184:187], v153 offset:49152
	ds_read_b128 v[188:191], v153 offset:50176
	ds_read_b128 v[192:195], v153 offset:51200
	ds_read_b128 v[196:199], v153 offset:52224
	ds_read_b128 v[200:203], v153 offset:53248
	ds_read_b128 v[208:211], v153 offset:54272
	ds_read_b128 v[212:215], v153 offset:55296
	ds_read_b128 v[216:219], v153 offset:56320
	global_load_lds_dwordx4 v220, s[26:27]
	s_add_i32 m0, s28, 0x2000
	s_add_u32 s26, s26, 0x40080
	s_addc_u32 s27, s27, 0
	s_add_i32 s28, s56, s35
	global_load_lds_dwordx4 v204, s[98:99]
	s_mov_b32 m0, s28
	s_nop 0
	global_load_lds_dwordx4 v132, s[26:27]
	s_add_i32 m0, s28, 0x2000
	s_nop 0
	global_load_lds_dwordx4 v128, s[26:27]
	s_mov_b32 m0, s45
	s_nop 0
	global_load_lds_dwordx4 v221, s[100:101]
	s_mov_b32 m0, s46
	s_nop 0
	global_load_lds_dwordx4 v205, s[100:101]
	s_waitcnt vmcnt(8)
	s_waitcnt lgkmcnt(0)
	s_barrier
	s_waitcnt lgkmcnt(0)
	v_mfma_f32_16x16x32_bf16 v[60:63], v[144:147], v[184:187], v[60:63]
	v_mfma_f32_16x16x32_bf16 v[56:59], v[160:163], v[184:187], v[56:59]
	v_mfma_f32_16x16x32_bf16 v[44:47], v[144:147], v[192:195], v[44:47]
	v_mfma_f32_16x16x32_bf16 v[40:43], v[160:163], v[192:195], v[40:43]
	v_mfma_f32_16x16x32_bf16 v[28:31], v[144:147], v[200:203], v[28:31]
	v_mfma_f32_16x16x32_bf16 v[24:27], v[160:163], v[200:203], v[24:27]
	v_mfma_f32_16x16x32_bf16 v[12:15], v[144:147], v[212:215], v[12:15]
	v_mfma_f32_16x16x32_bf16 v[8:11], v[160:163], v[212:215], v[8:11]
	v_mfma_f32_16x16x32_bf16 v[60:63], v[156:159], v[188:191], v[60:63]
	v_mfma_f32_16x16x32_bf16 v[56:59], v[164:167], v[188:191], v[56:59]
	v_mfma_f32_16x16x32_bf16 v[44:47], v[156:159], v[196:199], v[44:47]
	v_mfma_f32_16x16x32_bf16 v[40:43], v[164:167], v[196:199], v[40:43]
	v_mfma_f32_16x16x32_bf16 v[28:31], v[156:159], v[208:211], v[28:31]
	v_mfma_f32_16x16x32_bf16 v[24:27], v[164:167], v[208:211], v[24:27]
	v_mfma_f32_16x16x32_bf16 v[12:15], v[156:159], v[216:219], v[12:15]
	v_mfma_f32_16x16x32_bf16 v[8:11], v[164:167], v[216:219], v[8:11]
	v_mfma_f32_16x16x32_bf16 v[52:55], v[168:171], v[184:187], v[52:55]
	v_mfma_f32_16x16x32_bf16 v[48:51], v[176:179], v[184:187], v[48:51]
	v_mfma_f32_16x16x32_bf16 v[36:39], v[168:171], v[192:195], v[36:39]
	v_mfma_f32_16x16x32_bf16 v[32:35], v[176:179], v[192:195], v[32:35]
	v_mfma_f32_16x16x32_bf16 v[20:23], v[168:171], v[200:203], v[20:23]
	v_mfma_f32_16x16x32_bf16 v[16:19], v[176:179], v[200:203], v[16:19]
	v_mfma_f32_16x16x32_bf16 v[4:7], v[168:171], v[212:215], v[4:7]
	v_mfma_f32_16x16x32_bf16 v[0:3], v[176:179], v[212:215], v[0:3]
	v_mfma_f32_16x16x32_bf16 v[52:55], v[172:175], v[188:191], v[52:55]
	v_mfma_f32_16x16x32_bf16 v[48:51], v[180:183], v[188:191], v[48:51]
	v_mfma_f32_16x16x32_bf16 v[36:39], v[172:175], v[196:199], v[36:39]
	v_mfma_f32_16x16x32_bf16 v[32:35], v[180:183], v[196:199], v[32:35]
	v_mfma_f32_16x16x32_bf16 v[20:23], v[172:175], v[208:211], v[20:23]
	v_mfma_f32_16x16x32_bf16 v[16:19], v[180:183], v[208:211], v[16:19]
	v_mfma_f32_16x16x32_bf16 v[4:7], v[172:175], v[216:219], v[4:7]
	v_mfma_f32_16x16x32_bf16 v[0:3], v[180:183], v[216:219], v[0:3]
	s_barrier
	s_add_i32 s54, s54, 2
	s_add_u32 s52, s52, 0x100
	s_addc_u32 s53, s53, 0
	s_add_u32 s24, s24, 0x100
	s_addc_u32 s25, s25, 0
	s_cmp_gt_u32 s54, 13
	s_cbranch_scc0 .LBB0_1646
	s_setprio 0
	s_and_b64 vcc, exec, s[14:15]
	s_cbranch_vccz .LBB0_1649
	s_barrier
